# attention units (both phases): the 16 gate + 16 norm-gain loads of the head-norm epilogue issued together, stores no longer waited on; on top of dn_scan prefetch change
# speedup vs baseline: 1.0009x; 1.0009x over previous
; #define MFMA(a, b, c) __builtin_amdgcn_mfma_f32_32x32x16_bf16((a), (b), (c), 0, 0, 0)
; DI f32x16 zero16() { f32x16 z; for (int i = 0; i < 16; ++i) z[i] = 0.f; return z; }
; DI void attn_unit(const Params& p, int l, int unit, unsigned char* smem) {
;     ...
;   for (int kt = 0; kt < ntile; ++kt) {
;     __syncthreads();
; #pragma unroll
;     for (int i = 0; i < 4; ++i) {
;       const int c = tid + 256 * i;
;       { const int key = c >> 4, kc = c & 15; *(u32x4*)(sK + key * 136 + 8 * kc) = rk[i]; }
;       { const int dv = c >> 3, kc = c & 7; *(u32x4*)(sVT + dv * 72 + 8 * kc) = rv[i]; }
;     }
;     __syncthreads();
;     if (kt + 1 < ntile) {
; #pragma unroll
;       for (int i = 0; i < 4; ++i) {
;         const int c = tid + 256 * i;
;         { const int key = c >> 4, kc = c & 15; rk[i] = *(const u32x4*)(Kbase + (size_t)((kt + 1) * 64 + key) * PLD + 8 * kc); }
;         { const int dv = c >> 3, kc = c & 7; rv[i] = *(const u32x4*)(VT + (size_t)dv * SP + (kt + 1) * 64 + 8 * kc); }
;       }
;     }
; #pragma unroll
;     for (int kb = 0; kb < 2; ++kb) {
;       f32x16 s0 = zero16(), s1 = zero16();
; #pragma unroll
;       for (int s = 0; s < 4; ++s) {
;         s0 = MFMA(ld16(sK + (32 * kb + l31) * 136 + 16 * s + 8 * h), qf[0][s], s0);
;         s1 = MFMA(ld16(sK + (32 * kb + l31) * 136 + 64 + 16 * s + 8 * h), qf[1][s], s1);
;       }
; #pragma unroll
;       for (int r = 0; r < 16; ++r) s0[r] = __builtin_amdgcn_exp2f(fmaf(s0[r], cs, nm[0])) * sc[0] - __builtin_amdgcn_exp2f(fmaf(s1[r], cs, nm[1])) * sc[1];
;       const bf16x8 p0 = pack8<0>(s0), p1 = pack8<1>(s0);
; #pragma unroll
;       for (int dvb = 0; dvb < 4; ++dvb) {
;         oacc[dvb] = MFMA(ld2x8(sVT + (32 * dvb + l31) * 72 + 32 * kb + 4 * h), p0, oacc[dvb]);
;         oacc[dvb] = MFMA(ld2x8(sVT + (32 * dvb + l31) * 72 + 32 * kb + 16 + 4 * h), p1, oacc[dvb]);
;       }
;     }
.LBB0_479:
	v_lshl_add_u64 v[64:65], s[4:5], 0, v[174:175]
	s_waitcnt lgkmcnt(0)
	s_barrier
	s_waitcnt vmcnt(0)
	ds_write_b128 v187, v[128:131]
	ds_write_b128 v203, v[132:135] offset:17408
	ds_write_b128 v186, v[136:139]
	ds_write_b128 v202, v[140:143] offset:17408
	ds_write_b128 v185, v[144:147]
	ds_write_b128 v201, v[148:151] offset:17408
	ds_write_b128 v184, v[152:155]
	ds_write_b128 v200, v[156:159] offset:17408
	s_waitcnt lgkmcnt(0)
	s_barrier
	global_load_dwordx4 v[128:131], v[64:65], off
	v_lshl_add_u64 v[64:65], s[4:5], 0, v[182:183]
	global_load_dwordx4 v[132:135], v[64:65], off
	v_lshl_add_u64 v[64:65], s[4:5], 0, v[172:173]
	global_load_dwordx4 v[136:139], v[64:65], off
	v_lshl_add_u64 v[64:65], s[4:5], 0, v[180:181]
	global_load_dwordx4 v[140:143], v[64:65], off
	v_lshl_add_u64 v[64:65], s[4:5], 0, v[170:171]
	global_load_dwordx4 v[144:147], v[64:65], off
	v_lshl_add_u64 v[64:65], s[4:5], 0, v[178:179]
	global_load_dwordx4 v[148:151], v[64:65], off
	v_lshl_add_u64 v[64:65], s[4:5], 0, v[168:169]
	global_load_dwordx4 v[152:155], v[64:65], off
	v_lshl_add_u64 v[64:65], s[4:5], 0, v[176:177]
	global_load_dwordx4 v[156:159], v[64:65], off
	ds_read_b128 v[236:239], v197
	ds_read_b128 v[246:249], v197 offset:32
	ds_read_b128 v[250:253], v197 offset:128
	s_waitcnt lgkmcnt(2)
	v_mfma_f32_32x32x16_bf16 v[64:79], v[236:239], v[120:123], 0
	v_add_u32_e32 v193, 0x4000, v198
	v_add_u32_e32 v196, 0x4000, v199
	v_add_u32_e32 v195, 0x6800, v198
	v_add_u32_e32 v194, 0x7800, v198
	s_add_i32 s6, s6, -1
	v_lshl_add_u64 v[168:169], v[168:169], 0, s[52:53]
	ds_read_b128 v[236:239], v197 offset:160
	s_waitcnt lgkmcnt(2)
	v_mfma_f32_32x32x16_bf16 v[64:79], v[246:249], v[116:119], v[64:79]
	v_lshl_add_u64 v[170:171], v[170:171], 0, s[52:53]
	v_lshl_add_u64 v[172:173], v[172:173], 0, s[52:53]
	v_lshl_add_u64 v[174:175], v[174:175], 0, s[52:53]
	v_lshl_add_u64 v[176:177], v[176:177], 0, s[80:81]
	v_lshl_add_u64 v[178:179], v[178:179], 0, s[80:81]
	v_lshl_add_u64 v[180:181], v[180:181], 0, s[80:81]
	ds_read_b128 v[246:249], v197 offset:64
	s_waitcnt lgkmcnt(2)
	v_mfma_f32_32x32x16_bf16 v[80:95], v[250:253], v[124:127], 0
	v_lshl_add_u64 v[182:183], v[182:183], 0, s[80:81]
	s_cmp_lg_u32 s6, 0
	ds_read_b128 v[250:253], v197 offset:192
	s_waitcnt lgkmcnt(2)
	v_mfma_f32_32x32x16_bf16 v[80:95], v[236:239], v[112:115], v[80:95]
	ds_read_b128 v[236:239], v197 offset:96
	s_waitcnt lgkmcnt(2)
	v_mfma_f32_32x32x16_bf16 v[64:79], v[246:249], v[104:107], v[64:79]
	ds_read_b128 v[246:249], v197 offset:224
	s_waitcnt lgkmcnt(2)
	v_mfma_f32_32x32x16_bf16 v[80:95], v[250:253], v[108:111], v[80:95]
	ds_read2_b64 v[250:253], v193 offset0:128 offset1:130
	s_waitcnt lgkmcnt(2)
	v_mfma_f32_32x32x16_bf16 v[64:79], v[236:239], v[100:103], v[64:79]
	ds_read2_b64 v[236:239], v193 offset0:132 offset1:134
	s_waitcnt lgkmcnt(2)
	v_mfma_f32_32x32x16_bf16 v[80:95], v[246:249], v[96:99], v[80:95]
	s_nop 8
	v_fmamk_f32 v64, v64, 0x3e38aa3b, v190
	v_fmamk_f32 v65, v65, 0x3e38aa3b, v190
	v_exp_f32_e32 v64, v64
	v_exp_f32_e32 v65, v65
	v_fmamk_f32 v66, v66, 0x3e38aa3b, v190
	v_fmamk_f32 v67, v67, 0x3e38aa3b, v190
	v_exp_f32_e32 v66, v66
	v_fmamk_f32 v80, v80, 0x3e38aa3b, v191
	v_fmamk_f32 v81, v81, 0x3e38aa3b, v191
	v_exp_f32_e32 v80, v80
	v_exp_f32_e32 v81, v81
	v_exp_f32_e32 v67, v67
	v_fmamk_f32 v68, v68, 0x3e38aa3b, v190
	v_fmamk_f32 v69, v69, 0x3e38aa3b, v190
	v_pk_mul_f32 v[80:81], v[166:167], v[80:81]
	v_exp_f32_e32 v68, v68
	v_pk_fma_f32 v[64:65], v[164:165], v[64:65], v[80:81] neg_lo:[0,0,1] neg_hi:[0,0,1]
	v_fmamk_f32 v80, v82, 0x3e38aa3b, v191
	v_fmamk_f32 v81, v83, 0x3e38aa3b, v191
	v_exp_f32_e32 v80, v80
	v_exp_f32_e32 v81, v81
	v_exp_f32_e32 v69, v69
	v_fmamk_f32 v70, v70, 0x3e38aa3b, v190
	v_fmamk_f32 v71, v71, 0x3e38aa3b, v190
	v_pk_mul_f32 v[80:81], v[166:167], v[80:81]
	v_exp_f32_e32 v70, v70
	v_pk_fma_f32 v[66:67], v[164:165], v[66:67], v[80:81] neg_lo:[0,0,1] neg_hi:[0,0,1]
	v_fmamk_f32 v80, v84, 0x3e38aa3b, v191
	v_fmamk_f32 v81, v85, 0x3e38aa3b, v191
	v_exp_f32_e32 v80, v80
	v_exp_f32_e32 v81, v81
	v_exp_f32_e32 v71, v71
	v_fmamk_f32 v72, v72, 0x3e38aa3b, v190
	v_fmamk_f32 v73, v73, 0x3e38aa3b, v190
	v_pk_mul_f32 v[80:81], v[166:167], v[80:81]
	v_exp_f32_e32 v72, v72
	v_pk_fma_f32 v[68:69], v[164:165], v[68:69], v[80:81] neg_lo:[0,0,1] neg_hi:[0,0,1]
	v_fmamk_f32 v80, v86, 0x3e38aa3b, v191
	v_fmamk_f32 v81, v87, 0x3e38aa3b, v191
	v_exp_f32_e32 v80, v80
	v_exp_f32_e32 v81, v81
	v_exp_f32_e32 v73, v73
	v_fmamk_f32 v74, v74, 0x3e38aa3b, v190
	v_fmamk_f32 v75, v75, 0x3e38aa3b, v190
	v_pk_mul_f32 v[80:81], v[166:167], v[80:81]
	v_exp_f32_e32 v74, v74
	v_pk_fma_f32 v[70:71], v[164:165], v[70:71], v[80:81] neg_lo:[0,0,1] neg_hi:[0,0,1]
	v_fmamk_f32 v80, v88, 0x3e38aa3b, v191
	v_fmamk_f32 v81, v89, 0x3e38aa3b, v191
	v_exp_f32_e32 v80, v80
	v_exp_f32_e32 v81, v81
	v_exp_f32_e32 v75, v75
	v_fmamk_f32 v76, v76, 0x3e38aa3b, v190
	v_fmamk_f32 v77, v77, 0x3e38aa3b, v190
	v_pk_mul_f32 v[80:81], v[166:167], v[80:81]
	v_exp_f32_e32 v76, v76
	v_pk_fma_f32 v[72:73], v[164:165], v[72:73], v[80:81] neg_lo:[0,0,1] neg_hi:[0,0,1]
	v_fmamk_f32 v80, v90, 0x3e38aa3b, v191
	v_fmamk_f32 v81, v91, 0x3e38aa3b, v191
	v_exp_f32_e32 v80, v80
	v_exp_f32_e32 v81, v81
	v_exp_f32_e32 v77, v77
	v_fmamk_f32 v78, v78, 0x3e38aa3b, v190
	v_fmamk_f32 v79, v79, 0x3e38aa3b, v190
	v_pk_mul_f32 v[80:81], v[166:167], v[80:81]
	v_exp_f32_e32 v78, v78
	v_pk_fma_f32 v[74:75], v[164:165], v[74:75], v[80:81] neg_lo:[0,0,1] neg_hi:[0,0,1]
	v_fmamk_f32 v80, v92, 0x3e38aa3b, v191
	v_fmamk_f32 v81, v93, 0x3e38aa3b, v191
	v_exp_f32_e32 v80, v80
	v_exp_f32_e32 v81, v81
	v_exp_f32_e32 v79, v79
	v_cvt_pk_bf16_f32 v64, v64, v65
	v_cvt_pk_bf16_f32 v65, v66, v67
	v_pk_mul_f32 v[80:81], v[166:167], v[80:81]
	v_cvt_pk_bf16_f32 v66, v68, v69
	v_pk_fma_f32 v[76:77], v[164:165], v[76:77], v[80:81] neg_lo:[0,0,1] neg_hi:[0,0,1]
	v_fmamk_f32 v80, v94, 0x3e38aa3b, v191
	v_fmamk_f32 v81, v95, 0x3e38aa3b, v191
	v_exp_f32_e32 v80, v80
	v_exp_f32_e32 v81, v81
	v_cvt_pk_bf16_f32 v67, v70, v71
	v_cvt_pk_bf16_f32 v68, v72, v73
	v_cvt_pk_bf16_f32 v69, v74, v75
	v_pk_mul_f32 v[80:81], v[166:167], v[80:81]
	v_cvt_pk_bf16_f32 v70, v76, v77
	v_pk_fma_f32 v[78:79], v[164:165], v[78:79], v[80:81] neg_lo:[0,0,1] neg_hi:[0,0,1]
	s_nop 0
	v_cvt_pk_bf16_f32 v71, v78, v79
	ds_read2_b64 v[246:249], v196 offset0:128 offset1:130
	s_waitcnt lgkmcnt(2)
; #define MFMA(a, b, c) __builtin_amdgcn_mfma_f32_32x32x16_bf16((a), (b), (c), 0, 0, 0)
; DI f32x16 zero16() { f32x16 z; for (int i = 0; i < 16; ++i) z[i] = 0.f; return z; }
; DI void attn_unit(const Params& p, int l, int unit, unsigned char* smem) {
;     ...
; #pragma unroll
;     for (int kb = 0; kb < 2; ++kb) {
;       f32x16 s0 = zero16(), s1 = zero16();
; #pragma unroll
;       for (int s = 0; s < 4; ++s) {
;         s0 = MFMA(ld16(sK + (32 * kb + l31) * 136 + 16 * s + 8 * h), qf[0][s], s0);
;         s1 = MFMA(ld16(sK + (32 * kb + l31) * 136 + 64 + 16 * s + 8 * h), qf[1][s], s1);
;       }
; #pragma unroll
;       for (int r = 0; r < 16; ++r) s0[r] = __builtin_amdgcn_exp2f(fmaf(s0[r], cs, nm[0])) * sc[0] - __builtin_amdgcn_exp2f(fmaf(s1[r], cs, nm[1])) * sc[1];
;       const bf16x8 p0 = pack8<0>(s0), p1 = pack8<1>(s0);
; #pragma unroll
;       for (int dvb = 0; dvb < 4; ++dvb) {
;         oacc[dvb] = MFMA(ld2x8(sVT + (32 * dvb + l31) * 72 + 32 * kb + 4 * h), p0, oacc[dvb]);
;         oacc[dvb] = MFMA(ld2x8(sVT + (32 * dvb + l31) * 72 + 32 * kb + 16 + 4 * h), p1, oacc[dvb]);
;       }
;     }
	v_mfma_f32_32x32x16_bf16 v[48:63], v[250:253], v[64:67], v[48:63]
	ds_read2_b64 v[250:253], v195 offset1:2
	s_waitcnt lgkmcnt(2)
	v_mfma_f32_32x32x16_bf16 v[48:63], v[236:239], v[68:71], v[48:63]
	ds_read2_b64 v[236:239], v195 offset0:4 offset1:6
	s_waitcnt lgkmcnt(2)
	v_mfma_f32_32x32x16_bf16 v[32:47], v[246:249], v[64:67], v[32:47]
	ds_read2_b64 v[246:249], v194 offset0:64 offset1:66
	s_waitcnt lgkmcnt(2)
	v_mfma_f32_32x32x16_bf16 v[16:31], v[250:253], v[64:67], v[16:31]
	ds_read2_b64 v[250:253], v194 offset0:68 offset1:70
	s_waitcnt lgkmcnt(2)
	v_mfma_f32_32x32x16_bf16 v[16:31], v[236:239], v[68:71], v[16:31]
	ds_read2_b64 v[236:239], v196 offset0:132 offset1:134
	s_waitcnt lgkmcnt(2)
	v_mfma_f32_32x32x16_bf16 v[0:15], v[246:249], v[64:67], v[0:15]
	ds_read_b128 v[246:249], v192
	s_waitcnt lgkmcnt(2)
	v_mfma_f32_32x32x16_bf16 v[0:15], v[250:253], v[68:71], v[0:15]
	ds_read_b128 v[250:253], v192 offset:32
	s_waitcnt lgkmcnt(2)
	v_mfma_f32_32x32x16_bf16 v[32:47], v[236:239], v[68:71], v[32:47]
	ds_read_b128 v[236:239], v192 offset:128
	s_waitcnt lgkmcnt(2)
	v_mfma_f32_32x32x16_bf16 v[64:79], v[246:249], v[120:123], 0
	ds_read_b128 v[246:249], v192 offset:160
	s_waitcnt lgkmcnt(2)
	v_mfma_f32_32x32x16_bf16 v[64:79], v[250:253], v[116:119], v[64:79]
	ds_read_b128 v[250:253], v192 offset:64
	s_waitcnt lgkmcnt(2)
	v_mfma_f32_32x32x16_bf16 v[80:95], v[236:239], v[124:127], 0
	ds_read_b128 v[236:239], v192 offset:192
	s_waitcnt lgkmcnt(2)
	v_mfma_f32_32x32x16_bf16 v[80:95], v[246:249], v[112:115], v[80:95]
	ds_read_b128 v[246:249], v192 offset:96
	s_waitcnt lgkmcnt(2)
	v_mfma_f32_32x32x16_bf16 v[64:79], v[250:253], v[104:107], v[64:79]
	ds_read_b128 v[250:253], v192 offset:224
	s_waitcnt lgkmcnt(2)
	v_mfma_f32_32x32x16_bf16 v[80:95], v[236:239], v[108:111], v[80:95]
	ds_read2_b64 v[236:239], v193 offset0:136 offset1:138
	s_waitcnt lgkmcnt(2)
	v_mfma_f32_32x32x16_bf16 v[64:79], v[246:249], v[100:103], v[64:79]
	ds_read2_b64 v[246:249], v193 offset0:140 offset1:142
	s_waitcnt lgkmcnt(2)
	v_mfma_f32_32x32x16_bf16 v[80:95], v[250:253], v[96:99], v[80:95]
	s_nop 8
	v_fmamk_f32 v64, v64, 0x3e38aa3b, v190
	v_fmamk_f32 v65, v65, 0x3e38aa3b, v190
	v_exp_f32_e32 v64, v64
	v_exp_f32_e32 v65, v65
	v_fmamk_f32 v66, v66, 0x3e38aa3b, v190
	v_fmamk_f32 v67, v67, 0x3e38aa3b, v190
	v_exp_f32_e32 v66, v66
	v_fmamk_f32 v80, v80, 0x3e38aa3b, v191
	v_fmamk_f32 v81, v81, 0x3e38aa3b, v191
	v_exp_f32_e32 v80, v80
	v_exp_f32_e32 v81, v81
	v_exp_f32_e32 v67, v67
	v_fmamk_f32 v68, v68, 0x3e38aa3b, v190
	v_fmamk_f32 v69, v69, 0x3e38aa3b, v190
	v_pk_mul_f32 v[80:81], v[166:167], v[80:81]
	v_exp_f32_e32 v68, v68
	v_pk_fma_f32 v[64:65], v[164:165], v[64:65], v[80:81] neg_lo:[0,0,1] neg_hi:[0,0,1]
	v_fmamk_f32 v80, v82, 0x3e38aa3b, v191
	v_fmamk_f32 v81, v83, 0x3e38aa3b, v191
	v_exp_f32_e32 v80, v80
	v_exp_f32_e32 v81, v81
	v_exp_f32_e32 v69, v69
	v_fmamk_f32 v70, v70, 0x3e38aa3b, v190
	v_fmamk_f32 v71, v71, 0x3e38aa3b, v190
	v_pk_mul_f32 v[80:81], v[166:167], v[80:81]
	v_exp_f32_e32 v70, v70
	v_pk_fma_f32 v[66:67], v[164:165], v[66:67], v[80:81] neg_lo:[0,0,1] neg_hi:[0,0,1]
	v_fmamk_f32 v80, v84, 0x3e38aa3b, v191
	v_fmamk_f32 v81, v85, 0x3e38aa3b, v191
	v_exp_f32_e32 v80, v80
	v_exp_f32_e32 v81, v81
	v_exp_f32_e32 v71, v71
	v_fmamk_f32 v72, v72, 0x3e38aa3b, v190
	v_fmamk_f32 v73, v73, 0x3e38aa3b, v190
	v_pk_mul_f32 v[80:81], v[166:167], v[80:81]
	v_exp_f32_e32 v72, v72
	v_pk_fma_f32 v[68:69], v[164:165], v[68:69], v[80:81] neg_lo:[0,0,1] neg_hi:[0,0,1]
	v_fmamk_f32 v80, v86, 0x3e38aa3b, v191
	v_fmamk_f32 v81, v87, 0x3e38aa3b, v191
	v_exp_f32_e32 v80, v80
	v_exp_f32_e32 v81, v81
	v_exp_f32_e32 v73, v73
	v_fmamk_f32 v74, v74, 0x3e38aa3b, v190
	v_fmamk_f32 v75, v75, 0x3e38aa3b, v190
	v_pk_mul_f32 v[80:81], v[166:167], v[80:81]
	v_exp_f32_e32 v74, v74
	v_pk_fma_f32 v[70:71], v[164:165], v[70:71], v[80:81] neg_lo:[0,0,1] neg_hi:[0,0,1]
	v_fmamk_f32 v80, v88, 0x3e38aa3b, v191
	v_fmamk_f32 v81, v89, 0x3e38aa3b, v191
	v_exp_f32_e32 v80, v80
	v_exp_f32_e32 v81, v81
	v_exp_f32_e32 v75, v75
	v_cvt_pk_bf16_f32 v64, v64, v65
	v_cvt_pk_bf16_f32 v65, v66, v67
	v_pk_mul_f32 v[80:81], v[166:167], v[80:81]
	v_cvt_pk_bf16_f32 v66, v68, v69
	v_pk_fma_f32 v[72:73], v[164:165], v[72:73], v[80:81] neg_lo:[0,0,1] neg_hi:[0,0,1]
	v_fmamk_f32 v80, v90, 0x3e38aa3b, v191
	v_fmamk_f32 v81, v91, 0x3e38aa3b, v191
	v_exp_f32_e32 v80, v80
	v_exp_f32_e32 v81, v81
	v_cvt_pk_bf16_f32 v68, v72, v73
	v_fmamk_f32 v76, v76, 0x3e38aa3b, v190
	v_fmamk_f32 v77, v77, 0x3e38aa3b, v190
	v_pk_mul_f32 v[80:81], v[166:167], v[80:81]
	v_exp_f32_e32 v76, v76
	v_pk_fma_f32 v[74:75], v[164:165], v[74:75], v[80:81] neg_lo:[0,0,1] neg_hi:[0,0,1]
	v_fmamk_f32 v80, v92, 0x3e38aa3b, v191
	v_cvt_pk_bf16_f32 v69, v74, v75
	v_fmamk_f32 v81, v93, 0x3e38aa3b, v191
	v_exp_f32_e32 v80, v80
	v_exp_f32_e32 v81, v81
	v_exp_f32_e32 v77, v77
	v_cvt_pk_bf16_f32 v67, v70, v71
	v_fmamk_f32 v78, v78, 0x3e38aa3b, v190
	v_pk_mul_f32 v[80:81], v[166:167], v[80:81]
	ds_read2_b64 v[250:253], v196 offset0:136 offset1:138
	s_waitcnt lgkmcnt(2)
	v_mfma_f32_32x32x16_bf16 v[48:63], v[236:239], v[64:67], v[48:63]
	v_fma_f32 v76, v164, v76, -v80
	v_fma_f32 v77, v165, v77, -v81
	v_fmamk_f32 v80, v94, 0x3e38aa3b, v191
	v_fmamk_f32 v81, v95, 0x3e38aa3b, v191
	v_exp_f32_e32 v80, v80
	v_fmamk_f32 v79, v79, 0x3e38aa3b, v190
	v_exp_f32_e32 v81, v81
	v_exp_f32_e32 v78, v78
	v_exp_f32_e32 v79, v79
	v_cvt_pk_bf16_f32 v70, v76, v77
	v_pk_mul_f32 v[80:81], v[166:167], v[80:81]
	s_nop 0
	v_pk_fma_f32 v[78:79], v[164:165], v[78:79], v[80:81] neg_lo:[0,0,1] neg_hi:[0,0,1]
	s_nop 0
	v_cvt_pk_bf16_f32 v71, v78, v79
	s_nop 0
	ds_read2_b64 v[236:239], v195 offset0:8 offset1:10
	s_waitcnt lgkmcnt(2)
	v_mfma_f32_32x32x16_bf16 v[48:63], v[246:249], v[68:71], v[48:63]
	ds_read2_b64 v[246:249], v195 offset0:12 offset1:14
	s_waitcnt lgkmcnt(2)
	v_mfma_f32_32x32x16_bf16 v[32:47], v[250:253], v[64:67], v[32:47]
	ds_read2_b64 v[250:253], v194 offset0:72 offset1:74
	s_waitcnt lgkmcnt(2)
	v_mfma_f32_32x32x16_bf16 v[16:31], v[236:239], v[64:67], v[16:31]
	ds_read2_b64 v[236:239], v196 offset0:140 offset1:142
	s_waitcnt lgkmcnt(2)
	v_mfma_f32_32x32x16_bf16 v[16:31], v[246:249], v[68:71], v[16:31]
	ds_read2_b64 v[246:249], v194 offset0:76 offset1:78
	s_waitcnt lgkmcnt(2)
	v_mfma_f32_32x32x16_bf16 v[0:15], v[250:253], v[64:67], v[0:15]
	s_waitcnt lgkmcnt(1)
	v_mfma_f32_32x32x16_bf16 v[32:47], v[236:239], v[68:71], v[32:47]
	s_waitcnt lgkmcnt(0)
	v_mfma_f32_32x32x16_bf16 v[0:15], v[246:249], v[68:71], v[0:15]
	s_cbranch_scc1 .LBB0_479
; #define MFMA(a, b, c) __builtin_amdgcn_mfma_f32_32x32x16_bf16((a), (b), (c), 0, 0, 0)
; DI f32x16 zero16() { f32x16 z; for (int i = 0; i < 16; ++i) z[i] = 0.f; return z; }
; DI void attn_unit(const Params& p, int l, int unit, unsigned char* smem) {
;     ...
;   for (int kt = 0; kt < ntile; ++kt) {
;     __syncthreads();
; #pragma unroll
;     for (int i = 0; i < 4; ++i) {
;       const int c = tid + 256 * i;
;       { const int key = c >> 4, kc = c & 15; *(u32x4*)(sK + key * 136 + 8 * kc) = rk[i]; }
;       { const int dv = c >> 3, kc = c & 7; *(u32x4*)(sVT + dv * 72 + 8 * kc) = rv[i]; }
;     }
;     __syncthreads();
;     if (kt + 1 < ntile) {
; #pragma unroll
;       for (int i = 0; i < 4; ++i) {
;         const int c = tid + 256 * i;
;         { const int key = c >> 4, kc = c & 15; rk[i] = *(const u32x4*)(Kbase + (size_t)((kt + 1) * 64 + key) * PLD + 8 * kc); }
;         { const int dv = c >> 3, kc = c & 7; rv[i] = *(const u32x4*)(VT + (size_t)dv * SP + (kt + 1) * 64 + 8 * kc); }
;       }
;     }
; #pragma unroll
;     for (int kb = 0; kb < 2; ++kb) {
;       f32x16 s0 = zero16(), s1 = zero16();
; #pragma unroll
;       for (int s = 0; s < 4; ++s) {
;         s0 = MFMA(ld16(sK + (32 * kb + l31) * 136 + 16 * s + 8 * h), qf[0][s], s0);
;         s1 = MFMA(ld16(sK + (32 * kb + l31) * 136 + 64 + 16 * s + 8 * h), qf[1][s], s1);
;       }
; #pragma unroll
;       for (int r = 0; r < 16; ++r) s0[r] = __builtin_amdgcn_exp2f(fmaf(s0[r], cs, nm[0])) * sc[0] - __builtin_amdgcn_exp2f(fmaf(s1[r], cs, nm[1])) * sc[1];
;       const bf16x8 p0 = pack8<0>(s0), p1 = pack8<1>(s0);
; #pragma unroll
;       for (int dvb = 0; dvb < 4; ++dvb) {
;         oacc[dvb] = MFMA(ld2x8(sVT + (32 * dvb + l31) * 72 + 32 * kb + 4 * h), p0, oacc[dvb]);
;         oacc[dvb] = MFMA(ld2x8(sVT + (32 * dvb + l31) * 72 + 32 * kb + 16 + 4 * h), p1, oacc[dvb]);
;       }
;     }
	s_barrier
	s_waitcnt vmcnt(0)
	ds_write_b128 v187, v[128:131]
	ds_write_b128 v203, v[132:135] offset:17408
	ds_write_b128 v186, v[136:139]
	ds_write_b128 v202, v[140:143] offset:17408
	ds_write_b128 v185, v[144:147]
	ds_write_b128 v201, v[148:151] offset:17408
	ds_write_b128 v184, v[152:155]
	ds_write_b128 v200, v[156:159] offset:17408
	s_waitcnt lgkmcnt(0)
	s_barrier
	ds_read_b128 v[64:67], v197
	ds_read_b128 v[128:131], v197 offset:32
	s_waitcnt lgkmcnt(1)
	v_mfma_f32_32x32x16_bf16 v[64:79], v[64:67], v[120:123], 0
	ds_read_b128 v[80:83], v197 offset:128
	s_lshl_b32 s44, s8, 1
	v_lshlrev_b32_e32 v208, 1, v188
	s_mov_b32 s40, 0x800000
	s_waitcnt lgkmcnt(1)
	v_mfma_f32_32x32x16_bf16 v[64:79], v[128:131], v[116:119], v[64:79]
	ds_read_b128 v[128:131], v197 offset:160
	s_waitcnt lgkmcnt(1)
	v_mfma_f32_32x32x16_bf16 v[80:95], v[80:83], v[124:127], 0
	s_waitcnt lgkmcnt(0)
	v_mfma_f32_32x32x16_bf16 v[80:95], v[128:131], v[112:115], v[80:95]
	ds_read_b128 v[128:131], v197 offset:64
	s_waitcnt lgkmcnt(0)
	v_mfma_f32_32x32x16_bf16 v[64:79], v[128:131], v[104:107], v[64:79]
	ds_read_b128 v[128:131], v197 offset:192
	s_waitcnt lgkmcnt(0)
	v_mfma_f32_32x32x16_bf16 v[80:95], v[128:131], v[108:111], v[80:95]
	ds_read_b128 v[128:131], v197 offset:96
	s_waitcnt lgkmcnt(0)
	v_mfma_f32_32x32x16_bf16 v[64:79], v[128:131], v[100:103], v[64:79]
	ds_read_b128 v[128:131], v197 offset:224
	s_waitcnt lgkmcnt(0)
	v_mfma_f32_32x32x16_bf16 v[80:95], v[128:131], v[96:99], v[80:95]
	s_nop 8
	v_fmamk_f32 v64, v64, 0x3e38aa3b, v190
	v_fmamk_f32 v65, v65, 0x3e38aa3b, v190
	v_exp_f32_e32 v64, v64
	v_exp_f32_e32 v65, v65
	v_fmamk_f32 v66, v66, 0x3e38aa3b, v190
	v_fmamk_f32 v67, v67, 0x3e38aa3b, v190
	v_exp_f32_e32 v66, v66
	v_fmamk_f32 v80, v80, 0x3e38aa3b, v191
	v_fmamk_f32 v81, v81, 0x3e38aa3b, v191
	v_exp_f32_e32 v80, v80
	v_exp_f32_e32 v81, v81
	v_exp_f32_e32 v67, v67
	v_fmamk_f32 v68, v68, 0x3e38aa3b, v190
	v_fmamk_f32 v69, v69, 0x3e38aa3b, v190
	v_pk_mul_f32 v[80:81], v[166:167], v[80:81]
	v_exp_f32_e32 v68, v68
	v_pk_fma_f32 v[64:65], v[164:165], v[64:65], v[80:81] neg_lo:[0,0,1] neg_hi:[0,0,1]
	v_fmamk_f32 v80, v82, 0x3e38aa3b, v191
	v_fmamk_f32 v81, v83, 0x3e38aa3b, v191
	v_exp_f32_e32 v80, v80
	v_exp_f32_e32 v81, v81
	v_exp_f32_e32 v69, v69
	v_fmamk_f32 v70, v70, 0x3e38aa3b, v190
	v_fmamk_f32 v71, v71, 0x3e38aa3b, v190
	v_pk_mul_f32 v[80:81], v[166:167], v[80:81]
	v_exp_f32_e32 v70, v70
	v_pk_fma_f32 v[66:67], v[164:165], v[66:67], v[80:81] neg_lo:[0,0,1] neg_hi:[0,0,1]
	v_fmamk_f32 v80, v84, 0x3e38aa3b, v191
	v_fmamk_f32 v81, v85, 0x3e38aa3b, v191
	v_exp_f32_e32 v80, v80
	v_exp_f32_e32 v81, v81
	v_exp_f32_e32 v71, v71
	v_fmamk_f32 v72, v72, 0x3e38aa3b, v190
	v_fmamk_f32 v73, v73, 0x3e38aa3b, v190
	v_pk_mul_f32 v[80:81], v[166:167], v[80:81]
	v_exp_f32_e32 v72, v72
	v_pk_fma_f32 v[68:69], v[164:165], v[68:69], v[80:81] neg_lo:[0,0,1] neg_hi:[0,0,1]
	v_fmamk_f32 v80, v86, 0x3e38aa3b, v191
	v_fmamk_f32 v81, v87, 0x3e38aa3b, v191
	v_exp_f32_e32 v80, v80
	v_exp_f32_e32 v81, v81
	v_exp_f32_e32 v73, v73
	v_fmamk_f32 v74, v74, 0x3e38aa3b, v190
	v_fmamk_f32 v75, v75, 0x3e38aa3b, v190
	v_pk_mul_f32 v[80:81], v[166:167], v[80:81]
	v_exp_f32_e32 v74, v74
	v_pk_fma_f32 v[70:71], v[164:165], v[70:71], v[80:81] neg_lo:[0,0,1] neg_hi:[0,0,1]
	v_fmamk_f32 v80, v88, 0x3e38aa3b, v191
	v_fmamk_f32 v81, v89, 0x3e38aa3b, v191
	v_exp_f32_e32 v80, v80
	v_exp_f32_e32 v81, v81
	v_exp_f32_e32 v75, v75
	v_fmamk_f32 v76, v76, 0x3e38aa3b, v190
	v_fmamk_f32 v77, v77, 0x3e38aa3b, v190
	v_pk_mul_f32 v[80:81], v[166:167], v[80:81]
	v_exp_f32_e32 v76, v76
	v_pk_fma_f32 v[72:73], v[164:165], v[72:73], v[80:81] neg_lo:[0,0,1] neg_hi:[0,0,1]
	v_fmamk_f32 v80, v90, 0x3e38aa3b, v191
	v_fmamk_f32 v81, v91, 0x3e38aa3b, v191
	v_exp_f32_e32 v80, v80
	v_exp_f32_e32 v81, v81
	v_exp_f32_e32 v77, v77
	v_fmamk_f32 v78, v78, 0x3e38aa3b, v190
	v_fmamk_f32 v79, v79, 0x3e38aa3b, v190
	v_pk_mul_f32 v[80:81], v[166:167], v[80:81]
	v_exp_f32_e32 v78, v78
	v_pk_fma_f32 v[74:75], v[164:165], v[74:75], v[80:81] neg_lo:[0,0,1] neg_hi:[0,0,1]
	v_fmamk_f32 v80, v92, 0x3e38aa3b, v191
	v_fmamk_f32 v81, v93, 0x3e38aa3b, v191
	v_exp_f32_e32 v80, v80
	v_exp_f32_e32 v81, v81
	v_exp_f32_e32 v79, v79
	v_cvt_pk_bf16_f32 v64, v64, v65
	v_cvt_pk_bf16_f32 v65, v66, v67
	v_pk_mul_f32 v[80:81], v[166:167], v[80:81]
	v_cvt_pk_bf16_f32 v66, v68, v69
	v_pk_fma_f32 v[76:77], v[164:165], v[76:77], v[80:81] neg_lo:[0,0,1] neg_hi:[0,0,1]
	v_fmamk_f32 v80, v94, 0x3e38aa3b, v191
	v_fmamk_f32 v81, v95, 0x3e38aa3b, v191
	v_exp_f32_e32 v80, v80
	v_exp_f32_e32 v81, v81
	v_cvt_pk_bf16_f32 v67, v70, v71
	v_cvt_pk_bf16_f32 v68, v72, v73
	v_cvt_pk_bf16_f32 v69, v74, v75
	v_pk_mul_f32 v[80:81], v[166:167], v[80:81]
	v_cvt_pk_bf16_f32 v70, v76, v77
	v_pk_fma_f32 v[78:79], v[164:165], v[78:79], v[80:81] neg_lo:[0,0,1] neg_hi:[0,0,1]
	s_nop 0
	v_cvt_pk_bf16_f32 v71, v78, v79
	ds_read2_b64 v[72:75], v193 offset0:128 offset1:130
	ds_read2_b64 v[76:79], v193 offset0:132 offset1:134
	s_waitcnt lgkmcnt(1)
	v_mfma_f32_32x32x16_bf16 v[48:63], v[72:75], v[64:67], v[48:63]
	s_waitcnt lgkmcnt(0)
	v_mfma_f32_32x32x16_bf16 v[48:63], v[76:79], v[68:71], v[48:63]
	ds_read2_b64 v[72:75], v196 offset0:128 offset1:130
	ds_read2_b64 v[76:79], v196 offset0:132 offset1:134
	s_waitcnt lgkmcnt(1)
	v_mfma_f32_32x32x16_bf16 v[32:47], v[72:75], v[64:67], v[32:47]
	ds_read2_b64 v[72:75], v195 offset1:2
	s_waitcnt lgkmcnt(0)
	v_mfma_f32_32x32x16_bf16 v[16:31], v[72:75], v[64:67], v[16:31]
	ds_read2_b64 v[72:75], v195 offset0:4 offset1:6
	s_waitcnt lgkmcnt(0)
	v_mfma_f32_32x32x16_bf16 v[16:31], v[72:75], v[68:71], v[16:31]
	ds_read2_b64 v[72:75], v194 offset0:64 offset1:66
	s_waitcnt lgkmcnt(0)
; #define MFMA(a, b, c) __builtin_amdgcn_mfma_f32_32x32x16_bf16((a), (b), (c), 0, 0, 0)
; DI f32x16 zero16() { f32x16 z; for (int i = 0; i < 16; ++i) z[i] = 0.f; return z; }
; DI void attn_unit(const Params& p, int l, int unit, unsigned char* smem) {
;     ...
; #pragma unroll
;     for (int kb = 0; kb < 2; ++kb) {
;       f32x16 s0 = zero16(), s1 = zero16();
; #pragma unroll
;       for (int s = 0; s < 4; ++s) {
;         s0 = MFMA(ld16(sK + (32 * kb + l31) * 136 + 16 * s + 8 * h), qf[0][s], s0);
;         s1 = MFMA(ld16(sK + (32 * kb + l31) * 136 + 64 + 16 * s + 8 * h), qf[1][s], s1);
;       }
; #pragma unroll
;       for (int r = 0; r < 16; ++r) s0[r] = __builtin_amdgcn_exp2f(fmaf(s0[r], cs, nm[0])) * sc[0] - __builtin_amdgcn_exp2f(fmaf(s1[r], cs, nm[1])) * sc[1];
;       const bf16x8 p0 = pack8<0>(s0), p1 = pack8<1>(s0);
; #pragma unroll
;       for (int dvb = 0; dvb < 4; ++dvb) {
;         oacc[dvb] = MFMA(ld2x8(sVT + (32 * dvb + l31) * 72 + 32 * kb + 4 * h), p0, oacc[dvb]);
;         oacc[dvb] = MFMA(ld2x8(sVT + (32 * dvb + l31) * 72 + 32 * kb + 16 + 4 * h), p1, oacc[dvb]);
;       }
;     }
	v_mfma_f32_32x32x16_bf16 v[0:15], v[72:75], v[64:67], v[0:15]
	ds_read2_b64 v[64:67], v194 offset0:68 offset1:70
	s_waitcnt lgkmcnt(0)
	v_mfma_f32_32x32x16_bf16 v[0:15], v[64:67], v[68:71], v[0:15]
	ds_read_b128 v[64:67], v192
	ds_read_b128 v[128:131], v192 offset:32
	ds_read_b128 v[80:83], v192 offset:128
	v_mfma_f32_32x32x16_bf16 v[32:47], v[76:79], v[68:71], v[32:47]
	s_waitcnt lgkmcnt(2)
	v_mfma_f32_32x32x16_bf16 v[64:79], v[64:67], v[120:123], 0
	s_waitcnt lgkmcnt(1)
	v_mfma_f32_32x32x16_bf16 v[64:79], v[128:131], v[116:119], v[64:79]
	ds_read_b128 v[116:119], v192 offset:160
	s_waitcnt lgkmcnt(1)
	v_mfma_f32_32x32x16_bf16 v[80:95], v[80:83], v[124:127], 0
	s_waitcnt lgkmcnt(0)
	v_mfma_f32_32x32x16_bf16 v[80:95], v[116:119], v[112:115], v[80:95]
	ds_read_b128 v[112:115], v192 offset:64
	s_waitcnt lgkmcnt(0)
	v_mfma_f32_32x32x16_bf16 v[64:79], v[112:115], v[104:107], v[64:79]
	ds_read_b128 v[104:107], v192 offset:192
	s_waitcnt lgkmcnt(0)
	v_mfma_f32_32x32x16_bf16 v[80:95], v[104:107], v[108:111], v[80:95]
	ds_read_b128 v[104:107], v192 offset:96
	s_waitcnt lgkmcnt(0)
	v_mfma_f32_32x32x16_bf16 v[64:79], v[104:107], v[100:103], v[64:79]
	ds_read_b128 v[100:103], v192 offset:224
	s_waitcnt lgkmcnt(0)
	v_mfma_f32_32x32x16_bf16 v[80:95], v[100:103], v[96:99], v[80:95]
	s_nop 8
	v_fmamk_f32 v64, v64, 0x3e38aa3b, v190
	v_fmamk_f32 v65, v65, 0x3e38aa3b, v190
	v_exp_f32_e32 v64, v64
	v_exp_f32_e32 v65, v65
	v_fmamk_f32 v66, v66, 0x3e38aa3b, v190
	v_fmamk_f32 v67, v67, 0x3e38aa3b, v190
	v_exp_f32_e32 v66, v66
	v_fmamk_f32 v80, v80, 0x3e38aa3b, v191
	v_fmamk_f32 v81, v81, 0x3e38aa3b, v191
	v_exp_f32_e32 v80, v80
	v_exp_f32_e32 v81, v81
	v_exp_f32_e32 v67, v67
	v_fmamk_f32 v68, v68, 0x3e38aa3b, v190
	v_fmamk_f32 v69, v69, 0x3e38aa3b, v190
	v_pk_mul_f32 v[80:81], v[166:167], v[80:81]
	v_exp_f32_e32 v68, v68
	v_pk_fma_f32 v[64:65], v[164:165], v[64:65], v[80:81] neg_lo:[0,0,1] neg_hi:[0,0,1]
	v_fmamk_f32 v80, v82, 0x3e38aa3b, v191
	v_fmamk_f32 v81, v83, 0x3e38aa3b, v191
	v_exp_f32_e32 v80, v80
	v_exp_f32_e32 v81, v81
	v_exp_f32_e32 v69, v69
	v_fmamk_f32 v70, v70, 0x3e38aa3b, v190
	v_fmamk_f32 v71, v71, 0x3e38aa3b, v190
	v_pk_mul_f32 v[80:81], v[166:167], v[80:81]
	v_exp_f32_e32 v70, v70
	v_pk_fma_f32 v[66:67], v[164:165], v[66:67], v[80:81] neg_lo:[0,0,1] neg_hi:[0,0,1]
	v_fmamk_f32 v80, v84, 0x3e38aa3b, v191
	v_fmamk_f32 v81, v85, 0x3e38aa3b, v191
	v_exp_f32_e32 v80, v80
	v_exp_f32_e32 v81, v81
	v_exp_f32_e32 v71, v71
	v_fmamk_f32 v72, v72, 0x3e38aa3b, v190
	v_fmamk_f32 v73, v73, 0x3e38aa3b, v190
	v_pk_mul_f32 v[80:81], v[166:167], v[80:81]
	v_exp_f32_e32 v72, v72
	v_pk_fma_f32 v[68:69], v[164:165], v[68:69], v[80:81] neg_lo:[0,0,1] neg_hi:[0,0,1]
	v_fmamk_f32 v80, v86, 0x3e38aa3b, v191
	v_fmamk_f32 v81, v87, 0x3e38aa3b, v191
	v_exp_f32_e32 v80, v80
	v_exp_f32_e32 v81, v81
	v_exp_f32_e32 v73, v73
	v_fmamk_f32 v74, v74, 0x3e38aa3b, v190
	v_fmamk_f32 v75, v75, 0x3e38aa3b, v190
	v_pk_mul_f32 v[80:81], v[166:167], v[80:81]
	v_exp_f32_e32 v74, v74
	v_pk_fma_f32 v[70:71], v[164:165], v[70:71], v[80:81] neg_lo:[0,0,1] neg_hi:[0,0,1]
	v_fmamk_f32 v80, v88, 0x3e38aa3b, v191
	v_fmamk_f32 v81, v89, 0x3e38aa3b, v191
	v_exp_f32_e32 v80, v80
	v_exp_f32_e32 v81, v81
	v_exp_f32_e32 v75, v75
	v_cvt_pk_bf16_f32 v64, v64, v65
	v_cvt_pk_bf16_f32 v65, v66, v67
	v_pk_mul_f32 v[80:81], v[166:167], v[80:81]
	v_cvt_pk_bf16_f32 v66, v68, v69
	v_pk_fma_f32 v[72:73], v[164:165], v[72:73], v[80:81] neg_lo:[0,0,1] neg_hi:[0,0,1]
	v_fmamk_f32 v80, v90, 0x3e38aa3b, v191
	v_fmamk_f32 v81, v91, 0x3e38aa3b, v191
	v_exp_f32_e32 v80, v80
	v_exp_f32_e32 v81, v81
	v_cvt_pk_bf16_f32 v68, v72, v73
	v_fmamk_f32 v76, v76, 0x3e38aa3b, v190
	v_fmamk_f32 v77, v77, 0x3e38aa3b, v190
	v_pk_mul_f32 v[80:81], v[166:167], v[80:81]
	v_exp_f32_e32 v76, v76
	v_pk_fma_f32 v[74:75], v[164:165], v[74:75], v[80:81] neg_lo:[0,0,1] neg_hi:[0,0,1]
	v_fmamk_f32 v80, v92, 0x3e38aa3b, v191
	v_cvt_pk_bf16_f32 v69, v74, v75
	ds_read2_b64 v[72:75], v193 offset0:136 offset1:138
	v_fmamk_f32 v81, v93, 0x3e38aa3b, v191
	v_exp_f32_e32 v80, v80
	v_exp_f32_e32 v81, v81
	v_exp_f32_e32 v77, v77
	v_cvt_pk_bf16_f32 v67, v70, v71
	v_fmamk_f32 v78, v78, 0x3e38aa3b, v190
	v_pk_mul_f32 v[80:81], v[166:167], v[80:81]
	s_waitcnt lgkmcnt(0)
	v_mfma_f32_32x32x16_bf16 v[48:63], v[72:75], v[64:67], v[48:63]
	ds_read2_b64 v[72:75], v193 offset0:140 offset1:142
	v_fma_f32 v76, v164, v76, -v80
	v_fma_f32 v77, v165, v77, -v81
	v_fmamk_f32 v80, v94, 0x3e38aa3b, v191
	v_fmac_f32_e32 v191, 0x3e38aa3b, v95
	v_exp_f32_e32 v80, v80
	v_fmac_f32_e32 v190, 0x3e38aa3b, v79
	v_exp_f32_e32 v81, v191
	v_exp_f32_e32 v78, v78
	v_exp_f32_e32 v79, v190
	v_cvt_pk_bf16_f32 v70, v76, v77
	v_pk_mul_f32 v[80:81], v[166:167], v[80:81]
	s_nop 0
	v_pk_fma_f32 v[78:79], v[164:165], v[78:79], v[80:81] neg_lo:[0,0,1] neg_hi:[0,0,1]
	s_nop 0
	v_cvt_pk_bf16_f32 v71, v78, v79
	s_waitcnt lgkmcnt(0)
	s_nop 0
	v_mfma_f32_32x32x16_bf16 v[48:63], v[72:75], v[68:71], v[48:63]
	ds_read2_b64 v[72:75], v196 offset0:136 offset1:138
	ds_read2_b64 v[76:79], v196 offset0:140 offset1:142
	s_waitcnt lgkmcnt(1)
	v_mfma_f32_32x32x16_bf16 v[32:47], v[72:75], v[64:67], v[32:47]
	ds_read2_b64 v[72:75], v195 offset0:8 offset1:10
	s_waitcnt lgkmcnt(0)
	v_mfma_f32_32x32x16_bf16 v[16:31], v[72:75], v[64:67], v[16:31]
	ds_read2_b64 v[72:75], v195 offset0:12 offset1:14
	s_waitcnt lgkmcnt(0)
	v_mfma_f32_32x32x16_bf16 v[16:31], v[72:75], v[68:71], v[16:31]
	ds_read2_b64 v[72:75], v194 offset0:72 offset1:74
	s_waitcnt lgkmcnt(0)
; #define MFMA(a, b, c) __builtin_amdgcn_mfma_f32_32x32x16_bf16((a), (b), (c), 0, 0, 0)
; DI float bf2f(bfr v) { return __uint_as_float(((unsigned)v) << 16); }
; DI float siluf_(float x) { return x / (1.f + __expf(-x)); }
; DI void attn_unit(const Params& p, int l, int unit, unsigned char* smem) {
;     ...
;         oacc[dvb] = MFMA(ld2x8(sVT + (32 * dvb + l31) * 72 + 32 * kb + 4 * h), p0, oacc[dvb]);
;         oacc[dvb] = MFMA(ld2x8(sVT + (32 * dvb + l31) * 72 + 32 * kb + 16 + 4 * h), p1, oacc[dvb]);
;       }
;     }
;   }
;   float ss = 0.f;
; #pragma unroll
;   for (int dvb = 0; dvb < 4; ++dvb)
; #pragma unroll
;     for (int r = 0; r < 16; ++r) ss += oacc[dvb][r] * oacc[dvb][r];
;   ss += __shfl_xor(ss, 32);
;   const float rs = rsqrtf(ss * (1.f / 128.f) + EPS) * (1.f - lam_init);
;   bfr* YS = (bfr*)(WS_ + O_YS);
; #pragma unroll
;   for (int dvb = 0; dvb < 4; ++dvb)
; #pragma unroll
;     for (int g = 0; g < 4; ++g) {
;       const int dv = 32 * dvb + 8 * g + 4 * h;
;       const s16x4 z4 = *(const s16x4*)(P + rowq * PLD + C_DAZ + hd * 128 + dv);
;       const f32x4 gn = *(const f32x4*)(p.da_norm + l * 128 + dv);
;       float y[4];
;       for (int q = 0; q < 4; ++q) y[q] = oacc[dvb][4 * g + q] * rs * gn[q] * siluf_(bf2f((bfr)z4[q]));
	v_mfma_f32_32x32x16_bf16 v[0:15], v[72:75], v[64:67], v[0:15]
	v_mul_f32_e32 v74, v49, v49
	v_fmac_f32_e32 v74, v48, v48
	v_fmac_f32_e32 v74, v50, v50
	v_fmac_f32_e32 v74, v51, v51
	v_fmac_f32_e32 v74, v52, v52
	v_fmac_f32_e32 v74, v53, v53
	v_fmac_f32_e32 v74, v54, v54
	v_fmac_f32_e32 v74, v55, v55
	v_mfma_f32_32x32x16_bf16 v[32:47], v[76:79], v[68:71], v[32:47]
	v_fmac_f32_e32 v74, v56, v56
	v_fmac_f32_e32 v74, v57, v57
	v_fmac_f32_e32 v74, v58, v58
	v_fmac_f32_e32 v74, v59, v59
	v_fmac_f32_e32 v74, v60, v60
	v_fmac_f32_e32 v74, v61, v61
	v_fmac_f32_e32 v74, v62, v62
	v_fmac_f32_e32 v74, v63, v63
	s_nop 3
	v_fmac_f32_e32 v74, v32, v32
	v_fmac_f32_e32 v74, v33, v33
	v_fmac_f32_e32 v74, v34, v34
	v_fmac_f32_e32 v74, v35, v35
	v_fmac_f32_e32 v74, v36, v36
	v_fmac_f32_e32 v74, v37, v37
	v_fmac_f32_e32 v74, v38, v38
	v_fmac_f32_e32 v74, v39, v39
	v_fmac_f32_e32 v74, v40, v40
	v_fmac_f32_e32 v74, v41, v41
	v_fmac_f32_e32 v74, v42, v42
	v_fmac_f32_e32 v74, v43, v43
	v_fmac_f32_e32 v74, v44, v44
	v_fmac_f32_e32 v74, v45, v45
	v_fmac_f32_e32 v74, v46, v46
	ds_read2_b64 v[64:67], v194 offset0:76 offset1:78
	v_fmac_f32_e32 v74, v47, v47
	v_fmac_f32_e32 v74, v16, v16
	v_fmac_f32_e32 v74, v17, v17
	v_fmac_f32_e32 v74, v18, v18
	v_fmac_f32_e32 v74, v19, v19
	v_fmac_f32_e32 v74, v20, v20
	v_fmac_f32_e32 v74, v21, v21
	v_fmac_f32_e32 v74, v22, v22
	v_fmac_f32_e32 v74, v23, v23
	s_waitcnt lgkmcnt(0)
	v_mfma_f32_32x32x16_bf16 v[0:15], v[64:67], v[68:71], v[0:15]
	v_fmac_f32_e32 v74, v24, v24
	v_fmac_f32_e32 v74, v25, v25
	v_fmac_f32_e32 v74, v26, v26
	v_fmac_f32_e32 v74, v27, v27
	v_fmac_f32_e32 v74, v28, v28
	v_fmac_f32_e32 v74, v29, v29
	v_fmac_f32_e32 v74, v30, v30
	v_fmac_f32_e32 v74, v31, v31
	s_nop 3
	v_fmac_f32_e32 v74, v0, v0
	v_fmac_f32_e32 v74, v1, v1
	v_fmac_f32_e32 v74, v2, v2
	v_fmac_f32_e32 v74, v3, v3
	v_fmac_f32_e32 v74, v4, v4
	v_fmac_f32_e32 v74, v5, v5
	v_pk_mul_f32 v[72:73], v[6:7], v[6:7]
	v_pk_mul_f32 v[70:71], v[8:9], v[8:9]
	v_add_f32_e32 v72, v72, v74
	v_add_f32_e32 v72, v73, v72
	v_add_f32_e32 v70, v70, v72
	v_pk_mul_f32 v[68:69], v[10:11], v[10:11]
	v_add_f32_e32 v70, v71, v70
	v_add_f32_e32 v68, v68, v70
	v_pk_mul_f32 v[66:67], v[12:13], v[12:13]
	v_add_f32_e32 v68, v69, v68
	v_add_f32_e32 v66, v66, v68
	v_pk_mul_f32 v[64:65], v[14:15], v[14:15]
	v_add_f32_e32 v66, v67, v66
	v_add_f32_e32 v64, v64, v66
	v_add_f32_e32 v64, v65, v64
	ds_bpermute_b32 v65, v189, v64
	v_lshlrev_b64 v[68:69], 12, v[160:161]
	v_lshl_add_u64 v[66:67], v[162:163], 0, s[44:45]
	v_lshl_add_u64 v[68:69], s[4:5], 0, v[68:69]
	v_lshl_add_u64 v[72:73], v[68:69], 0, s[44:45]
	s_waitcnt lgkmcnt(0)
	v_add_f32_e32 v64, v64, v65
	v_fmamk_f32 v64, v64, 0x3c000000, v217
	v_cmp_gt_f32_e32 vcc, s30, v64
	v_mul_f32_e32 v65, 0x4b800000, v64
	v_lshl_add_u64 v[68:69], v[66:67], 0, v[208:209]
	v_cndmask_b32_e32 v64, v64, v65, vcc
	v_rsq_f32_e32 v64, v64
	s_mov_b64 s[4:5], 0x3c00
	v_lshl_add_u64 v[66:67], v[68:69], 0, s[4:5]
	s_movk_i32 s4, 0x3000
	v_mul_f32_e32 v65, 0x45800000, v64
	v_cndmask_b32_e32 v64, v64, v65, vcc
	v_add_co_u32_e32 v68, vcc, s4, v68
	v_lshlrev_b32_e32 v65, 2, v188
	s_nop 0
	v_addc_co_u32_e32 v69, vcc, 0, v69, vcc
	global_load_dwordx2 v[96:97], v[68:69], off offset:3072
	global_load_dwordx4 v[136:139], v65, s[18:19]
	global_load_dwordx2 v[98:99], v[66:67], off offset:16
	global_load_dwordx4 v[140:143], v65, s[18:19] offset:32
	global_load_dwordx2 v[100:101], v[66:67], off offset:32
	global_load_dwordx4 v[144:147], v65, s[18:19] offset:64
	global_load_dwordx2 v[102:103], v[66:67], off offset:48
	global_load_dwordx4 v[148:151], v65, s[18:19] offset:96
	global_load_dwordx2 v[104:105], v[66:67], off offset:64
	global_load_dwordx4 v[152:155], v65, s[18:19] offset:128
	global_load_dwordx2 v[106:107], v[66:67], off offset:80
	global_load_dwordx4 v[156:159], v65, s[18:19] offset:160
	global_load_dwordx2 v[108:109], v[66:67], off offset:96
	global_load_dwordx4 v[160:163], v65, s[18:19] offset:192
	global_load_dwordx2 v[110:111], v[66:67], off offset:112
	global_load_dwordx4 v[164:167], v65, s[18:19] offset:224
	global_load_dwordx2 v[112:113], v[66:67], off offset:128
	global_load_dwordx4 v[168:171], v65, s[18:19] offset:256
	global_load_dwordx2 v[114:115], v[66:67], off offset:144
	global_load_dwordx4 v[172:175], v65, s[18:19] offset:288
	global_load_dwordx2 v[82:83], v[66:67], off offset:160
	global_load_dwordx4 v[176:179], v65, s[18:19] offset:320
	global_load_dwordx2 v[84:85], v[66:67], off offset:176
	global_load_dwordx4 v[180:183], v65, s[18:19] offset:352
	global_load_dwordx2 v[86:87], v[66:67], off offset:192
	global_load_dwordx4 v[184:187], v65, s[18:19] offset:384
	global_load_dwordx2 v[88:89], v[66:67], off offset:208
	global_load_dwordx4 v[188:191], v65, s[18:19] offset:416
	global_load_dwordx2 v[90:91], v[66:67], off offset:224
	global_load_dwordx4 v[192:195], v65, s[18:19] offset:448
	global_load_dwordx2 v[92:93], v[66:67], off offset:240
	global_load_dwordx4 v[196:199], v65, s[18:19] offset:480
	s_waitcnt vmcnt(0)
; DI float bf2f(bfr v) { return __uint_as_float(((unsigned)v) << 16); }
; DI unsigned pk2(float a, float b) { f2_t v = {a, b}; bf2_t r = __builtin_convertvector(v, bf2_t); return __builtin_bit_cast(unsigned, r); }
; DI float siluf_(float x) { return x / (1.f + __expf(-x)); }
; DI void attn_unit(const Params& p, int l, int unit, unsigned char* smem) {
;     ...
; #pragma unroll
;   for (int dvb = 0; dvb < 4; ++dvb)
; #pragma unroll
;     for (int g = 0; g < 4; ++g) {
;       const int dv = 32 * dvb + 8 * g + 4 * h;
;       const s16x4 z4 = *(const s16x4*)(P + rowq * PLD + C_DAZ + hd * 128 + dv);
;       const f32x4 gn = *(const f32x4*)(p.da_norm + l * 128 + dv);
;       float y[4];
;       for (int q = 0; q < 4; ++q) y[q] = oacc[dvb][4 * g + q] * rs * gn[q] * siluf_(bf2f((bfr)z4[q]));
;       u32x2 w; w[0] = pk2(y[0], y[1]); w[1] = pk2(y[2], y[3]);
;       *(u32x2*)(YS + rowq * DM + 1536 + hd * 128 + dv) = w;
;     }
	v_mov_b32_e32 v74, v96
	v_mov_b32_e32 v75, v97
	v_mul_f32_e32 v64, v244, v64
	v_mov_b32_e32 v68, v136
	v_mov_b32_e32 v69, v137
	v_mov_b32_e32 v70, v138
	v_mov_b32_e32 v71, v139
	v_pk_mul_f32 v[48:49], v[48:49], v[64:65] op_sel_hi:[1,0]
	v_pk_mul_f32 v[50:51], v[50:51], v[64:65] op_sel_hi:[1,0]
	v_pk_mul_f32 v[52:53], v[52:53], v[64:65] op_sel_hi:[1,0]
	v_pk_mul_f32 v[54:55], v[54:55], v[64:65] op_sel_hi:[1,0]
	v_pk_mul_f32 v[56:57], v[56:57], v[64:65] op_sel_hi:[1,0]
	v_pk_mul_f32 v[32:33], v[32:33], v[64:65] op_sel_hi:[1,0]
	v_pk_mul_f32 v[34:35], v[34:35], v[64:65] op_sel_hi:[1,0]
	v_pk_mul_f32 v[36:37], v[36:37], v[64:65] op_sel_hi:[1,0]
	v_pk_mul_f32 v[38:39], v[38:39], v[64:65] op_sel_hi:[1,0]
	v_pk_mul_f32 v[40:41], v[40:41], v[64:65] op_sel_hi:[1,0]
	v_pk_mul_f32 v[16:17], v[16:17], v[64:65] op_sel_hi:[1,0]
	v_pk_mul_f32 v[18:19], v[18:19], v[64:65] op_sel_hi:[1,0]
	v_pk_mul_f32 v[20:21], v[20:21], v[64:65] op_sel_hi:[1,0]
	v_pk_mul_f32 v[22:23], v[22:23], v[64:65] op_sel_hi:[1,0]
	v_pk_mul_f32 v[24:25], v[24:25], v[64:65] op_sel_hi:[1,0]
	v_pk_mul_f32 v[0:1], v[0:1], v[64:65] op_sel_hi:[1,0]
	v_pk_mul_f32 v[2:3], v[2:3], v[64:65] op_sel_hi:[1,0]
	v_pk_mul_f32 v[4:5], v[4:5], v[64:65] op_sel_hi:[1,0]
	v_pk_mul_f32 v[6:7], v[6:7], v[64:65] op_sel_hi:[1,0]
	v_pk_mul_f32 v[8:9], v[8:9], v[64:65] op_sel_hi:[1,0]
	s_waitcnt lgkmcnt(0)
	v_and_b32_e32 v78, 0xffff0000, v74
	v_lshlrev_b32_e32 v74, 16, v74
	v_mul_f32_e32 v76, 0xbfb8aa3b, v74
	v_pk_mul_f32 v[48:49], v[68:69], v[48:49]
	v_mul_f32_e32 v68, 0xbfb8aa3b, v78
	v_exp_f32_e32 v76, v76
	v_exp_f32_e32 v77, v68
	v_pk_mul_f32 v[50:51], v[70:71], v[50:51]
	v_pk_add_f32 v[68:69], v[76:77], 1.0 op_sel_hi:[1,0]
	s_nop 0
	v_div_scale_f32 v76, s[4:5], v69, v69, v78
	v_rcp_f32_e32 v77, v76
	s_nop 0
	v_fma_f32 v79, -v76, v77, 1.0
	v_fmac_f32_e32 v77, v79, v77
	v_div_scale_f32 v79, vcc, v78, v69, v78
	v_mul_f32_e32 v80, v79, v77
	v_fma_f32 v81, -v76, v80, v79
	v_fmac_f32_e32 v80, v81, v77
	v_fma_f32 v76, -v76, v80, v79
	v_div_fmas_f32 v76, v76, v77, v80
	v_div_fixup_f32 v69, v76, v69, v78
	v_div_scale_f32 v76, s[4:5], v68, v68, v74
	v_rcp_f32_e32 v77, v76
	s_nop 0
	v_fma_f32 v78, -v76, v77, 1.0
	v_fmac_f32_e32 v77, v78, v77
	v_div_scale_f32 v78, vcc, v74, v68, v74
	v_mul_f32_e32 v79, v78, v77
	v_fma_f32 v80, -v76, v79, v78
	v_fmac_f32_e32 v79, v80, v77
	v_fma_f32 v76, -v76, v79, v78
	v_div_fmas_f32 v76, v76, v77, v79
	v_div_fixup_f32 v68, v76, v68, v74
	v_and_b32_e32 v74, 0xffff0000, v75
	v_lshlrev_b32_e32 v75, 16, v75
	v_pk_mul_f32 v[48:49], v[68:69], v[48:49]
	v_mul_f32_e32 v68, 0xbfb8aa3b, v75
	v_mul_f32_e32 v69, 0xbfb8aa3b, v74
	v_exp_f32_e32 v68, v68
	v_exp_f32_e32 v69, v69
	s_nop 0
	v_pk_add_f32 v[68:69], v[68:69], 1.0 op_sel_hi:[1,0]
	s_nop 0
	v_div_scale_f32 v70, s[4:5], v69, v69, v74
	v_rcp_f32_e32 v71, v70
	s_nop 0
	v_fma_f32 v76, -v70, v71, 1.0
	v_fmac_f32_e32 v71, v76, v71
	v_div_scale_f32 v76, vcc, v74, v69, v74
	v_mul_f32_e32 v77, v76, v71
	v_fma_f32 v78, -v70, v77, v76
	v_fmac_f32_e32 v77, v78, v71
	v_fma_f32 v70, -v70, v77, v76
	v_div_fmas_f32 v70, v70, v71, v77
	v_div_fixup_f32 v69, v70, v69, v74
	v_div_scale_f32 v70, s[4:5], v68, v68, v75
	v_rcp_f32_e32 v71, v70
	s_mov_b64 s[4:5], 0x33110c00
	v_fma_f32 v74, -v70, v71, 1.0
	v_fmac_f32_e32 v71, v74, v71
	v_div_scale_f32 v74, vcc, v75, v68, v75
	v_mul_f32_e32 v76, v74, v71
	v_fma_f32 v77, -v70, v76, v74
	v_fmac_f32_e32 v76, v77, v71
	v_fma_f32 v70, -v70, v76, v74
	v_div_fmas_f32 v70, v70, v71, v76
	v_div_fixup_f32 v68, v70, v68, v75
	v_pk_mul_f32 v[50:51], v[68:69], v[50:51]
	v_cvt_pk_bf16_f32 v68, v48, v49
	v_cvt_pk_bf16_f32 v69, v50, v51
	v_lshl_add_u64 v[50:51], v[72:73], 0, v[208:209]
	v_lshl_add_u64 v[48:49], v[50:51], 0, s[4:5]
	s_mov_b32 s4, 0x33110000
	v_add_co_u32_e32 v50, vcc, s4, v50
	s_nop 1
	v_addc_co_u32_e32 v51, vcc, 0, v51, vcc
	global_store_dwordx2 v[50:51], v[68:69], off offset:3072
	v_mov_b32_e32 v50, v98
	v_mov_b32_e32 v51, v99
	s_nop 0
	v_mov_b32_e32 v68, v140
	v_mov_b32_e32 v69, v141
	v_mov_b32_e32 v70, v142
	v_mov_b32_e32 v71, v143
	s_waitcnt lgkmcnt(0)
	v_and_b32_e32 v74, 0xffff0000, v50
	v_lshlrev_b32_e32 v50, 16, v50
	v_mul_f32_e32 v72, 0xbfb8aa3b, v50
	v_pk_mul_f32 v[52:53], v[68:69], v[52:53]
	v_mul_f32_e32 v68, 0xbfb8aa3b, v74
	v_exp_f32_e32 v72, v72
	v_exp_f32_e32 v73, v68
	v_pk_mul_f32 v[54:55], v[70:71], v[54:55]
	v_pk_add_f32 v[68:69], v[72:73], 1.0 op_sel_hi:[1,0]
	s_nop 0
	v_div_scale_f32 v72, s[4:5], v69, v69, v74
	v_rcp_f32_e32 v73, v72
	s_nop 0
	v_fma_f32 v75, -v72, v73, 1.0
	v_fmac_f32_e32 v73, v75, v73
	v_div_scale_f32 v75, vcc, v74, v69, v74
	v_mul_f32_e32 v76, v75, v73
	v_fma_f32 v77, -v72, v76, v75
	v_fmac_f32_e32 v76, v77, v73
	v_fma_f32 v72, -v72, v76, v75
	v_div_fmas_f32 v72, v72, v73, v76
	v_div_fixup_f32 v69, v72, v69, v74
	v_div_scale_f32 v72, s[4:5], v68, v68, v50
	v_rcp_f32_e32 v73, v72
	s_nop 0
	v_fma_f32 v74, -v72, v73, 1.0
	v_fmac_f32_e32 v73, v74, v73
	v_div_scale_f32 v74, vcc, v50, v68, v50
	v_mul_f32_e32 v75, v74, v73
	v_fma_f32 v76, -v72, v75, v74
	v_fmac_f32_e32 v75, v76, v73
	v_fma_f32 v72, -v72, v75, v74
	v_div_fmas_f32 v72, v72, v73, v75
	v_div_fixup_f32 v68, v72, v68, v50
	v_pk_mul_f32 v[52:53], v[68:69], v[52:53]
	v_and_b32_e32 v68, 0xffff0000, v51
	v_lshlrev_b32_e32 v69, 16, v51
	v_mul_f32_e32 v50, 0xbfb8aa3b, v69
	v_mul_f32_e32 v51, 0xbfb8aa3b, v68
	v_exp_f32_e32 v50, v50
	v_exp_f32_e32 v51, v51
	v_cvt_pk_bf16_f32 v52, v52, v53
	v_pk_add_f32 v[50:51], v[50:51], 1.0 op_sel_hi:[1,0]
	s_nop 0
	v_div_scale_f32 v70, s[4:5], v51, v51, v68
	v_rcp_f32_e32 v71, v70
	s_nop 0
	v_fma_f32 v72, -v70, v71, 1.0
	v_fmac_f32_e32 v71, v72, v71
	v_div_scale_f32 v72, vcc, v68, v51, v68
	v_mul_f32_e32 v73, v72, v71
	v_fma_f32 v74, -v70, v73, v72
	v_fmac_f32_e32 v73, v74, v71
	v_fma_f32 v70, -v70, v73, v72
	v_div_fmas_f32 v70, v70, v71, v73
	v_div_fixup_f32 v51, v70, v51, v68
	v_div_scale_f32 v68, s[4:5], v50, v50, v69
	v_rcp_f32_e32 v70, v68
	s_nop 0
	v_fma_f32 v71, -v68, v70, 1.0
	v_fmac_f32_e32 v70, v71, v70
	v_div_scale_f32 v71, vcc, v69, v50, v69
	v_mul_f32_e32 v72, v71, v70
	v_fma_f32 v73, -v68, v72, v71
	v_fmac_f32_e32 v72, v73, v70
	v_fma_f32 v68, -v68, v72, v71
	v_div_fmas_f32 v68, v68, v70, v72
	v_div_fixup_f32 v50, v68, v50, v69
	v_pk_mul_f32 v[50:51], v[50:51], v[54:55]
	s_nop 0
	v_cvt_pk_bf16_f32 v53, v50, v51
	global_store_dwordx2 v[48:49], v[52:53], off offset:16
	v_mov_b32_e32 v54, v100
	v_mov_b32_e32 v55, v101
	s_nop 0
	v_mov_b32_e32 v50, v144
	v_mov_b32_e32 v51, v145
	v_mov_b32_e32 v52, v146
	v_mov_b32_e32 v53, v147
	s_waitcnt lgkmcnt(0)
; DI float bf2f(bfr v) { return __uint_as_float(((unsigned)v) << 16); }
; DI unsigned pk2(float a, float b) { f2_t v = {a, b}; bf2_t r = __builtin_convertvector(v, bf2_t); return __builtin_bit_cast(unsigned, r); }
; DI float siluf_(float x) { return x / (1.f + __expf(-x)); }
; DI void attn_unit(const Params& p, int l, int unit, unsigned char* smem) {
;     ...
; #pragma unroll
;   for (int dvb = 0; dvb < 4; ++dvb)
; #pragma unroll
;     for (int g = 0; g < 4; ++g) {
;       const int dv = 32 * dvb + 8 * g + 4 * h;
;       const s16x4 z4 = *(const s16x4*)(P + rowq * PLD + C_DAZ + hd * 128 + dv);
;       const f32x4 gn = *(const f32x4*)(p.da_norm + l * 128 + dv);
;       float y[4];
;       for (int q = 0; q < 4; ++q) y[q] = oacc[dvb][4 * g + q] * rs * gn[q] * siluf_(bf2f((bfr)z4[q]));
;       u32x2 w; w[0] = pk2(y[0], y[1]); w[1] = pk2(y[2], y[3]);
;       *(u32x2*)(YS + rowq * DM + 1536 + hd * 128 + dv) = w;
;     }
	v_and_b32_e32 v70, 0xffff0000, v54
	v_lshlrev_b32_e32 v54, 16, v54
	v_mul_f32_e32 v68, 0xbfb8aa3b, v54
	v_pk_mul_f32 v[50:51], v[50:51], v[56:57]
	v_mul_f32_e32 v56, 0xbfb8aa3b, v70
	v_exp_f32_e32 v68, v68
	v_exp_f32_e32 v69, v56
	s_nop 0
	v_pk_add_f32 v[56:57], v[68:69], 1.0 op_sel_hi:[1,0]
	s_nop 0
	v_div_scale_f32 v68, s[4:5], v57, v57, v70
	v_rcp_f32_e32 v69, v68
	s_nop 0
	v_fma_f32 v71, -v68, v69, 1.0
	v_fmac_f32_e32 v69, v71, v69
	v_div_scale_f32 v71, vcc, v70, v57, v70
	v_mul_f32_e32 v72, v71, v69
	v_fma_f32 v73, -v68, v72, v71
	v_fmac_f32_e32 v72, v73, v69
	v_fma_f32 v68, -v68, v72, v71
	v_div_fmas_f32 v68, v68, v69, v72
	v_div_fixup_f32 v57, v68, v57, v70
	v_div_scale_f32 v68, s[4:5], v56, v56, v54
	v_rcp_f32_e32 v69, v68
	s_nop 0
	v_fma_f32 v70, -v68, v69, 1.0
	v_fmac_f32_e32 v69, v70, v69
	v_div_scale_f32 v70, vcc, v54, v56, v54
	v_mul_f32_e32 v71, v70, v69
	v_fma_f32 v72, -v68, v71, v70
	v_fmac_f32_e32 v71, v72, v69
	v_fma_f32 v68, -v68, v71, v70
	v_div_fmas_f32 v68, v68, v69, v71
	v_div_fixup_f32 v56, v68, v56, v54
	v_and_b32_e32 v68, 0xffff0000, v55
	v_lshlrev_b32_e32 v69, 16, v55
	v_mul_f32_e32 v54, 0xbfb8aa3b, v69
	v_mul_f32_e32 v55, 0xbfb8aa3b, v68
	v_exp_f32_e32 v54, v54
	v_exp_f32_e32 v55, v55
	v_pk_mul_f32 v[50:51], v[56:57], v[50:51]
	v_pk_mul_f32 v[56:57], v[58:59], v[64:65] op_sel_hi:[1,0]
	v_cvt_pk_bf16_f32 v50, v50, v51
	v_pk_add_f32 v[54:55], v[54:55], 1.0 op_sel_hi:[1,0]
	v_pk_mul_f32 v[52:53], v[52:53], v[56:57]
	v_div_scale_f32 v56, s[4:5], v55, v55, v68
	v_rcp_f32_e32 v57, v56
	s_nop 0
	v_fma_f32 v58, -v56, v57, 1.0
	v_fmac_f32_e32 v57, v58, v57
	v_div_scale_f32 v58, vcc, v68, v55, v68
	v_mul_f32_e32 v59, v58, v57
	v_fma_f32 v70, -v56, v59, v58
	v_fmac_f32_e32 v59, v70, v57
	v_fma_f32 v56, -v56, v59, v58
	v_div_fmas_f32 v56, v56, v57, v59
	v_div_fixup_f32 v55, v56, v55, v68
	v_div_scale_f32 v56, s[4:5], v54, v54, v69
	v_rcp_f32_e32 v57, v56
	s_nop 0
	v_fma_f32 v58, -v56, v57, 1.0
	v_fmac_f32_e32 v57, v58, v57
	v_div_scale_f32 v58, vcc, v69, v54, v69
	v_mul_f32_e32 v59, v58, v57
	v_fma_f32 v68, -v56, v59, v58
	v_fmac_f32_e32 v59, v68, v57
	v_fma_f32 v56, -v56, v59, v58
	v_div_fmas_f32 v56, v56, v57, v59
	v_div_fixup_f32 v54, v56, v54, v69
	v_pk_mul_f32 v[52:53], v[54:55], v[52:53]
	v_pk_mul_f32 v[58:59], v[60:61], v[64:65] op_sel_hi:[1,0]
	v_cvt_pk_bf16_f32 v51, v52, v53
	global_store_dwordx2 v[48:49], v[50:51], off offset:32
	v_mov_b32_e32 v54, v102
	v_mov_b32_e32 v55, v103
	s_nop 0
	v_mov_b32_e32 v50, v148
	v_mov_b32_e32 v51, v149
	v_mov_b32_e32 v52, v150
	v_mov_b32_e32 v53, v151
	s_waitcnt lgkmcnt(0)
	v_and_b32_e32 v68, 0xffff0000, v54
	v_lshlrev_b32_e32 v54, 16, v54
	v_mul_f32_e32 v56, 0xbfb8aa3b, v54
	v_mul_f32_e32 v57, 0xbfb8aa3b, v68
	v_exp_f32_e32 v56, v56
	v_exp_f32_e32 v57, v57
	v_pk_mul_f32 v[50:51], v[50:51], v[58:59]
	v_pk_add_f32 v[56:57], v[56:57], 1.0 op_sel_hi:[1,0]
	s_nop 0
	v_div_scale_f32 v58, s[4:5], v57, v57, v68
	v_rcp_f32_e32 v59, v58
	s_nop 0
	v_fma_f32 v60, -v58, v59, 1.0
	v_fmac_f32_e32 v59, v60, v59
	v_div_scale_f32 v60, vcc, v68, v57, v68
	v_mul_f32_e32 v61, v60, v59
	v_fma_f32 v69, -v58, v61, v60
	v_fmac_f32_e32 v61, v69, v59
	v_fma_f32 v58, -v58, v61, v60
	v_div_fmas_f32 v58, v58, v59, v61
	v_div_fixup_f32 v57, v58, v57, v68
	v_div_scale_f32 v58, s[4:5], v56, v56, v54
	v_rcp_f32_e32 v59, v58
	s_nop 0
	v_fma_f32 v60, -v58, v59, 1.0
	v_fmac_f32_e32 v59, v60, v59
	v_div_scale_f32 v60, vcc, v54, v56, v54
	v_mul_f32_e32 v61, v60, v59
	v_fma_f32 v68, -v58, v61, v60
	v_fmac_f32_e32 v61, v68, v59
	v_fma_f32 v58, -v58, v61, v60
	v_div_fmas_f32 v58, v58, v59, v61
	v_div_fixup_f32 v56, v58, v56, v54
	v_and_b32_e32 v58, 0xffff0000, v55
	v_lshlrev_b32_e32 v59, 16, v55
	v_mul_f32_e32 v54, 0xbfb8aa3b, v59
	v_mul_f32_e32 v55, 0xbfb8aa3b, v58
	v_exp_f32_e32 v54, v54
	v_exp_f32_e32 v55, v55
	v_pk_mul_f32 v[50:51], v[56:57], v[50:51]
	v_pk_mul_f32 v[56:57], v[62:63], v[64:65] op_sel_hi:[1,0]
	v_cvt_pk_bf16_f32 v50, v50, v51
	v_pk_add_f32 v[54:55], v[54:55], 1.0 op_sel_hi:[1,0]
	v_pk_mul_f32 v[52:53], v[52:53], v[56:57]
	v_div_scale_f32 v56, s[4:5], v55, v55, v58
	v_rcp_f32_e32 v57, v56
	s_nop 0
	v_fma_f32 v60, -v56, v57, 1.0
	v_fmac_f32_e32 v57, v60, v57
	v_div_scale_f32 v60, vcc, v58, v55, v58
	v_mul_f32_e32 v61, v60, v57
	v_fma_f32 v62, -v56, v61, v60
	v_fmac_f32_e32 v61, v62, v57
	v_fma_f32 v56, -v56, v61, v60
	v_div_fmas_f32 v56, v56, v57, v61
	v_div_fixup_f32 v55, v56, v55, v58
	v_div_scale_f32 v56, s[4:5], v54, v54, v59
	v_rcp_f32_e32 v57, v56
	s_nop 0
	v_fma_f32 v58, -v56, v57, 1.0
	v_fmac_f32_e32 v57, v58, v57
	v_div_scale_f32 v58, vcc, v59, v54, v59
	v_mul_f32_e32 v60, v58, v57
	v_fma_f32 v61, -v56, v60, v58
	v_fmac_f32_e32 v60, v61, v57
	v_fma_f32 v56, -v56, v60, v58
	v_div_fmas_f32 v56, v56, v57, v60
	v_div_fixup_f32 v54, v56, v54, v59
	v_pk_mul_f32 v[52:53], v[54:55], v[52:53]
	s_nop 0
	v_cvt_pk_bf16_f32 v51, v52, v53
	global_store_dwordx2 v[48:49], v[50:51], off offset:48
	v_mov_b32_e32 v54, v104
	v_mov_b32_e32 v55, v105
	s_nop 0
	v_mov_b32_e32 v50, v152
	v_mov_b32_e32 v51, v153
	v_mov_b32_e32 v52, v154
	v_mov_b32_e32 v53, v155
	s_waitcnt lgkmcnt(0)
; DI float bf2f(bfr v) { return __uint_as_float(((unsigned)v) << 16); }
; DI unsigned pk2(float a, float b) { f2_t v = {a, b}; bf2_t r = __builtin_convertvector(v, bf2_t); return __builtin_bit_cast(unsigned, r); }
; DI float siluf_(float x) { return x / (1.f + __expf(-x)); }
; DI void attn_unit(const Params& p, int l, int unit, unsigned char* smem) {
;     ...
; #pragma unroll
;   for (int dvb = 0; dvb < 4; ++dvb)
; #pragma unroll
;     for (int g = 0; g < 4; ++g) {
;       const int dv = 32 * dvb + 8 * g + 4 * h;
;       const s16x4 z4 = *(const s16x4*)(P + rowq * PLD + C_DAZ + hd * 128 + dv);
;       const f32x4 gn = *(const f32x4*)(p.da_norm + l * 128 + dv);
;       float y[4];
;       for (int q = 0; q < 4; ++q) y[q] = oacc[dvb][4 * g + q] * rs * gn[q] * siluf_(bf2f((bfr)z4[q]));
;       u32x2 w; w[0] = pk2(y[0], y[1]); w[1] = pk2(y[2], y[3]);
;       *(u32x2*)(YS + rowq * DM + 1536 + hd * 128 + dv) = w;
;     }
	v_and_b32_e32 v58, 0xffff0000, v54
	v_lshlrev_b32_e32 v54, 16, v54
	v_mul_f32_e32 v56, 0xbfb8aa3b, v54
	v_pk_mul_f32 v[32:33], v[50:51], v[32:33]
	v_mul_f32_e32 v50, 0xbfb8aa3b, v58
	v_exp_f32_e32 v56, v56
	v_exp_f32_e32 v57, v50
	v_pk_mul_f32 v[34:35], v[52:53], v[34:35]
	v_pk_add_f32 v[50:51], v[56:57], 1.0 op_sel_hi:[1,0]
	s_nop 0
	v_div_scale_f32 v56, s[4:5], v51, v51, v58
	v_rcp_f32_e32 v57, v56
	s_nop 0
	v_fma_f32 v59, -v56, v57, 1.0
	v_fmac_f32_e32 v57, v59, v57
	v_div_scale_f32 v59, vcc, v58, v51, v58
	v_mul_f32_e32 v60, v59, v57
	v_fma_f32 v61, -v56, v60, v59
	v_fmac_f32_e32 v60, v61, v57
	v_fma_f32 v56, -v56, v60, v59
	v_div_fmas_f32 v56, v56, v57, v60
	v_div_fixup_f32 v51, v56, v51, v58
	v_div_scale_f32 v56, s[4:5], v50, v50, v54
	v_rcp_f32_e32 v57, v56
	s_nop 0
	v_fma_f32 v58, -v56, v57, 1.0
	v_fmac_f32_e32 v57, v58, v57
	v_div_scale_f32 v58, vcc, v54, v50, v54
	v_mul_f32_e32 v59, v58, v57
	v_fma_f32 v60, -v56, v59, v58
	v_fmac_f32_e32 v59, v60, v57
	v_fma_f32 v56, -v56, v59, v58
	v_div_fmas_f32 v56, v56, v57, v59
	v_div_fixup_f32 v50, v56, v50, v54
	v_and_b32_e32 v54, 0xffff0000, v55
	v_lshlrev_b32_e32 v55, 16, v55
	v_pk_mul_f32 v[32:33], v[50:51], v[32:33]
	v_mul_f32_e32 v50, 0xbfb8aa3b, v55
	v_mul_f32_e32 v51, 0xbfb8aa3b, v54
	v_exp_f32_e32 v50, v50
	v_exp_f32_e32 v51, v51
	v_cvt_pk_bf16_f32 v32, v32, v33
	v_pk_add_f32 v[50:51], v[50:51], 1.0 op_sel_hi:[1,0]
	s_nop 0
	v_div_scale_f32 v52, s[4:5], v51, v51, v54
	v_rcp_f32_e32 v53, v52
	s_nop 0
	v_fma_f32 v56, -v52, v53, 1.0
	v_fmac_f32_e32 v53, v56, v53
	v_div_scale_f32 v56, vcc, v54, v51, v54
	v_mul_f32_e32 v57, v56, v53
	v_fma_f32 v58, -v52, v57, v56
	v_fmac_f32_e32 v57, v58, v53
	v_fma_f32 v52, -v52, v57, v56
	v_div_fmas_f32 v52, v52, v53, v57
	v_div_fixup_f32 v51, v52, v51, v54
	v_div_scale_f32 v52, s[4:5], v50, v50, v55
	v_rcp_f32_e32 v53, v52
	s_nop 0
	v_fma_f32 v54, -v52, v53, 1.0
	v_fmac_f32_e32 v53, v54, v53
	v_div_scale_f32 v54, vcc, v55, v50, v55
	v_mul_f32_e32 v56, v54, v53
	v_fma_f32 v57, -v52, v56, v54
	v_fmac_f32_e32 v56, v57, v53
	v_fma_f32 v52, -v52, v56, v54
	v_div_fmas_f32 v52, v52, v53, v56
	v_div_fixup_f32 v50, v52, v50, v55
	v_pk_mul_f32 v[34:35], v[50:51], v[34:35]
	s_nop 0
	v_cvt_pk_bf16_f32 v33, v34, v35
	global_store_dwordx2 v[48:49], v[32:33], off offset:64
	v_mov_b32_e32 v50, v106
	v_mov_b32_e32 v51, v107
	s_nop 0
	v_mov_b32_e32 v32, v156
	v_mov_b32_e32 v33, v157
	v_mov_b32_e32 v34, v158
	v_mov_b32_e32 v35, v159
	s_waitcnt lgkmcnt(0)
	v_and_b32_e32 v54, 0xffff0000, v50
	v_lshlrev_b32_e32 v50, 16, v50
	v_mul_f32_e32 v52, 0xbfb8aa3b, v50
	v_pk_mul_f32 v[32:33], v[32:33], v[36:37]
	v_mul_f32_e32 v36, 0xbfb8aa3b, v54
	v_exp_f32_e32 v52, v52
	v_exp_f32_e32 v53, v36
	v_pk_mul_f32 v[34:35], v[34:35], v[38:39]
	v_pk_add_f32 v[36:37], v[52:53], 1.0 op_sel_hi:[1,0]
	s_nop 0
	v_div_scale_f32 v52, s[4:5], v37, v37, v54
	v_rcp_f32_e32 v53, v52
	s_nop 0
	v_fma_f32 v55, -v52, v53, 1.0
	v_fmac_f32_e32 v53, v55, v53
	v_div_scale_f32 v55, vcc, v54, v37, v54
	v_mul_f32_e32 v56, v55, v53
	v_fma_f32 v57, -v52, v56, v55
	v_fmac_f32_e32 v56, v57, v53
	v_fma_f32 v52, -v52, v56, v55
	v_div_fmas_f32 v52, v52, v53, v56
	v_div_fixup_f32 v37, v52, v37, v54
	v_div_scale_f32 v52, s[4:5], v36, v36, v50
	v_rcp_f32_e32 v53, v52
	s_nop 0
	v_fma_f32 v54, -v52, v53, 1.0
	v_fmac_f32_e32 v53, v54, v53
	v_div_scale_f32 v54, vcc, v50, v36, v50
	v_mul_f32_e32 v55, v54, v53
	v_fma_f32 v56, -v52, v55, v54
	v_fmac_f32_e32 v55, v56, v53
	v_fma_f32 v52, -v52, v55, v54
	v_div_fmas_f32 v52, v52, v53, v55
	v_div_fixup_f32 v36, v52, v36, v50
	v_and_b32_e32 v50, 0xffff0000, v51
	v_lshlrev_b32_e32 v51, 16, v51
	v_pk_mul_f32 v[32:33], v[36:37], v[32:33]
	v_mul_f32_e32 v36, 0xbfb8aa3b, v51
	v_mul_f32_e32 v37, 0xbfb8aa3b, v50
	v_exp_f32_e32 v36, v36
	v_exp_f32_e32 v37, v37
	v_cvt_pk_bf16_f32 v32, v32, v33
	v_pk_add_f32 v[36:37], v[36:37], 1.0 op_sel_hi:[1,0]
	s_nop 0
	v_div_scale_f32 v38, s[4:5], v37, v37, v50
	v_rcp_f32_e32 v39, v38
	s_nop 0
	v_fma_f32 v52, -v38, v39, 1.0
	v_fmac_f32_e32 v39, v52, v39
	v_div_scale_f32 v52, vcc, v50, v37, v50
	v_mul_f32_e32 v53, v52, v39
	v_fma_f32 v54, -v38, v53, v52
	v_fmac_f32_e32 v53, v54, v39
	v_fma_f32 v38, -v38, v53, v52
	v_div_fmas_f32 v38, v38, v39, v53
	v_div_fixup_f32 v37, v38, v37, v50
	v_div_scale_f32 v38, s[4:5], v36, v36, v51
	v_rcp_f32_e32 v39, v38
	s_nop 0
	v_fma_f32 v50, -v38, v39, 1.0
	v_fmac_f32_e32 v39, v50, v39
	v_div_scale_f32 v50, vcc, v51, v36, v51
	v_mul_f32_e32 v52, v50, v39
	v_fma_f32 v53, -v38, v52, v50
	v_fmac_f32_e32 v52, v53, v39
	v_fma_f32 v38, -v38, v52, v50
	v_div_fmas_f32 v38, v38, v39, v52
	v_div_fixup_f32 v36, v38, v36, v51
	v_pk_mul_f32 v[34:35], v[36:37], v[34:35]
	s_nop 0
	v_cvt_pk_bf16_f32 v33, v34, v35
	global_store_dwordx2 v[48:49], v[32:33], off offset:80
	v_mov_b32_e32 v36, v108
	v_mov_b32_e32 v37, v109
	s_nop 0
	v_mov_b32_e32 v32, v160
	v_mov_b32_e32 v33, v161
	v_mov_b32_e32 v34, v162
	v_mov_b32_e32 v35, v163
	s_waitcnt lgkmcnt(0)
; DI float bf2f(bfr v) { return __uint_as_float(((unsigned)v) << 16); }
; DI unsigned pk2(float a, float b) { f2_t v = {a, b}; bf2_t r = __builtin_convertvector(v, bf2_t); return __builtin_bit_cast(unsigned, r); }
; DI float siluf_(float x) { return x / (1.f + __expf(-x)); }
; DI void attn_unit(const Params& p, int l, int unit, unsigned char* smem) {
;     ...
; #pragma unroll
;   for (int dvb = 0; dvb < 4; ++dvb)
; #pragma unroll
;     for (int g = 0; g < 4; ++g) {
;       const int dv = 32 * dvb + 8 * g + 4 * h;
;       const s16x4 z4 = *(const s16x4*)(P + rowq * PLD + C_DAZ + hd * 128 + dv);
;       const f32x4 gn = *(const f32x4*)(p.da_norm + l * 128 + dv);
;       float y[4];
;       for (int q = 0; q < 4; ++q) y[q] = oacc[dvb][4 * g + q] * rs * gn[q] * siluf_(bf2f((bfr)z4[q]));
;       u32x2 w; w[0] = pk2(y[0], y[1]); w[1] = pk2(y[2], y[3]);
;       *(u32x2*)(YS + rowq * DM + 1536 + hd * 128 + dv) = w;
;     }
	v_and_b32_e32 v50, 0xffff0000, v36
	v_lshlrev_b32_e32 v36, 16, v36
	v_mul_f32_e32 v38, 0xbfb8aa3b, v36
	v_mul_f32_e32 v39, 0xbfb8aa3b, v50
	v_exp_f32_e32 v38, v38
	v_exp_f32_e32 v39, v39
	v_pk_mul_f32 v[32:33], v[32:33], v[40:41]
	v_pk_add_f32 v[38:39], v[38:39], 1.0 op_sel_hi:[1,0]
	s_nop 0
	v_div_scale_f32 v40, s[4:5], v39, v39, v50
	v_rcp_f32_e32 v41, v40
	s_nop 0
	v_fma_f32 v51, -v40, v41, 1.0
	v_fmac_f32_e32 v41, v51, v41
	v_div_scale_f32 v51, vcc, v50, v39, v50
	v_mul_f32_e32 v52, v51, v41
	v_fma_f32 v53, -v40, v52, v51
	v_fmac_f32_e32 v52, v53, v41
	v_fma_f32 v40, -v40, v52, v51
	v_div_fmas_f32 v40, v40, v41, v52
	v_div_fixup_f32 v39, v40, v39, v50
	v_div_scale_f32 v40, s[4:5], v38, v38, v36
	v_rcp_f32_e32 v41, v40
	s_nop 0
	v_fma_f32 v50, -v40, v41, 1.0
	v_fmac_f32_e32 v41, v50, v41
	v_div_scale_f32 v50, vcc, v36, v38, v36
	v_mul_f32_e32 v51, v50, v41
	v_fma_f32 v52, -v40, v51, v50
	v_fmac_f32_e32 v51, v52, v41
	v_fma_f32 v40, -v40, v51, v50
	v_div_fmas_f32 v40, v40, v41, v51
	v_div_fixup_f32 v38, v40, v38, v36
	v_and_b32_e32 v40, 0xffff0000, v37
	v_lshlrev_b32_e32 v41, 16, v37
	v_mul_f32_e32 v36, 0xbfb8aa3b, v41
	v_mul_f32_e32 v37, 0xbfb8aa3b, v40
	v_exp_f32_e32 v36, v36
	v_exp_f32_e32 v37, v37
	v_pk_mul_f32 v[32:33], v[38:39], v[32:33]
	v_pk_mul_f32 v[38:39], v[42:43], v[64:65] op_sel_hi:[1,0]
	v_cvt_pk_bf16_f32 v32, v32, v33
	v_pk_add_f32 v[36:37], v[36:37], 1.0 op_sel_hi:[1,0]
	v_pk_mul_f32 v[34:35], v[34:35], v[38:39]
	v_div_scale_f32 v38, s[4:5], v37, v37, v40
	v_rcp_f32_e32 v39, v38
	s_nop 0
	v_fma_f32 v42, -v38, v39, 1.0
	v_fmac_f32_e32 v39, v42, v39
	v_div_scale_f32 v42, vcc, v40, v37, v40
	v_mul_f32_e32 v43, v42, v39
	v_fma_f32 v50, -v38, v43, v42
	v_fmac_f32_e32 v43, v50, v39
	v_fma_f32 v38, -v38, v43, v42
	v_div_fmas_f32 v38, v38, v39, v43
	v_div_fixup_f32 v37, v38, v37, v40
	v_div_scale_f32 v38, s[4:5], v36, v36, v41
	v_rcp_f32_e32 v39, v38
	s_nop 0
	v_fma_f32 v40, -v38, v39, 1.0
	v_fmac_f32_e32 v39, v40, v39
	v_div_scale_f32 v40, vcc, v41, v36, v41
	v_mul_f32_e32 v42, v40, v39
	v_fma_f32 v43, -v38, v42, v40
	v_fmac_f32_e32 v42, v43, v39
	v_fma_f32 v38, -v38, v42, v40
	v_div_fmas_f32 v38, v38, v39, v42
	v_div_fixup_f32 v36, v38, v36, v41
	v_pk_mul_f32 v[34:35], v[36:37], v[34:35]
	v_pk_mul_f32 v[40:41], v[44:45], v[64:65] op_sel_hi:[1,0]
	v_cvt_pk_bf16_f32 v33, v34, v35
	global_store_dwordx2 v[48:49], v[32:33], off offset:96
	v_mov_b32_e32 v36, v110
	v_mov_b32_e32 v37, v111
	s_nop 0
	v_mov_b32_e32 v32, v164
	v_mov_b32_e32 v33, v165
	v_mov_b32_e32 v34, v166
	v_mov_b32_e32 v35, v167
	s_waitcnt lgkmcnt(0)
	v_and_b32_e32 v42, 0xffff0000, v36
	v_lshlrev_b32_e32 v36, 16, v36
	v_mul_f32_e32 v38, 0xbfb8aa3b, v36
	v_mul_f32_e32 v39, 0xbfb8aa3b, v42
	v_exp_f32_e32 v38, v38
	v_exp_f32_e32 v39, v39
	v_pk_mul_f32 v[32:33], v[32:33], v[40:41]
	v_pk_add_f32 v[38:39], v[38:39], 1.0 op_sel_hi:[1,0]
	s_nop 0
	v_div_scale_f32 v40, s[4:5], v39, v39, v42
	v_rcp_f32_e32 v41, v40
	s_nop 0
	v_fma_f32 v43, -v40, v41, 1.0
	v_fmac_f32_e32 v41, v43, v41
	v_div_scale_f32 v43, vcc, v42, v39, v42
	v_mul_f32_e32 v44, v43, v41
	v_fma_f32 v45, -v40, v44, v43
	v_fmac_f32_e32 v44, v45, v41
	v_fma_f32 v40, -v40, v44, v43
	v_div_fmas_f32 v40, v40, v41, v44
	v_div_fixup_f32 v39, v40, v39, v42
	v_div_scale_f32 v40, s[4:5], v38, v38, v36
	v_rcp_f32_e32 v41, v40
	s_nop 0
	v_fma_f32 v42, -v40, v41, 1.0
	v_fmac_f32_e32 v41, v42, v41
	v_div_scale_f32 v42, vcc, v36, v38, v36
	v_mul_f32_e32 v43, v42, v41
	v_fma_f32 v44, -v40, v43, v42
	v_fmac_f32_e32 v43, v44, v41
	v_fma_f32 v40, -v40, v43, v42
	v_div_fmas_f32 v40, v40, v41, v43
	v_div_fixup_f32 v38, v40, v38, v36
	v_and_b32_e32 v40, 0xffff0000, v37
	v_lshlrev_b32_e32 v41, 16, v37
	v_mul_f32_e32 v36, 0xbfb8aa3b, v41
	v_mul_f32_e32 v37, 0xbfb8aa3b, v40
	v_exp_f32_e32 v36, v36
	v_exp_f32_e32 v37, v37
	v_pk_mul_f32 v[32:33], v[38:39], v[32:33]
	v_pk_mul_f32 v[38:39], v[46:47], v[64:65] op_sel_hi:[1,0]
	v_cvt_pk_bf16_f32 v32, v32, v33
	v_pk_add_f32 v[36:37], v[36:37], 1.0 op_sel_hi:[1,0]
	v_pk_mul_f32 v[34:35], v[34:35], v[38:39]
	v_div_scale_f32 v38, s[4:5], v37, v37, v40
	v_rcp_f32_e32 v39, v38
	s_nop 0
	v_fma_f32 v42, -v38, v39, 1.0
	v_fmac_f32_e32 v39, v42, v39
	v_div_scale_f32 v42, vcc, v40, v37, v40
	v_mul_f32_e32 v43, v42, v39
	v_fma_f32 v44, -v38, v43, v42
	v_fmac_f32_e32 v43, v44, v39
	v_fma_f32 v38, -v38, v43, v42
	v_div_fmas_f32 v38, v38, v39, v43
	v_div_fixup_f32 v37, v38, v37, v40
	v_div_scale_f32 v38, s[4:5], v36, v36, v41
	v_rcp_f32_e32 v39, v38
	s_nop 0
	v_fma_f32 v40, -v38, v39, 1.0
	v_fmac_f32_e32 v39, v40, v39
	v_div_scale_f32 v40, vcc, v41, v36, v41
	v_mul_f32_e32 v42, v40, v39
	v_fma_f32 v43, -v38, v42, v40
	v_fmac_f32_e32 v42, v43, v39
	v_fma_f32 v38, -v38, v42, v40
	v_div_fmas_f32 v38, v38, v39, v42
	v_div_fixup_f32 v36, v38, v36, v41
	v_pk_mul_f32 v[34:35], v[36:37], v[34:35]
	s_nop 0
	v_cvt_pk_bf16_f32 v33, v34, v35
	global_store_dwordx2 v[48:49], v[32:33], off offset:112
	v_mov_b32_e32 v36, v112
	v_mov_b32_e32 v37, v113
	s_nop 0
	v_mov_b32_e32 v32, v168
	v_mov_b32_e32 v33, v169
	v_mov_b32_e32 v34, v170
	v_mov_b32_e32 v35, v171
	s_waitcnt lgkmcnt(0)
; DI float bf2f(bfr v) { return __uint_as_float(((unsigned)v) << 16); }
; DI unsigned pk2(float a, float b) { f2_t v = {a, b}; bf2_t r = __builtin_convertvector(v, bf2_t); return __builtin_bit_cast(unsigned, r); }
; DI float siluf_(float x) { return x / (1.f + __expf(-x)); }
; DI void attn_unit(const Params& p, int l, int unit, unsigned char* smem) {
;     ...
; #pragma unroll
;   for (int dvb = 0; dvb < 4; ++dvb)
; #pragma unroll
;     for (int g = 0; g < 4; ++g) {
;       const int dv = 32 * dvb + 8 * g + 4 * h;
;       const s16x4 z4 = *(const s16x4*)(P + rowq * PLD + C_DAZ + hd * 128 + dv);
;       const f32x4 gn = *(const f32x4*)(p.da_norm + l * 128 + dv);
;       float y[4];
;       for (int q = 0; q < 4; ++q) y[q] = oacc[dvb][4 * g + q] * rs * gn[q] * siluf_(bf2f((bfr)z4[q]));
;       u32x2 w; w[0] = pk2(y[0], y[1]); w[1] = pk2(y[2], y[3]);
;       *(u32x2*)(YS + rowq * DM + 1536 + hd * 128 + dv) = w;
;     }
	v_and_b32_e32 v40, 0xffff0000, v36
	v_lshlrev_b32_e32 v36, 16, v36
	v_mul_f32_e32 v38, 0xbfb8aa3b, v36
	v_pk_mul_f32 v[16:17], v[32:33], v[16:17]
	v_mul_f32_e32 v32, 0xbfb8aa3b, v40
	v_exp_f32_e32 v38, v38
	v_exp_f32_e32 v39, v32
	v_pk_mul_f32 v[18:19], v[34:35], v[18:19]
	v_pk_add_f32 v[32:33], v[38:39], 1.0 op_sel_hi:[1,0]
	s_nop 0
	v_div_scale_f32 v38, s[4:5], v33, v33, v40
	v_rcp_f32_e32 v39, v38
	s_nop 0
	v_fma_f32 v41, -v38, v39, 1.0
	v_fmac_f32_e32 v39, v41, v39
	v_div_scale_f32 v41, vcc, v40, v33, v40
	v_mul_f32_e32 v42, v41, v39
	v_fma_f32 v43, -v38, v42, v41
	v_fmac_f32_e32 v42, v43, v39
	v_fma_f32 v38, -v38, v42, v41
	v_div_fmas_f32 v38, v38, v39, v42
	v_div_fixup_f32 v33, v38, v33, v40
	v_div_scale_f32 v38, s[4:5], v32, v32, v36
	v_rcp_f32_e32 v39, v38
	s_nop 0
	v_fma_f32 v40, -v38, v39, 1.0
	v_fmac_f32_e32 v39, v40, v39
	v_div_scale_f32 v40, vcc, v36, v32, v36
	v_mul_f32_e32 v41, v40, v39
	v_fma_f32 v42, -v38, v41, v40
	v_fmac_f32_e32 v41, v42, v39
	v_fma_f32 v38, -v38, v41, v40
	v_div_fmas_f32 v38, v38, v39, v41
	v_div_fixup_f32 v32, v38, v32, v36
	v_and_b32_e32 v36, 0xffff0000, v37
	v_lshlrev_b32_e32 v37, 16, v37
	v_pk_mul_f32 v[16:17], v[32:33], v[16:17]
	v_mul_f32_e32 v32, 0xbfb8aa3b, v37
	v_mul_f32_e32 v33, 0xbfb8aa3b, v36
	v_exp_f32_e32 v32, v32
	v_exp_f32_e32 v33, v33
	v_cvt_pk_bf16_f32 v16, v16, v17
	v_pk_add_f32 v[32:33], v[32:33], 1.0 op_sel_hi:[1,0]
	s_nop 0
	v_div_scale_f32 v34, s[4:5], v33, v33, v36
	v_rcp_f32_e32 v35, v34
	s_nop 0
	v_fma_f32 v38, -v34, v35, 1.0
	v_fmac_f32_e32 v35, v38, v35
	v_div_scale_f32 v38, vcc, v36, v33, v36
	v_mul_f32_e32 v39, v38, v35
	v_fma_f32 v40, -v34, v39, v38
	v_fmac_f32_e32 v39, v40, v35
	v_fma_f32 v34, -v34, v39, v38
	v_div_fmas_f32 v34, v34, v35, v39
	v_div_fixup_f32 v33, v34, v33, v36
	v_div_scale_f32 v34, s[4:5], v32, v32, v37
	v_rcp_f32_e32 v35, v34
	s_nop 0
	v_fma_f32 v36, -v34, v35, 1.0
	v_fmac_f32_e32 v35, v36, v35
	v_div_scale_f32 v36, vcc, v37, v32, v37
	v_mul_f32_e32 v38, v36, v35
	v_fma_f32 v39, -v34, v38, v36
	v_fmac_f32_e32 v38, v39, v35
	v_fma_f32 v34, -v34, v38, v36
	v_div_fmas_f32 v34, v34, v35, v38
	v_div_fixup_f32 v32, v34, v32, v37
	v_pk_mul_f32 v[18:19], v[32:33], v[18:19]
	s_nop 0
	v_cvt_pk_bf16_f32 v17, v18, v19
	global_store_dwordx2 v[48:49], v[16:17], off offset:128
	v_mov_b32_e32 v32, v114
	v_mov_b32_e32 v33, v115
	s_nop 0
	v_mov_b32_e32 v16, v172
	v_mov_b32_e32 v17, v173
	v_mov_b32_e32 v18, v174
	v_mov_b32_e32 v19, v175
	s_waitcnt lgkmcnt(0)
	v_and_b32_e32 v36, 0xffff0000, v32
	v_lshlrev_b32_e32 v32, 16, v32
	v_mul_f32_e32 v34, 0xbfb8aa3b, v32
	v_pk_mul_f32 v[16:17], v[16:17], v[20:21]
	v_mul_f32_e32 v20, 0xbfb8aa3b, v36
	v_exp_f32_e32 v34, v34
	v_exp_f32_e32 v35, v20
	v_pk_mul_f32 v[18:19], v[18:19], v[22:23]
	v_pk_add_f32 v[20:21], v[34:35], 1.0 op_sel_hi:[1,0]
	s_nop 0
	v_div_scale_f32 v34, s[4:5], v21, v21, v36
	v_rcp_f32_e32 v35, v34
	s_nop 0
	v_fma_f32 v37, -v34, v35, 1.0
	v_fmac_f32_e32 v35, v37, v35
	v_div_scale_f32 v37, vcc, v36, v21, v36
	v_mul_f32_e32 v38, v37, v35
	v_fma_f32 v39, -v34, v38, v37
	v_fmac_f32_e32 v38, v39, v35
	v_fma_f32 v34, -v34, v38, v37
	v_div_fmas_f32 v34, v34, v35, v38
	v_div_fixup_f32 v21, v34, v21, v36
	v_div_scale_f32 v34, s[4:5], v20, v20, v32
	v_rcp_f32_e32 v35, v34
	s_nop 0
	v_fma_f32 v36, -v34, v35, 1.0
	v_fmac_f32_e32 v35, v36, v35
	v_div_scale_f32 v36, vcc, v32, v20, v32
	v_mul_f32_e32 v37, v36, v35
	v_fma_f32 v38, -v34, v37, v36
	v_fmac_f32_e32 v37, v38, v35
	v_fma_f32 v34, -v34, v37, v36
	v_div_fmas_f32 v34, v34, v35, v37
	v_div_fixup_f32 v20, v34, v20, v32
	v_and_b32_e32 v32, 0xffff0000, v33
	v_lshlrev_b32_e32 v33, 16, v33
	v_pk_mul_f32 v[16:17], v[20:21], v[16:17]
	v_mul_f32_e32 v20, 0xbfb8aa3b, v33
	v_mul_f32_e32 v21, 0xbfb8aa3b, v32
	v_exp_f32_e32 v20, v20
	v_exp_f32_e32 v21, v21
	v_cvt_pk_bf16_f32 v16, v16, v17
	v_pk_add_f32 v[20:21], v[20:21], 1.0 op_sel_hi:[1,0]
	s_nop 0
	v_div_scale_f32 v22, s[4:5], v21, v21, v32
	v_rcp_f32_e32 v23, v22
	s_nop 0
	v_fma_f32 v34, -v22, v23, 1.0
	v_fmac_f32_e32 v23, v34, v23
	v_div_scale_f32 v34, vcc, v32, v21, v32
	v_mul_f32_e32 v35, v34, v23
	v_fma_f32 v36, -v22, v35, v34
	v_fmac_f32_e32 v35, v36, v23
	v_fma_f32 v22, -v22, v35, v34
	v_div_fmas_f32 v22, v22, v23, v35
	v_div_fixup_f32 v21, v22, v21, v32
	v_div_scale_f32 v22, s[4:5], v20, v20, v33
	v_rcp_f32_e32 v23, v22
	s_nop 0
	v_fma_f32 v32, -v22, v23, 1.0
	v_fmac_f32_e32 v23, v32, v23
	v_div_scale_f32 v32, vcc, v33, v20, v33
	v_mul_f32_e32 v34, v32, v23
	v_fma_f32 v35, -v22, v34, v32
	v_fmac_f32_e32 v34, v35, v23
	v_fma_f32 v22, -v22, v34, v32
	v_div_fmas_f32 v22, v22, v23, v34
	v_div_fixup_f32 v20, v22, v20, v33
	v_pk_mul_f32 v[18:19], v[20:21], v[18:19]
	s_nop 0
	v_cvt_pk_bf16_f32 v17, v18, v19
	global_store_dwordx2 v[48:49], v[16:17], off offset:144
	v_mov_b32_e32 v20, v82
	v_mov_b32_e32 v21, v83
	s_nop 0
	v_mov_b32_e32 v16, v176
	v_mov_b32_e32 v17, v177
	v_mov_b32_e32 v18, v178
	v_mov_b32_e32 v19, v179
	s_waitcnt lgkmcnt(0)
; DI float bf2f(bfr v) { return __uint_as_float(((unsigned)v) << 16); }
; DI unsigned pk2(float a, float b) { f2_t v = {a, b}; bf2_t r = __builtin_convertvector(v, bf2_t); return __builtin_bit_cast(unsigned, r); }
; DI float siluf_(float x) { return x / (1.f + __expf(-x)); }
; DI void attn_unit(const Params& p, int l, int unit, unsigned char* smem) {
;     ...
; #pragma unroll
;   for (int dvb = 0; dvb < 4; ++dvb)
; #pragma unroll
;     for (int g = 0; g < 4; ++g) {
;       const int dv = 32 * dvb + 8 * g + 4 * h;
;       const s16x4 z4 = *(const s16x4*)(P + rowq * PLD + C_DAZ + hd * 128 + dv);
;       const f32x4 gn = *(const f32x4*)(p.da_norm + l * 128 + dv);
;       float y[4];
;       for (int q = 0; q < 4; ++q) y[q] = oacc[dvb][4 * g + q] * rs * gn[q] * siluf_(bf2f((bfr)z4[q]));
;       u32x2 w; w[0] = pk2(y[0], y[1]); w[1] = pk2(y[2], y[3]);
;       *(u32x2*)(YS + rowq * DM + 1536 + hd * 128 + dv) = w;
;     }
	v_and_b32_e32 v32, 0xffff0000, v20
	v_lshlrev_b32_e32 v20, 16, v20
	v_mul_f32_e32 v22, 0xbfb8aa3b, v20
	v_mul_f32_e32 v23, 0xbfb8aa3b, v32
	v_exp_f32_e32 v22, v22
	v_exp_f32_e32 v23, v23
	v_pk_mul_f32 v[16:17], v[16:17], v[24:25]
	v_pk_add_f32 v[22:23], v[22:23], 1.0 op_sel_hi:[1,0]
	s_nop 0
	v_div_scale_f32 v24, s[4:5], v23, v23, v32
	v_rcp_f32_e32 v25, v24
	s_nop 0
	v_fma_f32 v33, -v24, v25, 1.0
	v_fmac_f32_e32 v25, v33, v25
	v_div_scale_f32 v33, vcc, v32, v23, v32
	v_mul_f32_e32 v34, v33, v25
	v_fma_f32 v35, -v24, v34, v33
	v_fmac_f32_e32 v34, v35, v25
	v_fma_f32 v24, -v24, v34, v33
	v_div_fmas_f32 v24, v24, v25, v34
	v_div_fixup_f32 v23, v24, v23, v32
	v_div_scale_f32 v24, s[4:5], v22, v22, v20
	v_rcp_f32_e32 v25, v24
	s_nop 0
	v_fma_f32 v32, -v24, v25, 1.0
	v_fmac_f32_e32 v25, v32, v25
	v_div_scale_f32 v32, vcc, v20, v22, v20
	v_mul_f32_e32 v33, v32, v25
	v_fma_f32 v34, -v24, v33, v32
	v_fmac_f32_e32 v33, v34, v25
	v_fma_f32 v24, -v24, v33, v32
	v_div_fmas_f32 v24, v24, v25, v33
	v_div_fixup_f32 v22, v24, v22, v20
	v_and_b32_e32 v24, 0xffff0000, v21
	v_lshlrev_b32_e32 v25, 16, v21
	v_mul_f32_e32 v20, 0xbfb8aa3b, v25
	v_mul_f32_e32 v21, 0xbfb8aa3b, v24
	v_exp_f32_e32 v20, v20
	v_exp_f32_e32 v21, v21
	v_pk_mul_f32 v[16:17], v[22:23], v[16:17]
	v_pk_mul_f32 v[22:23], v[26:27], v[64:65] op_sel_hi:[1,0]
	v_cvt_pk_bf16_f32 v16, v16, v17
	v_pk_add_f32 v[20:21], v[20:21], 1.0 op_sel_hi:[1,0]
	v_pk_mul_f32 v[18:19], v[18:19], v[22:23]
	v_div_scale_f32 v22, s[4:5], v21, v21, v24
	v_rcp_f32_e32 v23, v22
	s_nop 0
	v_fma_f32 v26, -v22, v23, 1.0
	v_fmac_f32_e32 v23, v26, v23
	v_div_scale_f32 v26, vcc, v24, v21, v24
	v_mul_f32_e32 v27, v26, v23
	v_fma_f32 v32, -v22, v27, v26
	v_fmac_f32_e32 v27, v32, v23
	v_fma_f32 v22, -v22, v27, v26
	v_div_fmas_f32 v22, v22, v23, v27
	v_div_fixup_f32 v21, v22, v21, v24
	v_div_scale_f32 v22, s[4:5], v20, v20, v25
	v_rcp_f32_e32 v23, v22
	s_nop 0
	v_fma_f32 v24, -v22, v23, 1.0
	v_fmac_f32_e32 v23, v24, v23
	v_div_scale_f32 v24, vcc, v25, v20, v25
	v_mul_f32_e32 v26, v24, v23
	v_fma_f32 v27, -v22, v26, v24
	v_fmac_f32_e32 v26, v27, v23
	v_fma_f32 v22, -v22, v26, v24
	v_div_fmas_f32 v22, v22, v23, v26
	v_div_fixup_f32 v20, v22, v20, v25
	v_pk_mul_f32 v[18:19], v[20:21], v[18:19]
	v_pk_mul_f32 v[24:25], v[28:29], v[64:65] op_sel_hi:[1,0]
	v_cvt_pk_bf16_f32 v17, v18, v19
	global_store_dwordx2 v[48:49], v[16:17], off offset:160
	v_mov_b32_e32 v20, v84
	v_mov_b32_e32 v21, v85
	s_nop 0
	v_mov_b32_e32 v16, v180
	v_mov_b32_e32 v17, v181
	v_mov_b32_e32 v18, v182
	v_mov_b32_e32 v19, v183
	s_waitcnt lgkmcnt(0)
	v_and_b32_e32 v26, 0xffff0000, v20
	v_lshlrev_b32_e32 v20, 16, v20
	v_mul_f32_e32 v22, 0xbfb8aa3b, v20
	v_mul_f32_e32 v23, 0xbfb8aa3b, v26
	v_exp_f32_e32 v22, v22
	v_exp_f32_e32 v23, v23
	v_pk_mul_f32 v[16:17], v[16:17], v[24:25]
	v_pk_add_f32 v[22:23], v[22:23], 1.0 op_sel_hi:[1,0]
	s_nop 0
	v_div_scale_f32 v24, s[4:5], v23, v23, v26
	v_rcp_f32_e32 v25, v24
	s_nop 0
	v_fma_f32 v27, -v24, v25, 1.0
	v_fmac_f32_e32 v25, v27, v25
	v_div_scale_f32 v27, vcc, v26, v23, v26
	v_mul_f32_e32 v28, v27, v25
	v_fma_f32 v29, -v24, v28, v27
	v_fmac_f32_e32 v28, v29, v25
	v_fma_f32 v24, -v24, v28, v27
	v_div_fmas_f32 v24, v24, v25, v28
	v_div_fixup_f32 v23, v24, v23, v26
	v_div_scale_f32 v24, s[4:5], v22, v22, v20
	v_rcp_f32_e32 v25, v24
	s_nop 0
	v_fma_f32 v26, -v24, v25, 1.0
	v_fmac_f32_e32 v25, v26, v25
	v_div_scale_f32 v26, vcc, v20, v22, v20
	v_mul_f32_e32 v27, v26, v25
	v_fma_f32 v28, -v24, v27, v26
	v_fmac_f32_e32 v27, v28, v25
	v_fma_f32 v24, -v24, v27, v26
	v_div_fmas_f32 v24, v24, v25, v27
	v_div_fixup_f32 v22, v24, v22, v20
	v_and_b32_e32 v24, 0xffff0000, v21
	v_lshlrev_b32_e32 v25, 16, v21
	v_mul_f32_e32 v20, 0xbfb8aa3b, v25
	v_mul_f32_e32 v21, 0xbfb8aa3b, v24
	v_exp_f32_e32 v20, v20
	v_exp_f32_e32 v21, v21
	v_pk_mul_f32 v[16:17], v[22:23], v[16:17]
	v_pk_mul_f32 v[22:23], v[30:31], v[64:65] op_sel_hi:[1,0]
	v_cvt_pk_bf16_f32 v16, v16, v17
	v_pk_add_f32 v[20:21], v[20:21], 1.0 op_sel_hi:[1,0]
	v_pk_mul_f32 v[18:19], v[18:19], v[22:23]
	v_div_scale_f32 v22, s[4:5], v21, v21, v24
	v_rcp_f32_e32 v23, v22
	s_nop 0
	v_fma_f32 v26, -v22, v23, 1.0
	v_fmac_f32_e32 v23, v26, v23
	v_div_scale_f32 v26, vcc, v24, v21, v24
	v_mul_f32_e32 v27, v26, v23
	v_fma_f32 v28, -v22, v27, v26
	v_fmac_f32_e32 v27, v28, v23
	v_fma_f32 v22, -v22, v27, v26
	v_div_fmas_f32 v22, v22, v23, v27
	v_div_fixup_f32 v21, v22, v21, v24
	v_div_scale_f32 v22, s[4:5], v20, v20, v25
	v_rcp_f32_e32 v23, v22
	s_nop 0
	v_fma_f32 v24, -v22, v23, 1.0
	v_fmac_f32_e32 v23, v24, v23
	v_div_scale_f32 v24, vcc, v25, v20, v25
	v_mul_f32_e32 v26, v24, v23
	v_fma_f32 v27, -v22, v26, v24
	v_fmac_f32_e32 v26, v27, v23
	v_fma_f32 v22, -v22, v26, v24
	v_div_fmas_f32 v22, v22, v23, v26
	v_div_fixup_f32 v20, v22, v20, v25
	v_pk_mul_f32 v[18:19], v[20:21], v[18:19]
	s_nop 0
	v_cvt_pk_bf16_f32 v17, v18, v19
	global_store_dwordx2 v[48:49], v[16:17], off offset:176
	v_mov_b32_e32 v20, v86
	v_mov_b32_e32 v21, v87
	s_nop 0
	v_mov_b32_e32 v16, v184
	v_mov_b32_e32 v17, v185
	v_mov_b32_e32 v18, v186
	v_mov_b32_e32 v19, v187
	s_waitcnt lgkmcnt(0)
; DI float bf2f(bfr v) { return __uint_as_float(((unsigned)v) << 16); }
; DI unsigned pk2(float a, float b) { f2_t v = {a, b}; bf2_t r = __builtin_convertvector(v, bf2_t); return __builtin_bit_cast(unsigned, r); }
; DI float siluf_(float x) { return x / (1.f + __expf(-x)); }
; DI void attn_unit(const Params& p, int l, int unit, unsigned char* smem) {
;     ...
; #pragma unroll
;   for (int dvb = 0; dvb < 4; ++dvb)
; #pragma unroll
;     for (int g = 0; g < 4; ++g) {
;       const int dv = 32 * dvb + 8 * g + 4 * h;
;       const s16x4 z4 = *(const s16x4*)(P + rowq * PLD + C_DAZ + hd * 128 + dv);
;       const f32x4 gn = *(const f32x4*)(p.da_norm + l * 128 + dv);
;       float y[4];
;       for (int q = 0; q < 4; ++q) y[q] = oacc[dvb][4 * g + q] * rs * gn[q] * siluf_(bf2f((bfr)z4[q]));
;       u32x2 w; w[0] = pk2(y[0], y[1]); w[1] = pk2(y[2], y[3]);
;       *(u32x2*)(YS + rowq * DM + 1536 + hd * 128 + dv) = w;
;     }
	v_and_b32_e32 v24, 0xffff0000, v20
	v_lshlrev_b32_e32 v20, 16, v20
	v_mul_f32_e32 v22, 0xbfb8aa3b, v20
	v_pk_mul_f32 v[0:1], v[16:17], v[0:1]
	v_mul_f32_e32 v16, 0xbfb8aa3b, v24
	v_exp_f32_e32 v22, v22
	v_exp_f32_e32 v23, v16
	v_pk_mul_f32 v[2:3], v[18:19], v[2:3]
	v_pk_add_f32 v[16:17], v[22:23], 1.0 op_sel_hi:[1,0]
	s_nop 0
	v_div_scale_f32 v22, s[4:5], v17, v17, v24
	v_rcp_f32_e32 v23, v22
	s_nop 0
	v_fma_f32 v25, -v22, v23, 1.0
	v_fmac_f32_e32 v23, v25, v23
	v_div_scale_f32 v25, vcc, v24, v17, v24
	v_mul_f32_e32 v26, v25, v23
	v_fma_f32 v27, -v22, v26, v25
	v_fmac_f32_e32 v26, v27, v23
	v_fma_f32 v22, -v22, v26, v25
	v_div_fmas_f32 v22, v22, v23, v26
	v_div_fixup_f32 v17, v22, v17, v24
	v_div_scale_f32 v22, s[4:5], v16, v16, v20
	v_rcp_f32_e32 v23, v22
	s_nop 0
	v_fma_f32 v24, -v22, v23, 1.0
	v_fmac_f32_e32 v23, v24, v23
	v_div_scale_f32 v24, vcc, v20, v16, v20
	v_mul_f32_e32 v25, v24, v23
	v_fma_f32 v26, -v22, v25, v24
	v_fmac_f32_e32 v25, v26, v23
	v_fma_f32 v22, -v22, v25, v24
	v_div_fmas_f32 v22, v22, v23, v25
	v_div_fixup_f32 v16, v22, v16, v20
	v_and_b32_e32 v20, 0xffff0000, v21
	v_lshlrev_b32_e32 v21, 16, v21
	v_pk_mul_f32 v[0:1], v[16:17], v[0:1]
	v_mul_f32_e32 v16, 0xbfb8aa3b, v21
	v_mul_f32_e32 v17, 0xbfb8aa3b, v20
	v_exp_f32_e32 v16, v16
	v_exp_f32_e32 v17, v17
	v_cvt_pk_bf16_f32 v0, v0, v1
	v_pk_add_f32 v[16:17], v[16:17], 1.0 op_sel_hi:[1,0]
	s_nop 0
	v_div_scale_f32 v18, s[4:5], v17, v17, v20
	v_rcp_f32_e32 v19, v18
	s_nop 0
	v_fma_f32 v22, -v18, v19, 1.0
	v_fmac_f32_e32 v19, v22, v19
	v_div_scale_f32 v22, vcc, v20, v17, v20
	v_mul_f32_e32 v23, v22, v19
	v_fma_f32 v24, -v18, v23, v22
	v_fmac_f32_e32 v23, v24, v19
	v_fma_f32 v18, -v18, v23, v22
	v_div_fmas_f32 v18, v18, v19, v23
	v_div_fixup_f32 v17, v18, v17, v20
	v_div_scale_f32 v18, s[4:5], v16, v16, v21
	v_rcp_f32_e32 v19, v18
	s_nop 0
	v_fma_f32 v20, -v18, v19, 1.0
	v_fmac_f32_e32 v19, v20, v19
	v_div_scale_f32 v20, vcc, v21, v16, v21
	v_mul_f32_e32 v22, v20, v19
	v_fma_f32 v23, -v18, v22, v20
	v_fmac_f32_e32 v22, v23, v19
	v_fma_f32 v18, -v18, v22, v20
	v_div_fmas_f32 v18, v18, v19, v22
	v_div_fixup_f32 v16, v18, v16, v21
	v_pk_mul_f32 v[2:3], v[16:17], v[2:3]
	s_nop 0
	v_cvt_pk_bf16_f32 v1, v2, v3
	global_store_dwordx2 v[48:49], v[0:1], off offset:192
	v_mov_b32_e32 v16, v88
	v_mov_b32_e32 v17, v89
	s_nop 0
	v_mov_b32_e32 v0, v188
	v_mov_b32_e32 v1, v189
	v_mov_b32_e32 v2, v190
	v_mov_b32_e32 v3, v191
	s_waitcnt lgkmcnt(0)
	v_and_b32_e32 v20, 0xffff0000, v16
	v_lshlrev_b32_e32 v16, 16, v16
	v_mul_f32_e32 v18, 0xbfb8aa3b, v16
	v_pk_mul_f32 v[0:1], v[0:1], v[4:5]
	v_mul_f32_e32 v4, 0xbfb8aa3b, v20
	v_exp_f32_e32 v18, v18
	v_exp_f32_e32 v19, v4
	v_pk_mul_f32 v[2:3], v[2:3], v[6:7]
	v_pk_add_f32 v[4:5], v[18:19], 1.0 op_sel_hi:[1,0]
	s_nop 0
	v_div_scale_f32 v18, s[4:5], v5, v5, v20
	v_rcp_f32_e32 v19, v18
	s_nop 0
	v_fma_f32 v21, -v18, v19, 1.0
	v_fmac_f32_e32 v19, v21, v19
	v_div_scale_f32 v21, vcc, v20, v5, v20
	v_mul_f32_e32 v22, v21, v19
	v_fma_f32 v23, -v18, v22, v21
	v_fmac_f32_e32 v22, v23, v19
	v_fma_f32 v18, -v18, v22, v21
	v_div_fmas_f32 v18, v18, v19, v22
	v_div_fixup_f32 v5, v18, v5, v20
	v_div_scale_f32 v18, s[4:5], v4, v4, v16
	v_rcp_f32_e32 v19, v18
	s_nop 0
	v_fma_f32 v20, -v18, v19, 1.0
	v_fmac_f32_e32 v19, v20, v19
	v_div_scale_f32 v20, vcc, v16, v4, v16
	v_mul_f32_e32 v21, v20, v19
	v_fma_f32 v22, -v18, v21, v20
	v_fmac_f32_e32 v21, v22, v19
	v_fma_f32 v18, -v18, v21, v20
	v_div_fmas_f32 v18, v18, v19, v21
	v_div_fixup_f32 v4, v18, v4, v16
	v_and_b32_e32 v16, 0xffff0000, v17
	v_lshlrev_b32_e32 v17, 16, v17
	v_pk_mul_f32 v[0:1], v[4:5], v[0:1]
	v_mul_f32_e32 v4, 0xbfb8aa3b, v17
	v_mul_f32_e32 v5, 0xbfb8aa3b, v16
	v_exp_f32_e32 v4, v4
	v_exp_f32_e32 v5, v5
	v_cvt_pk_bf16_f32 v0, v0, v1
	v_pk_add_f32 v[4:5], v[4:5], 1.0 op_sel_hi:[1,0]
	s_nop 0
	v_div_scale_f32 v6, s[4:5], v5, v5, v16
	v_rcp_f32_e32 v7, v6
	s_nop 0
	v_fma_f32 v18, -v6, v7, 1.0
	v_fmac_f32_e32 v7, v18, v7
	v_div_scale_f32 v18, vcc, v16, v5, v16
	v_mul_f32_e32 v19, v18, v7
	v_fma_f32 v20, -v6, v19, v18
	v_fmac_f32_e32 v19, v20, v7
	v_fma_f32 v6, -v6, v19, v18
	v_div_fmas_f32 v6, v6, v7, v19
	v_div_fixup_f32 v5, v6, v5, v16
	v_div_scale_f32 v6, s[4:5], v4, v4, v17
	v_rcp_f32_e32 v7, v6
	s_nop 0
	v_fma_f32 v16, -v6, v7, 1.0
	v_fmac_f32_e32 v7, v16, v7
	v_div_scale_f32 v16, vcc, v17, v4, v17
	v_mul_f32_e32 v18, v16, v7
	v_fma_f32 v19, -v6, v18, v16
	v_fmac_f32_e32 v18, v19, v7
	v_fma_f32 v6, -v6, v18, v16
	v_div_fmas_f32 v6, v6, v7, v18
	v_div_fixup_f32 v4, v6, v4, v17
	v_pk_mul_f32 v[2:3], v[4:5], v[2:3]
	s_nop 0
	v_cvt_pk_bf16_f32 v1, v2, v3
	global_store_dwordx2 v[48:49], v[0:1], off offset:208
	v_mov_b32_e32 v4, v90
	v_mov_b32_e32 v5, v91
	s_nop 0
	v_mov_b32_e32 v0, v192
	v_mov_b32_e32 v1, v193
	v_mov_b32_e32 v2, v194
	v_mov_b32_e32 v3, v195
	s_waitcnt lgkmcnt(0)
; DI float bf2f(bfr v) { return __uint_as_float(((unsigned)v) << 16); }
; DI unsigned pk2(float a, float b) { f2_t v = {a, b}; bf2_t r = __builtin_convertvector(v, bf2_t); return __builtin_bit_cast(unsigned, r); }
; DI float siluf_(float x) { return x / (1.f + __expf(-x)); }
; DI void attn_unit(const Params& p, int l, int unit, unsigned char* smem) {
;     ...
; #pragma unroll
;   for (int dvb = 0; dvb < 4; ++dvb)
; #pragma unroll
;     for (int g = 0; g < 4; ++g) {
;       const int dv = 32 * dvb + 8 * g + 4 * h;
;       const s16x4 z4 = *(const s16x4*)(P + rowq * PLD + C_DAZ + hd * 128 + dv);
;       const f32x4 gn = *(const f32x4*)(p.da_norm + l * 128 + dv);
;       float y[4];
;       for (int q = 0; q < 4; ++q) y[q] = oacc[dvb][4 * g + q] * rs * gn[q] * siluf_(bf2f((bfr)z4[q]));
;       u32x2 w; w[0] = pk2(y[0], y[1]); w[1] = pk2(y[2], y[3]);
;       *(u32x2*)(YS + rowq * DM + 1536 + hd * 128 + dv) = w;
;     }
	v_and_b32_e32 v16, 0xffff0000, v4
	v_lshlrev_b32_e32 v4, 16, v4
	v_mul_f32_e32 v6, 0xbfb8aa3b, v4
	v_mul_f32_e32 v7, 0xbfb8aa3b, v16
	v_exp_f32_e32 v6, v6
	v_exp_f32_e32 v7, v7
	v_pk_mul_f32 v[0:1], v[0:1], v[8:9]
	v_pk_add_f32 v[6:7], v[6:7], 1.0 op_sel_hi:[1,0]
	s_nop 0
	v_div_scale_f32 v8, s[4:5], v7, v7, v16
	v_rcp_f32_e32 v9, v8
	s_nop 0
	v_fma_f32 v17, -v8, v9, 1.0
	v_fmac_f32_e32 v9, v17, v9
	v_div_scale_f32 v17, vcc, v16, v7, v16
	v_mul_f32_e32 v18, v17, v9
	v_fma_f32 v19, -v8, v18, v17
	v_fmac_f32_e32 v18, v19, v9
	v_fma_f32 v8, -v8, v18, v17
	v_div_fmas_f32 v8, v8, v9, v18
	v_div_fixup_f32 v7, v8, v7, v16
	v_div_scale_f32 v8, s[4:5], v6, v6, v4
	v_rcp_f32_e32 v9, v8
	s_nop 0
	v_fma_f32 v16, -v8, v9, 1.0
	v_fmac_f32_e32 v9, v16, v9
	v_div_scale_f32 v16, vcc, v4, v6, v4
	v_mul_f32_e32 v17, v16, v9
	v_fma_f32 v18, -v8, v17, v16
	v_fmac_f32_e32 v17, v18, v9
	v_fma_f32 v8, -v8, v17, v16
	v_div_fmas_f32 v8, v8, v9, v17
	v_div_fixup_f32 v6, v8, v6, v4
	v_and_b32_e32 v8, 0xffff0000, v5
	v_lshlrev_b32_e32 v9, 16, v5
	v_mul_f32_e32 v4, 0xbfb8aa3b, v9
	v_mul_f32_e32 v5, 0xbfb8aa3b, v8
	v_exp_f32_e32 v4, v4
	v_exp_f32_e32 v5, v5
	v_pk_mul_f32 v[0:1], v[6:7], v[0:1]
	v_pk_mul_f32 v[6:7], v[10:11], v[64:65] op_sel_hi:[1,0]
	v_cvt_pk_bf16_f32 v0, v0, v1
	v_pk_add_f32 v[4:5], v[4:5], 1.0 op_sel_hi:[1,0]
	v_pk_mul_f32 v[2:3], v[2:3], v[6:7]
	v_div_scale_f32 v6, s[4:5], v5, v5, v8
	v_rcp_f32_e32 v7, v6
	s_nop 0
	v_fma_f32 v10, -v6, v7, 1.0
	v_fmac_f32_e32 v7, v10, v7
	v_div_scale_f32 v10, vcc, v8, v5, v8
	v_mul_f32_e32 v11, v10, v7
	v_fma_f32 v16, -v6, v11, v10
	v_fmac_f32_e32 v11, v16, v7
	v_fma_f32 v6, -v6, v11, v10
	v_div_fmas_f32 v6, v6, v7, v11
	v_div_fixup_f32 v5, v6, v5, v8
	v_div_scale_f32 v6, s[4:5], v4, v4, v9
	v_rcp_f32_e32 v7, v6
	s_nop 0
	v_fma_f32 v8, -v6, v7, 1.0
	v_fmac_f32_e32 v7, v8, v7
	v_div_scale_f32 v8, vcc, v9, v4, v9
	v_mul_f32_e32 v10, v8, v7
	v_fma_f32 v11, -v6, v10, v8
	v_fmac_f32_e32 v10, v11, v7
	v_fma_f32 v6, -v6, v10, v8
	v_div_fmas_f32 v6, v6, v7, v10
	v_div_fixup_f32 v4, v6, v4, v9
	v_pk_mul_f32 v[2:3], v[4:5], v[2:3]
	v_pk_mul_f32 v[8:9], v[12:13], v[64:65] op_sel_hi:[1,0]
	v_cvt_pk_bf16_f32 v1, v2, v3
	global_store_dwordx2 v[48:49], v[0:1], off offset:224
	v_mov_b32_e32 v0, v92
	v_mov_b32_e32 v1, v93
	s_nop 0
	v_mov_b32_e32 v2, v196
	v_mov_b32_e32 v3, v197
	v_mov_b32_e32 v4, v198
	v_mov_b32_e32 v5, v199
	s_waitcnt lgkmcnt(0)
	v_and_b32_e32 v10, 0xffff0000, v0
	v_lshlrev_b32_e32 v0, 16, v0
	v_mul_f32_e32 v6, 0xbfb8aa3b, v0
	v_mul_f32_e32 v7, 0xbfb8aa3b, v10
	v_exp_f32_e32 v6, v6
	v_exp_f32_e32 v7, v7
	v_pk_mul_f32 v[2:3], v[2:3], v[8:9]
	v_pk_add_f32 v[6:7], v[6:7], 1.0 op_sel_hi:[1,0]
	s_nop 0
	v_div_scale_f32 v8, s[4:5], v7, v7, v10
	v_rcp_f32_e32 v9, v8
	s_nop 0
	v_fma_f32 v11, -v8, v9, 1.0
	v_fmac_f32_e32 v9, v11, v9
	v_div_scale_f32 v11, vcc, v10, v7, v10
	v_mul_f32_e32 v12, v11, v9
	v_fma_f32 v13, -v8, v12, v11
	v_fmac_f32_e32 v12, v13, v9
	v_fma_f32 v8, -v8, v12, v11
	v_div_fmas_f32 v8, v8, v9, v12
	v_div_fixup_f32 v7, v8, v7, v10
	v_div_scale_f32 v8, s[4:5], v6, v6, v0
	v_rcp_f32_e32 v9, v8
	s_nop 0
	v_fma_f32 v10, -v8, v9, 1.0
	v_fmac_f32_e32 v9, v10, v9
	v_div_scale_f32 v10, vcc, v0, v6, v0
	v_mul_f32_e32 v11, v10, v9
	v_fma_f32 v12, -v8, v11, v10
	v_fmac_f32_e32 v11, v12, v9
	v_fma_f32 v8, -v8, v11, v10
	v_div_fmas_f32 v8, v8, v9, v11
	v_div_fixup_f32 v6, v8, v6, v0
	v_and_b32_e32 v8, 0xffff0000, v1
	v_lshlrev_b32_e32 v9, 16, v1
	v_mul_f32_e32 v0, 0xbfb8aa3b, v9
	v_mul_f32_e32 v1, 0xbfb8aa3b, v8
	v_exp_f32_e32 v0, v0
	v_exp_f32_e32 v1, v1
	v_pk_mul_f32 v[2:3], v[6:7], v[2:3]
	v_pk_mul_f32 v[6:7], v[14:15], v[64:65] op_sel_hi:[1,0]
	v_cvt_pk_bf16_f32 v2, v2, v3
	v_pk_add_f32 v[0:1], v[0:1], 1.0 op_sel_hi:[1,0]
	v_pk_mul_f32 v[4:5], v[4:5], v[6:7]
	v_div_scale_f32 v6, s[4:5], v1, v1, v8
	v_rcp_f32_e32 v7, v6
	s_nop 0
	v_fma_f32 v10, -v6, v7, 1.0
	v_fmac_f32_e32 v7, v10, v7
	v_div_scale_f32 v10, vcc, v8, v1, v8
	v_mul_f32_e32 v11, v10, v7
	v_fma_f32 v12, -v6, v11, v10
	v_fmac_f32_e32 v11, v12, v7
	v_fma_f32 v6, -v6, v11, v10
	v_div_fmas_f32 v6, v6, v7, v11
	v_div_fixup_f32 v1, v6, v1, v8
	v_div_scale_f32 v6, s[4:5], v0, v0, v9
	v_rcp_f32_e32 v7, v6
	s_nop 0
	v_fma_f32 v8, -v6, v7, 1.0
	v_fmac_f32_e32 v7, v8, v7
	v_div_scale_f32 v8, vcc, v9, v0, v9
	v_mul_f32_e32 v10, v8, v7
	v_fma_f32 v11, -v6, v10, v8
	v_fmac_f32_e32 v10, v11, v7
	v_fma_f32 v6, -v6, v10, v8
	v_div_fmas_f32 v6, v6, v7, v10
	v_div_fixup_f32 v0, v6, v0, v9
	v_pk_mul_f32 v[0:1], v[0:1], v[4:5]
	s_nop 0
	v_cvt_pk_bf16_f32 v3, v0, v1
	global_store_dwordx2 v[48:49], v[2:3], off offset:240
	s_branch .LBB0_309

; #define MFMA(a, b, c) __builtin_amdgcn_mfma_f32_32x32x16_bf16((a), (b), (c), 0, 0, 0)
; DI f32x16 zero16() { f32x16 z; for (int i = 0; i < 16; ++i) z[i] = 0.f; return z; }
; DI void attn_unit(const Params& p, int l, int unit, unsigned char* smem) {
;     ...
;   for (int kt = 0; kt < ntile; ++kt) {
;     __syncthreads();
; #pragma unroll
;     for (int i = 0; i < 4; ++i) {
;       const int c = tid + 256 * i;
;       { const int key = c >> 4, kc = c & 15; *(u32x4*)(sK + key * 136 + 8 * kc) = rk[i]; }
;       { const int dv = c >> 3, kc = c & 7; *(u32x4*)(sVT + dv * 72 + 8 * kc) = rv[i]; }
;     }
;     __syncthreads();
;     if (kt + 1 < ntile) {
; #pragma unroll
;       for (int i = 0; i < 4; ++i) {
;         const int c = tid + 256 * i;
;         { const int key = c >> 4, kc = c & 15; rk[i] = *(const u32x4*)(Kbase + (size_t)((kt + 1) * 64 + key) * PLD + 8 * kc); }
;         { const int dv = c >> 3, kc = c & 7; rv[i] = *(const u32x4*)(VT + (size_t)dv * SP + (kt + 1) * 64 + 8 * kc); }
;       }
;     }
; #pragma unroll
;     for (int kb = 0; kb < 2; ++kb) {
;       f32x16 s0 = zero16(), s1 = zero16();
; #pragma unroll
;       for (int s = 0; s < 4; ++s) {
;         s0 = MFMA(ld16(sK + (32 * kb + l31) * 136 + 16 * s + 8 * h), qf[0][s], s0);
;         s1 = MFMA(ld16(sK + (32 * kb + l31) * 136 + 64 + 16 * s + 8 * h), qf[1][s], s1);
;       }
; #pragma unroll
;       for (int r = 0; r < 16; ++r) s0[r] = __builtin_amdgcn_exp2f(fmaf(s0[r], cs, nm[0])) * sc[0] - __builtin_amdgcn_exp2f(fmaf(s1[r], cs, nm[1])) * sc[1];
;       const bf16x8 p0 = pack8<0>(s0), p1 = pack8<1>(s0);
; #pragma unroll
;       for (int dvb = 0; dvb < 4; ++dvb) {
;         oacc[dvb] = MFMA(ld2x8(sVT + (32 * dvb + l31) * 72 + 32 * kb + 4 * h), p0, oacc[dvb]);
;         oacc[dvb] = MFMA(ld2x8(sVT + (32 * dvb + l31) * 72 + 32 * kb + 16 + 4 * h), p1, oacc[dvb]);
;       }
;     }
.LBB0_524:
	v_lshl_add_u64 v[64:65], s[10:11], 0, v[174:175]
	s_waitcnt lgkmcnt(0)
	s_barrier
	s_waitcnt vmcnt(0)
	ds_write_b128 v187, v[128:131]
	ds_write_b128 v203, v[132:135] offset:17408
	ds_write_b128 v186, v[136:139]
	ds_write_b128 v202, v[140:143] offset:17408
	ds_write_b128 v185, v[144:147]
	ds_write_b128 v201, v[148:151] offset:17408
	ds_write_b128 v184, v[152:155]
	ds_write_b128 v200, v[156:159] offset:17408
	s_waitcnt lgkmcnt(0)
	s_barrier
	global_load_dwordx4 v[128:131], v[64:65], off
	v_lshl_add_u64 v[64:65], s[10:11], 0, v[182:183]
	global_load_dwordx4 v[132:135], v[64:65], off
	v_lshl_add_u64 v[64:65], s[10:11], 0, v[172:173]
	global_load_dwordx4 v[136:139], v[64:65], off
	v_lshl_add_u64 v[64:65], s[10:11], 0, v[180:181]
	global_load_dwordx4 v[140:143], v[64:65], off
	v_lshl_add_u64 v[64:65], s[10:11], 0, v[170:171]
	global_load_dwordx4 v[144:147], v[64:65], off
	v_lshl_add_u64 v[64:65], s[10:11], 0, v[178:179]
	global_load_dwordx4 v[148:151], v[64:65], off
	v_lshl_add_u64 v[64:65], s[10:11], 0, v[168:169]
	global_load_dwordx4 v[152:155], v[64:65], off
	v_lshl_add_u64 v[64:65], s[10:11], 0, v[176:177]
	global_load_dwordx4 v[156:159], v[64:65], off
	ds_read_b128 v[212:215], v197
	ds_read_b128 v[224:227], v197 offset:32
	ds_read_b128 v[228:231], v197 offset:128
	ds_read_b128 v[236:239], v197 offset:160
	ds_read_b128 v[246:249], v197 offset:64
	s_waitcnt lgkmcnt(4)
	v_mfma_f32_32x32x16_bf16 v[64:79], v[212:215], v[120:123], 0
	v_add_u32_e32 v193, 0x4000, v198
	v_add_u32_e32 v196, 0x4000, v199
	v_add_u32_e32 v195, 0x6800, v198
	v_add_u32_e32 v194, 0x7800, v198
	s_add_i32 s20, s20, -1
	v_lshl_add_u64 v[168:169], v[168:169], 0, s[52:53]
	ds_read_b128 v[250:253], v197 offset:192
	s_waitcnt lgkmcnt(4)
	v_mfma_f32_32x32x16_bf16 v[64:79], v[224:227], v[116:119], v[64:79]
	v_lshl_add_u64 v[170:171], v[170:171], 0, s[52:53]
	v_lshl_add_u64 v[172:173], v[172:173], 0, s[52:53]
	v_lshl_add_u64 v[174:175], v[174:175], 0, s[52:53]
	v_lshl_add_u64 v[176:177], v[176:177], 0, s[80:81]
	v_lshl_add_u64 v[178:179], v[178:179], 0, s[80:81]
	v_lshl_add_u64 v[180:181], v[180:181], 0, s[80:81]
	ds_read_b128 v[212:215], v197 offset:96
	s_waitcnt lgkmcnt(4)
	v_mfma_f32_32x32x16_bf16 v[80:95], v[228:231], v[124:127], 0
	v_lshl_add_u64 v[182:183], v[182:183], 0, s[80:81]
	s_cmp_lg_u32 s20, 0
	ds_read_b128 v[224:227], v197 offset:224
	s_waitcnt lgkmcnt(4)
	v_mfma_f32_32x32x16_bf16 v[80:95], v[236:239], v[112:115], v[80:95]
	ds_read2_b64 v[228:231], v193 offset0:128 offset1:130
	s_waitcnt lgkmcnt(4)
	v_mfma_f32_32x32x16_bf16 v[64:79], v[246:249], v[104:107], v[64:79]
	ds_read2_b64 v[236:239], v193 offset0:132 offset1:134
	s_waitcnt lgkmcnt(4)
	v_mfma_f32_32x32x16_bf16 v[80:95], v[250:253], v[108:111], v[80:95]
	ds_read2_b64 v[246:249], v196 offset0:128 offset1:130
	s_waitcnt lgkmcnt(4)
	v_mfma_f32_32x32x16_bf16 v[64:79], v[212:215], v[100:103], v[64:79]
	ds_read2_b64 v[250:253], v195 offset1:2
	s_waitcnt lgkmcnt(4)
	v_mfma_f32_32x32x16_bf16 v[80:95], v[224:227], v[96:99], v[80:95]
	s_nop 8
	v_fmamk_f32 v64, v64, 0x3e38aa3b, v190
	v_fmamk_f32 v65, v65, 0x3e38aa3b, v190
	v_exp_f32_e32 v64, v64
	v_exp_f32_e32 v65, v65
	v_fmamk_f32 v66, v66, 0x3e38aa3b, v190
	v_fmamk_f32 v67, v67, 0x3e38aa3b, v190
	v_exp_f32_e32 v66, v66
	v_fmamk_f32 v80, v80, 0x3e38aa3b, v191
	v_fmamk_f32 v81, v81, 0x3e38aa3b, v191
	v_exp_f32_e32 v80, v80
	v_exp_f32_e32 v81, v81
	v_exp_f32_e32 v67, v67
	v_fmamk_f32 v68, v68, 0x3e38aa3b, v190
	v_fmamk_f32 v69, v69, 0x3e38aa3b, v190
	v_pk_mul_f32 v[80:81], v[166:167], v[80:81]
	v_exp_f32_e32 v68, v68
	v_pk_fma_f32 v[64:65], v[164:165], v[64:65], v[80:81] neg_lo:[0,0,1] neg_hi:[0,0,1]
	v_fmamk_f32 v80, v82, 0x3e38aa3b, v191
	v_fmamk_f32 v81, v83, 0x3e38aa3b, v191
	v_exp_f32_e32 v80, v80
	v_exp_f32_e32 v81, v81
	v_exp_f32_e32 v69, v69
	v_fmamk_f32 v70, v70, 0x3e38aa3b, v190
	v_fmamk_f32 v71, v71, 0x3e38aa3b, v190
	v_pk_mul_f32 v[80:81], v[166:167], v[80:81]
	v_exp_f32_e32 v70, v70
	v_pk_fma_f32 v[66:67], v[164:165], v[66:67], v[80:81] neg_lo:[0,0,1] neg_hi:[0,0,1]
	v_fmamk_f32 v80, v84, 0x3e38aa3b, v191
	v_fmamk_f32 v81, v85, 0x3e38aa3b, v191
	v_exp_f32_e32 v80, v80
	v_exp_f32_e32 v81, v81
	v_exp_f32_e32 v71, v71
	v_fmamk_f32 v72, v72, 0x3e38aa3b, v190
	v_fmamk_f32 v73, v73, 0x3e38aa3b, v190
	v_pk_mul_f32 v[80:81], v[166:167], v[80:81]
	v_exp_f32_e32 v72, v72
	v_pk_fma_f32 v[68:69], v[164:165], v[68:69], v[80:81] neg_lo:[0,0,1] neg_hi:[0,0,1]
	v_fmamk_f32 v80, v86, 0x3e38aa3b, v191
	v_fmamk_f32 v81, v87, 0x3e38aa3b, v191
	v_exp_f32_e32 v80, v80
	v_exp_f32_e32 v81, v81
	v_exp_f32_e32 v73, v73
	v_fmamk_f32 v74, v74, 0x3e38aa3b, v190
	v_fmamk_f32 v75, v75, 0x3e38aa3b, v190
	v_pk_mul_f32 v[80:81], v[166:167], v[80:81]
	v_exp_f32_e32 v74, v74
	v_pk_fma_f32 v[70:71], v[164:165], v[70:71], v[80:81] neg_lo:[0,0,1] neg_hi:[0,0,1]
	v_fmamk_f32 v80, v88, 0x3e38aa3b, v191
	v_fmamk_f32 v81, v89, 0x3e38aa3b, v191
	v_exp_f32_e32 v80, v80
	v_exp_f32_e32 v81, v81
	v_exp_f32_e32 v75, v75
	v_fmamk_f32 v76, v76, 0x3e38aa3b, v190
	v_fmamk_f32 v77, v77, 0x3e38aa3b, v190
	v_pk_mul_f32 v[80:81], v[166:167], v[80:81]
	v_exp_f32_e32 v76, v76
	v_pk_fma_f32 v[72:73], v[164:165], v[72:73], v[80:81] neg_lo:[0,0,1] neg_hi:[0,0,1]
	v_fmamk_f32 v80, v90, 0x3e38aa3b, v191
	v_fmamk_f32 v81, v91, 0x3e38aa3b, v191
	v_exp_f32_e32 v80, v80
	v_exp_f32_e32 v81, v81
	v_exp_f32_e32 v77, v77
	v_fmamk_f32 v78, v78, 0x3e38aa3b, v190
	v_fmamk_f32 v79, v79, 0x3e38aa3b, v190
	v_pk_mul_f32 v[80:81], v[166:167], v[80:81]
	v_exp_f32_e32 v78, v78
	v_pk_fma_f32 v[74:75], v[164:165], v[74:75], v[80:81] neg_lo:[0,0,1] neg_hi:[0,0,1]
	v_fmamk_f32 v80, v92, 0x3e38aa3b, v191
	v_fmamk_f32 v81, v93, 0x3e38aa3b, v191
	v_exp_f32_e32 v80, v80
	v_exp_f32_e32 v81, v81
	v_exp_f32_e32 v79, v79
	v_cvt_pk_bf16_f32 v64, v64, v65
	v_cvt_pk_bf16_f32 v65, v66, v67
	v_pk_mul_f32 v[80:81], v[166:167], v[80:81]
	v_cvt_pk_bf16_f32 v66, v68, v69
	v_pk_fma_f32 v[76:77], v[164:165], v[76:77], v[80:81] neg_lo:[0,0,1] neg_hi:[0,0,1]
	v_fmamk_f32 v80, v94, 0x3e38aa3b, v191
	v_fmamk_f32 v81, v95, 0x3e38aa3b, v191
	v_exp_f32_e32 v80, v80
	v_exp_f32_e32 v81, v81
	v_cvt_pk_bf16_f32 v67, v70, v71
	v_cvt_pk_bf16_f32 v68, v72, v73
	v_cvt_pk_bf16_f32 v69, v74, v75
	v_pk_mul_f32 v[80:81], v[166:167], v[80:81]
	v_cvt_pk_bf16_f32 v70, v76, v77
	v_pk_fma_f32 v[78:79], v[164:165], v[78:79], v[80:81] neg_lo:[0,0,1] neg_hi:[0,0,1]
	s_nop 0
	v_cvt_pk_bf16_f32 v71, v78, v79
	ds_read2_b64 v[212:215], v195 offset0:4 offset1:6
	s_waitcnt lgkmcnt(4)
; #define MFMA(a, b, c) __builtin_amdgcn_mfma_f32_32x32x16_bf16((a), (b), (c), 0, 0, 0)
; DI f32x16 zero16() { f32x16 z; for (int i = 0; i < 16; ++i) z[i] = 0.f; return z; }
; DI void attn_unit(const Params& p, int l, int unit, unsigned char* smem) {
;     ...
; #pragma unroll
;     for (int kb = 0; kb < 2; ++kb) {
;       f32x16 s0 = zero16(), s1 = zero16();
; #pragma unroll
;       for (int s = 0; s < 4; ++s) {
;         s0 = MFMA(ld16(sK + (32 * kb + l31) * 136 + 16 * s + 8 * h), qf[0][s], s0);
;         s1 = MFMA(ld16(sK + (32 * kb + l31) * 136 + 64 + 16 * s + 8 * h), qf[1][s], s1);
;       }
; #pragma unroll
;       for (int r = 0; r < 16; ++r) s0[r] = __builtin_amdgcn_exp2f(fmaf(s0[r], cs, nm[0])) * sc[0] - __builtin_amdgcn_exp2f(fmaf(s1[r], cs, nm[1])) * sc[1];
;       const bf16x8 p0 = pack8<0>(s0), p1 = pack8<1>(s0);
; #pragma unroll
;       for (int dvb = 0; dvb < 4; ++dvb) {
;         oacc[dvb] = MFMA(ld2x8(sVT + (32 * dvb + l31) * 72 + 32 * kb + 4 * h), p0, oacc[dvb]);
;         oacc[dvb] = MFMA(ld2x8(sVT + (32 * dvb + l31) * 72 + 32 * kb + 16 + 4 * h), p1, oacc[dvb]);
;       }
	v_mfma_f32_32x32x16_bf16 v[48:63], v[228:231], v[64:67], v[48:63]
	ds_read2_b64 v[224:227], v194 offset0:64 offset1:66
	s_waitcnt lgkmcnt(4)
	v_mfma_f32_32x32x16_bf16 v[48:63], v[236:239], v[68:71], v[48:63]
	ds_read2_b64 v[228:231], v194 offset0:68 offset1:70
	s_waitcnt lgkmcnt(4)
	v_mfma_f32_32x32x16_bf16 v[32:47], v[246:249], v[64:67], v[32:47]
	ds_read2_b64 v[236:239], v196 offset0:132 offset1:134
	s_waitcnt lgkmcnt(4)
	v_mfma_f32_32x32x16_bf16 v[16:31], v[250:253], v[64:67], v[16:31]
	ds_read_b128 v[246:249], v192
	s_waitcnt lgkmcnt(4)
	v_mfma_f32_32x32x16_bf16 v[16:31], v[212:215], v[68:71], v[16:31]
	ds_read_b128 v[250:253], v192 offset:32
	s_waitcnt lgkmcnt(4)
	v_mfma_f32_32x32x16_bf16 v[0:15], v[224:227], v[64:67], v[0:15]
	ds_read_b128 v[212:215], v192 offset:128
	s_waitcnt lgkmcnt(4)
	v_mfma_f32_32x32x16_bf16 v[0:15], v[228:231], v[68:71], v[0:15]
	ds_read_b128 v[224:227], v192 offset:160
	s_waitcnt lgkmcnt(4)
	v_mfma_f32_32x32x16_bf16 v[32:47], v[236:239], v[68:71], v[32:47]
	ds_read_b128 v[228:231], v192 offset:64
	s_waitcnt lgkmcnt(4)
	v_mfma_f32_32x32x16_bf16 v[64:79], v[246:249], v[120:123], 0
	ds_read_b128 v[236:239], v192 offset:192
	s_waitcnt lgkmcnt(4)
	v_mfma_f32_32x32x16_bf16 v[64:79], v[250:253], v[116:119], v[64:79]
	ds_read_b128 v[246:249], v192 offset:96
	s_waitcnt lgkmcnt(4)
	v_mfma_f32_32x32x16_bf16 v[80:95], v[212:215], v[124:127], 0
	ds_read_b128 v[250:253], v192 offset:224
	s_waitcnt lgkmcnt(4)
	v_mfma_f32_32x32x16_bf16 v[80:95], v[224:227], v[112:115], v[80:95]
	ds_read2_b64 v[212:215], v193 offset0:136 offset1:138
	s_waitcnt lgkmcnt(4)
	v_mfma_f32_32x32x16_bf16 v[64:79], v[228:231], v[104:107], v[64:79]
	ds_read2_b64 v[224:227], v193 offset0:140 offset1:142
	s_waitcnt lgkmcnt(4)
	v_mfma_f32_32x32x16_bf16 v[80:95], v[236:239], v[108:111], v[80:95]
	ds_read2_b64 v[228:231], v196 offset0:136 offset1:138
	s_waitcnt lgkmcnt(4)
	v_mfma_f32_32x32x16_bf16 v[64:79], v[246:249], v[100:103], v[64:79]
	ds_read2_b64 v[236:239], v195 offset0:8 offset1:10
	s_waitcnt lgkmcnt(4)
	v_mfma_f32_32x32x16_bf16 v[80:95], v[250:253], v[96:99], v[80:95]
	s_nop 8
	v_fmamk_f32 v64, v64, 0x3e38aa3b, v190
	v_fmamk_f32 v65, v65, 0x3e38aa3b, v190
	v_exp_f32_e32 v64, v64
	v_exp_f32_e32 v65, v65
	v_fmamk_f32 v66, v66, 0x3e38aa3b, v190
	v_fmamk_f32 v67, v67, 0x3e38aa3b, v190
	v_exp_f32_e32 v66, v66
	v_fmamk_f32 v80, v80, 0x3e38aa3b, v191
	v_fmamk_f32 v81, v81, 0x3e38aa3b, v191
	v_exp_f32_e32 v80, v80
	v_exp_f32_e32 v81, v81
	v_exp_f32_e32 v67, v67
	v_fmamk_f32 v68, v68, 0x3e38aa3b, v190
	v_fmamk_f32 v69, v69, 0x3e38aa3b, v190
	v_pk_mul_f32 v[80:81], v[166:167], v[80:81]
	v_exp_f32_e32 v68, v68
	v_pk_fma_f32 v[64:65], v[164:165], v[64:65], v[80:81] neg_lo:[0,0,1] neg_hi:[0,0,1]
	v_fmamk_f32 v80, v82, 0x3e38aa3b, v191
	v_fmamk_f32 v81, v83, 0x3e38aa3b, v191
	v_exp_f32_e32 v80, v80
	v_exp_f32_e32 v81, v81
	v_exp_f32_e32 v69, v69
	v_fmamk_f32 v70, v70, 0x3e38aa3b, v190
	v_fmamk_f32 v71, v71, 0x3e38aa3b, v190
	v_pk_mul_f32 v[80:81], v[166:167], v[80:81]
	v_exp_f32_e32 v70, v70
	v_pk_fma_f32 v[66:67], v[164:165], v[66:67], v[80:81] neg_lo:[0,0,1] neg_hi:[0,0,1]
	v_fmamk_f32 v80, v84, 0x3e38aa3b, v191
	v_fmamk_f32 v81, v85, 0x3e38aa3b, v191
	v_exp_f32_e32 v80, v80
	v_exp_f32_e32 v81, v81
	v_exp_f32_e32 v71, v71
	v_fmamk_f32 v72, v72, 0x3e38aa3b, v190
	v_fmamk_f32 v73, v73, 0x3e38aa3b, v190
	v_pk_mul_f32 v[80:81], v[166:167], v[80:81]
	v_exp_f32_e32 v72, v72
	v_pk_fma_f32 v[68:69], v[164:165], v[68:69], v[80:81] neg_lo:[0,0,1] neg_hi:[0,0,1]
	v_fmamk_f32 v80, v86, 0x3e38aa3b, v191
	v_fmamk_f32 v81, v87, 0x3e38aa3b, v191
	v_exp_f32_e32 v80, v80
	v_exp_f32_e32 v81, v81
	v_exp_f32_e32 v73, v73
	v_fmamk_f32 v74, v74, 0x3e38aa3b, v190
	v_fmamk_f32 v75, v75, 0x3e38aa3b, v190
	v_pk_mul_f32 v[80:81], v[166:167], v[80:81]
	v_exp_f32_e32 v74, v74
	v_pk_fma_f32 v[70:71], v[164:165], v[70:71], v[80:81] neg_lo:[0,0,1] neg_hi:[0,0,1]
	v_fmamk_f32 v80, v88, 0x3e38aa3b, v191
	v_fmamk_f32 v81, v89, 0x3e38aa3b, v191
	v_exp_f32_e32 v80, v80
	v_exp_f32_e32 v81, v81
	v_exp_f32_e32 v75, v75
	v_cvt_pk_bf16_f32 v64, v64, v65
	v_cvt_pk_bf16_f32 v65, v66, v67
	v_pk_mul_f32 v[80:81], v[166:167], v[80:81]
	v_cvt_pk_bf16_f32 v66, v68, v69
	v_pk_fma_f32 v[72:73], v[164:165], v[72:73], v[80:81] neg_lo:[0,0,1] neg_hi:[0,0,1]
	v_fmamk_f32 v80, v90, 0x3e38aa3b, v191
	v_fmamk_f32 v81, v91, 0x3e38aa3b, v191
	v_exp_f32_e32 v80, v80
	v_exp_f32_e32 v81, v81
	v_cvt_pk_bf16_f32 v68, v72, v73
	v_fmamk_f32 v76, v76, 0x3e38aa3b, v190
	v_fmamk_f32 v77, v77, 0x3e38aa3b, v190
	v_pk_mul_f32 v[80:81], v[166:167], v[80:81]
	v_exp_f32_e32 v76, v76
	v_pk_fma_f32 v[74:75], v[164:165], v[74:75], v[80:81] neg_lo:[0,0,1] neg_hi:[0,0,1]
	v_fmamk_f32 v80, v92, 0x3e38aa3b, v191
	v_cvt_pk_bf16_f32 v69, v74, v75
	v_fmamk_f32 v81, v93, 0x3e38aa3b, v191
	v_exp_f32_e32 v80, v80
	v_exp_f32_e32 v81, v81
	v_exp_f32_e32 v77, v77
	v_cvt_pk_bf16_f32 v67, v70, v71
	v_fmamk_f32 v78, v78, 0x3e38aa3b, v190
	v_pk_mul_f32 v[80:81], v[166:167], v[80:81]
	ds_read2_b64 v[246:249], v195 offset0:12 offset1:14
	s_waitcnt lgkmcnt(4)
	v_mfma_f32_32x32x16_bf16 v[48:63], v[212:215], v[64:67], v[48:63]
	v_fma_f32 v76, v164, v76, -v80
	v_fma_f32 v77, v165, v77, -v81
	v_fmamk_f32 v80, v94, 0x3e38aa3b, v191
	v_fmamk_f32 v81, v95, 0x3e38aa3b, v191
	v_exp_f32_e32 v80, v80
	v_fmamk_f32 v79, v79, 0x3e38aa3b, v190
	v_exp_f32_e32 v81, v81
	v_exp_f32_e32 v78, v78
	v_exp_f32_e32 v79, v79
	v_cvt_pk_bf16_f32 v70, v76, v77
	v_pk_mul_f32 v[80:81], v[166:167], v[80:81]
	s_nop 0
	v_pk_fma_f32 v[78:79], v[164:165], v[78:79], v[80:81] neg_lo:[0,0,1] neg_hi:[0,0,1]
	s_nop 0
	v_cvt_pk_bf16_f32 v71, v78, v79
	s_nop 0
	ds_read2_b64 v[250:253], v194 offset0:72 offset1:74
	s_waitcnt lgkmcnt(4)
	v_mfma_f32_32x32x16_bf16 v[48:63], v[224:227], v[68:71], v[48:63]
	ds_read2_b64 v[212:215], v196 offset0:140 offset1:142
	s_waitcnt lgkmcnt(4)
	v_mfma_f32_32x32x16_bf16 v[32:47], v[228:231], v[64:67], v[32:47]
	ds_read2_b64 v[224:227], v194 offset0:76 offset1:78
	s_waitcnt lgkmcnt(4)
	v_mfma_f32_32x32x16_bf16 v[16:31], v[236:239], v[64:67], v[16:31]
	s_waitcnt lgkmcnt(3)
	v_mfma_f32_32x32x16_bf16 v[16:31], v[246:249], v[68:71], v[16:31]
	s_waitcnt lgkmcnt(2)
	v_mfma_f32_32x32x16_bf16 v[0:15], v[250:253], v[64:67], v[0:15]
	s_waitcnt lgkmcnt(1)
	v_mfma_f32_32x32x16_bf16 v[32:47], v[212:215], v[68:71], v[32:47]
	s_waitcnt lgkmcnt(0)
	v_mfma_f32_32x32x16_bf16 v[0:15], v[224:227], v[68:71], v[0:15]
	s_cbranch_scc1 .LBB0_524
; #define MFMA(a, b, c) __builtin_amdgcn_mfma_f32_32x32x16_bf16((a), (b), (c), 0, 0, 0)
; DI f32x16 zero16() { f32x16 z; for (int i = 0; i < 16; ++i) z[i] = 0.f; return z; }
; DI void attn_unit(const Params& p, int l, int unit, unsigned char* smem) {
;     ...
;   for (int kt = 0; kt < ntile; ++kt) {
;     __syncthreads();
; #pragma unroll
;     for (int i = 0; i < 4; ++i) {
;       const int c = tid + 256 * i;
;       { const int key = c >> 4, kc = c & 15; *(u32x4*)(sK + key * 136 + 8 * kc) = rk[i]; }
;       { const int dv = c >> 3, kc = c & 7; *(u32x4*)(sVT + dv * 72 + 8 * kc) = rv[i]; }
;     }
;     __syncthreads();
;     if (kt + 1 < ntile) {
; #pragma unroll
;       for (int i = 0; i < 4; ++i) {
;         const int c = tid + 256 * i;
;         { const int key = c >> 4, kc = c & 15; rk[i] = *(const u32x4*)(Kbase + (size_t)((kt + 1) * 64 + key) * PLD + 8 * kc); }
;         { const int dv = c >> 3, kc = c & 7; rv[i] = *(const u32x4*)(VT + (size_t)dv * SP + (kt + 1) * 64 + 8 * kc); }
;       }
;     }
; #pragma unroll
;     for (int kb = 0; kb < 2; ++kb) {
;       f32x16 s0 = zero16(), s1 = zero16();
; #pragma unroll
;       for (int s = 0; s < 4; ++s) {
;         s0 = MFMA(ld16(sK + (32 * kb + l31) * 136 + 16 * s + 8 * h), qf[0][s], s0);
;         s1 = MFMA(ld16(sK + (32 * kb + l31) * 136 + 64 + 16 * s + 8 * h), qf[1][s], s1);
;       }
; #pragma unroll
;       for (int r = 0; r < 16; ++r) s0[r] = __builtin_amdgcn_exp2f(fmaf(s0[r], cs, nm[0])) * sc[0] - __builtin_amdgcn_exp2f(fmaf(s1[r], cs, nm[1])) * sc[1];
;       const bf16x8 p0 = pack8<0>(s0), p1 = pack8<1>(s0);
; #pragma unroll
;       for (int dvb = 0; dvb < 4; ++dvb) {
;         oacc[dvb] = MFMA(ld2x8(sVT + (32 * dvb + l31) * 72 + 32 * kb + 4 * h), p0, oacc[dvb]);
;         oacc[dvb] = MFMA(ld2x8(sVT + (32 * dvb + l31) * 72 + 32 * kb + 16 + 4 * h), p1, oacc[dvb]);
;       }
	s_barrier
	s_waitcnt vmcnt(0)
	ds_write_b128 v187, v[128:131]
	ds_write_b128 v203, v[132:135] offset:17408
	ds_write_b128 v186, v[136:139]
	ds_write_b128 v202, v[140:143] offset:17408
	ds_write_b128 v185, v[144:147]
	ds_write_b128 v201, v[148:151] offset:17408
	ds_write_b128 v184, v[152:155]
	ds_write_b128 v200, v[156:159] offset:17408
	s_waitcnt lgkmcnt(0)
	s_barrier
	ds_read_b128 v[64:67], v197
	ds_read_b128 v[128:131], v197 offset:32
	s_waitcnt lgkmcnt(1)
	v_mfma_f32_32x32x16_bf16 v[64:79], v[64:67], v[120:123], 0
	ds_read_b128 v[80:83], v197 offset:128
	s_lshl_b32 s44, s22, 1
	v_lshlrev_b32_e32 v208, 1, v188
	s_waitcnt lgkmcnt(1)
	v_mfma_f32_32x32x16_bf16 v[64:79], v[128:131], v[116:119], v[64:79]
	ds_read_b128 v[128:131], v197 offset:160
	s_waitcnt lgkmcnt(1)
	v_mfma_f32_32x32x16_bf16 v[80:95], v[80:83], v[124:127], 0
	s_waitcnt lgkmcnt(0)
	v_mfma_f32_32x32x16_bf16 v[80:95], v[128:131], v[112:115], v[80:95]
	ds_read_b128 v[128:131], v197 offset:64
	s_waitcnt lgkmcnt(0)
	v_mfma_f32_32x32x16_bf16 v[64:79], v[128:131], v[104:107], v[64:79]
	ds_read_b128 v[128:131], v197 offset:192
	s_waitcnt lgkmcnt(0)
	v_mfma_f32_32x32x16_bf16 v[80:95], v[128:131], v[108:111], v[80:95]
	ds_read_b128 v[128:131], v197 offset:96
	s_waitcnt lgkmcnt(0)
	v_mfma_f32_32x32x16_bf16 v[64:79], v[128:131], v[100:103], v[64:79]
	ds_read_b128 v[128:131], v197 offset:224
	s_waitcnt lgkmcnt(0)
	v_mfma_f32_32x32x16_bf16 v[80:95], v[128:131], v[96:99], v[80:95]
	s_nop 8
	v_fmamk_f32 v64, v64, 0x3e38aa3b, v190
	v_fmamk_f32 v65, v65, 0x3e38aa3b, v190
	v_exp_f32_e32 v64, v64
	v_exp_f32_e32 v65, v65
	v_fmamk_f32 v66, v66, 0x3e38aa3b, v190
	v_fmamk_f32 v67, v67, 0x3e38aa3b, v190
	v_exp_f32_e32 v66, v66
	v_fmamk_f32 v80, v80, 0x3e38aa3b, v191
	v_fmamk_f32 v81, v81, 0x3e38aa3b, v191
	v_exp_f32_e32 v80, v80
	v_exp_f32_e32 v81, v81
	v_exp_f32_e32 v67, v67
	v_fmamk_f32 v68, v68, 0x3e38aa3b, v190
	v_fmamk_f32 v69, v69, 0x3e38aa3b, v190
	v_pk_mul_f32 v[80:81], v[166:167], v[80:81]
	v_exp_f32_e32 v68, v68
	v_pk_fma_f32 v[64:65], v[164:165], v[64:65], v[80:81] neg_lo:[0,0,1] neg_hi:[0,0,1]
	v_fmamk_f32 v80, v82, 0x3e38aa3b, v191
	v_fmamk_f32 v81, v83, 0x3e38aa3b, v191
	v_exp_f32_e32 v80, v80
	v_exp_f32_e32 v81, v81
	v_exp_f32_e32 v69, v69
	v_fmamk_f32 v70, v70, 0x3e38aa3b, v190
	v_fmamk_f32 v71, v71, 0x3e38aa3b, v190
	v_pk_mul_f32 v[80:81], v[166:167], v[80:81]
	v_exp_f32_e32 v70, v70
	v_pk_fma_f32 v[66:67], v[164:165], v[66:67], v[80:81] neg_lo:[0,0,1] neg_hi:[0,0,1]
	v_fmamk_f32 v80, v84, 0x3e38aa3b, v191
	v_fmamk_f32 v81, v85, 0x3e38aa3b, v191
	v_exp_f32_e32 v80, v80
	v_exp_f32_e32 v81, v81
	v_exp_f32_e32 v71, v71
	v_fmamk_f32 v72, v72, 0x3e38aa3b, v190
	v_fmamk_f32 v73, v73, 0x3e38aa3b, v190
	v_pk_mul_f32 v[80:81], v[166:167], v[80:81]
	v_exp_f32_e32 v72, v72
	v_pk_fma_f32 v[68:69], v[164:165], v[68:69], v[80:81] neg_lo:[0,0,1] neg_hi:[0,0,1]
	v_fmamk_f32 v80, v86, 0x3e38aa3b, v191
	v_fmamk_f32 v81, v87, 0x3e38aa3b, v191
	v_exp_f32_e32 v80, v80
	v_exp_f32_e32 v81, v81
	v_exp_f32_e32 v73, v73
	v_fmamk_f32 v74, v74, 0x3e38aa3b, v190
	v_fmamk_f32 v75, v75, 0x3e38aa3b, v190
	v_pk_mul_f32 v[80:81], v[166:167], v[80:81]
	v_exp_f32_e32 v74, v74
	v_pk_fma_f32 v[70:71], v[164:165], v[70:71], v[80:81] neg_lo:[0,0,1] neg_hi:[0,0,1]
	v_fmamk_f32 v80, v88, 0x3e38aa3b, v191
	v_fmamk_f32 v81, v89, 0x3e38aa3b, v191
	v_exp_f32_e32 v80, v80
	v_exp_f32_e32 v81, v81
	v_exp_f32_e32 v75, v75
	v_fmamk_f32 v76, v76, 0x3e38aa3b, v190
	v_fmamk_f32 v77, v77, 0x3e38aa3b, v190
	v_pk_mul_f32 v[80:81], v[166:167], v[80:81]
	v_exp_f32_e32 v76, v76
	v_pk_fma_f32 v[72:73], v[164:165], v[72:73], v[80:81] neg_lo:[0,0,1] neg_hi:[0,0,1]
	v_fmamk_f32 v80, v90, 0x3e38aa3b, v191
	v_fmamk_f32 v81, v91, 0x3e38aa3b, v191
	v_exp_f32_e32 v80, v80
	v_exp_f32_e32 v81, v81
	v_exp_f32_e32 v77, v77
	v_fmamk_f32 v78, v78, 0x3e38aa3b, v190
	v_fmamk_f32 v79, v79, 0x3e38aa3b, v190
	v_pk_mul_f32 v[80:81], v[166:167], v[80:81]
	v_exp_f32_e32 v78, v78
	v_pk_fma_f32 v[74:75], v[164:165], v[74:75], v[80:81] neg_lo:[0,0,1] neg_hi:[0,0,1]
	v_fmamk_f32 v80, v92, 0x3e38aa3b, v191
	v_fmamk_f32 v81, v93, 0x3e38aa3b, v191
	v_exp_f32_e32 v80, v80
	v_exp_f32_e32 v81, v81
	v_exp_f32_e32 v79, v79
	v_cvt_pk_bf16_f32 v64, v64, v65
	v_cvt_pk_bf16_f32 v65, v66, v67
	v_pk_mul_f32 v[80:81], v[166:167], v[80:81]
	v_cvt_pk_bf16_f32 v66, v68, v69
	v_pk_fma_f32 v[76:77], v[164:165], v[76:77], v[80:81] neg_lo:[0,0,1] neg_hi:[0,0,1]
	v_fmamk_f32 v80, v94, 0x3e38aa3b, v191
	v_fmamk_f32 v81, v95, 0x3e38aa3b, v191
	v_exp_f32_e32 v80, v80
	v_exp_f32_e32 v81, v81
	v_cvt_pk_bf16_f32 v67, v70, v71
	v_cvt_pk_bf16_f32 v68, v72, v73
	v_cvt_pk_bf16_f32 v69, v74, v75
	v_pk_mul_f32 v[80:81], v[166:167], v[80:81]
	v_cvt_pk_bf16_f32 v70, v76, v77
	v_pk_fma_f32 v[78:79], v[164:165], v[78:79], v[80:81] neg_lo:[0,0,1] neg_hi:[0,0,1]
	s_nop 0
	v_cvt_pk_bf16_f32 v71, v78, v79
	ds_read2_b64 v[72:75], v193 offset0:128 offset1:130
	ds_read2_b64 v[76:79], v193 offset0:132 offset1:134
	s_waitcnt lgkmcnt(1)
	v_mfma_f32_32x32x16_bf16 v[48:63], v[72:75], v[64:67], v[48:63]
	s_waitcnt lgkmcnt(0)
	v_mfma_f32_32x32x16_bf16 v[48:63], v[76:79], v[68:71], v[48:63]
	ds_read2_b64 v[72:75], v196 offset0:128 offset1:130
	ds_read2_b64 v[76:79], v196 offset0:132 offset1:134
	s_waitcnt lgkmcnt(1)
	v_mfma_f32_32x32x16_bf16 v[32:47], v[72:75], v[64:67], v[32:47]
	ds_read2_b64 v[72:75], v195 offset1:2
	s_waitcnt lgkmcnt(0)
	v_mfma_f32_32x32x16_bf16 v[16:31], v[72:75], v[64:67], v[16:31]
	ds_read2_b64 v[72:75], v195 offset0:4 offset1:6
	s_waitcnt lgkmcnt(0)
	v_mfma_f32_32x32x16_bf16 v[16:31], v[72:75], v[68:71], v[16:31]
	ds_read2_b64 v[72:75], v194 offset0:64 offset1:66
	s_waitcnt lgkmcnt(0)
; #define MFMA(a, b, c) __builtin_amdgcn_mfma_f32_32x32x16_bf16((a), (b), (c), 0, 0, 0)
; DI f32x16 zero16() { f32x16 z; for (int i = 0; i < 16; ++i) z[i] = 0.f; return z; }
; DI void attn_unit(const Params& p, int l, int unit, unsigned char* smem) {
;     ...
;   for (int kt = 0; kt < ntile; ++kt) {
;     __syncthreads();
; #pragma unroll
;     for (int i = 0; i < 4; ++i) {
;       const int c = tid + 256 * i;
;       { const int key = c >> 4, kc = c & 15; *(u32x4*)(sK + key * 136 + 8 * kc) = rk[i]; }
;       { const int dv = c >> 3, kc = c & 7; *(u32x4*)(sVT + dv * 72 + 8 * kc) = rv[i]; }
;     }
;     __syncthreads();
;     if (kt + 1 < ntile) {
; #pragma unroll
;       for (int i = 0; i < 4; ++i) {
;         const int c = tid + 256 * i;
;         { const int key = c >> 4, kc = c & 15; rk[i] = *(const u32x4*)(Kbase + (size_t)((kt + 1) * 64 + key) * PLD + 8 * kc); }
;         { const int dv = c >> 3, kc = c & 7; rv[i] = *(const u32x4*)(VT + (size_t)dv * SP + (kt + 1) * 64 + 8 * kc); }
;       }
;     }
; #pragma unroll
;     for (int kb = 0; kb < 2; ++kb) {
;       f32x16 s0 = zero16(), s1 = zero16();
; #pragma unroll
;       for (int s = 0; s < 4; ++s) {
;         s0 = MFMA(ld16(sK + (32 * kb + l31) * 136 + 16 * s + 8 * h), qf[0][s], s0);
;         s1 = MFMA(ld16(sK + (32 * kb + l31) * 136 + 64 + 16 * s + 8 * h), qf[1][s], s1);
;       }
; #pragma unroll
;       for (int r = 0; r < 16; ++r) s0[r] = __builtin_amdgcn_exp2f(fmaf(s0[r], cs, nm[0])) * sc[0] - __builtin_amdgcn_exp2f(fmaf(s1[r], cs, nm[1])) * sc[1];
;       const bf16x8 p0 = pack8<0>(s0), p1 = pack8<1>(s0);
; #pragma unroll
;       for (int dvb = 0; dvb < 4; ++dvb) {
;         oacc[dvb] = MFMA(ld2x8(sVT + (32 * dvb + l31) * 72 + 32 * kb + 4 * h), p0, oacc[dvb]);
;         oacc[dvb] = MFMA(ld2x8(sVT + (32 * dvb + l31) * 72 + 32 * kb + 16 + 4 * h), p1, oacc[dvb]);
;       }
	v_mfma_f32_32x32x16_bf16 v[0:15], v[72:75], v[64:67], v[0:15]
	ds_read2_b64 v[64:67], v194 offset0:68 offset1:70
	s_waitcnt lgkmcnt(0)
	v_mfma_f32_32x32x16_bf16 v[0:15], v[64:67], v[68:71], v[0:15]
	ds_read_b128 v[64:67], v192
	ds_read_b128 v[128:131], v192 offset:32
	ds_read_b128 v[80:83], v192 offset:128
	v_mfma_f32_32x32x16_bf16 v[32:47], v[76:79], v[68:71], v[32:47]
	s_waitcnt lgkmcnt(2)
	v_mfma_f32_32x32x16_bf16 v[64:79], v[64:67], v[120:123], 0
	s_waitcnt lgkmcnt(1)
	v_mfma_f32_32x32x16_bf16 v[64:79], v[128:131], v[116:119], v[64:79]
	ds_read_b128 v[116:119], v192 offset:160
	s_waitcnt lgkmcnt(1)
	v_mfma_f32_32x32x16_bf16 v[80:95], v[80:83], v[124:127], 0
	s_waitcnt lgkmcnt(0)
	v_mfma_f32_32x32x16_bf16 v[80:95], v[116:119], v[112:115], v[80:95]
	ds_read_b128 v[112:115], v192 offset:64
	s_waitcnt lgkmcnt(0)
	v_mfma_f32_32x32x16_bf16 v[64:79], v[112:115], v[104:107], v[64:79]
	ds_read_b128 v[104:107], v192 offset:192
	s_waitcnt lgkmcnt(0)
	v_mfma_f32_32x32x16_bf16 v[80:95], v[104:107], v[108:111], v[80:95]
	ds_read_b128 v[104:107], v192 offset:96
	s_waitcnt lgkmcnt(0)
	v_mfma_f32_32x32x16_bf16 v[64:79], v[104:107], v[100:103], v[64:79]
	ds_read_b128 v[100:103], v192 offset:224
	s_waitcnt lgkmcnt(0)
	v_mfma_f32_32x32x16_bf16 v[80:95], v[100:103], v[96:99], v[80:95]
	s_nop 8
	v_fmamk_f32 v64, v64, 0x3e38aa3b, v190
	v_fmamk_f32 v65, v65, 0x3e38aa3b, v190
	v_exp_f32_e32 v64, v64
	v_exp_f32_e32 v65, v65
	v_fmamk_f32 v66, v66, 0x3e38aa3b, v190
	v_fmamk_f32 v67, v67, 0x3e38aa3b, v190
	v_exp_f32_e32 v66, v66
	v_fmamk_f32 v80, v80, 0x3e38aa3b, v191
	v_fmamk_f32 v81, v81, 0x3e38aa3b, v191
	v_exp_f32_e32 v80, v80
	v_exp_f32_e32 v81, v81
	v_exp_f32_e32 v67, v67
	v_fmamk_f32 v68, v68, 0x3e38aa3b, v190
	v_fmamk_f32 v69, v69, 0x3e38aa3b, v190
	v_pk_mul_f32 v[80:81], v[166:167], v[80:81]
	v_exp_f32_e32 v68, v68
	v_pk_fma_f32 v[64:65], v[164:165], v[64:65], v[80:81] neg_lo:[0,0,1] neg_hi:[0,0,1]
	v_fmamk_f32 v80, v82, 0x3e38aa3b, v191
	v_fmamk_f32 v81, v83, 0x3e38aa3b, v191
	v_exp_f32_e32 v80, v80
	v_exp_f32_e32 v81, v81
	v_exp_f32_e32 v69, v69
	v_fmamk_f32 v70, v70, 0x3e38aa3b, v190
	v_fmamk_f32 v71, v71, 0x3e38aa3b, v190
	v_pk_mul_f32 v[80:81], v[166:167], v[80:81]
	v_exp_f32_e32 v70, v70
	v_pk_fma_f32 v[66:67], v[164:165], v[66:67], v[80:81] neg_lo:[0,0,1] neg_hi:[0,0,1]
	v_fmamk_f32 v80, v84, 0x3e38aa3b, v191
	v_fmamk_f32 v81, v85, 0x3e38aa3b, v191
	v_exp_f32_e32 v80, v80
	v_exp_f32_e32 v81, v81
	v_exp_f32_e32 v71, v71
	v_fmamk_f32 v72, v72, 0x3e38aa3b, v190
	v_fmamk_f32 v73, v73, 0x3e38aa3b, v190
	v_pk_mul_f32 v[80:81], v[166:167], v[80:81]
	v_exp_f32_e32 v72, v72
	v_pk_fma_f32 v[68:69], v[164:165], v[68:69], v[80:81] neg_lo:[0,0,1] neg_hi:[0,0,1]
	v_fmamk_f32 v80, v86, 0x3e38aa3b, v191
	v_fmamk_f32 v81, v87, 0x3e38aa3b, v191
	v_exp_f32_e32 v80, v80
	v_exp_f32_e32 v81, v81
	v_exp_f32_e32 v73, v73
	v_fmamk_f32 v74, v74, 0x3e38aa3b, v190
	v_fmamk_f32 v75, v75, 0x3e38aa3b, v190
	v_pk_mul_f32 v[80:81], v[166:167], v[80:81]
	v_exp_f32_e32 v74, v74
	v_pk_fma_f32 v[70:71], v[164:165], v[70:71], v[80:81] neg_lo:[0,0,1] neg_hi:[0,0,1]
	v_fmamk_f32 v80, v88, 0x3e38aa3b, v191
	v_fmamk_f32 v81, v89, 0x3e38aa3b, v191
	v_exp_f32_e32 v80, v80
	v_exp_f32_e32 v81, v81
	v_exp_f32_e32 v75, v75
	v_cvt_pk_bf16_f32 v64, v64, v65
	v_cvt_pk_bf16_f32 v65, v66, v67
	v_pk_mul_f32 v[80:81], v[166:167], v[80:81]
	v_cvt_pk_bf16_f32 v66, v68, v69
	v_pk_fma_f32 v[72:73], v[164:165], v[72:73], v[80:81] neg_lo:[0,0,1] neg_hi:[0,0,1]
	v_fmamk_f32 v80, v90, 0x3e38aa3b, v191
	v_fmamk_f32 v81, v91, 0x3e38aa3b, v191
	v_exp_f32_e32 v80, v80
	v_exp_f32_e32 v81, v81
	v_cvt_pk_bf16_f32 v68, v72, v73
	v_fmamk_f32 v76, v76, 0x3e38aa3b, v190
	v_fmamk_f32 v77, v77, 0x3e38aa3b, v190
	v_pk_mul_f32 v[80:81], v[166:167], v[80:81]
	v_exp_f32_e32 v76, v76
	v_pk_fma_f32 v[74:75], v[164:165], v[74:75], v[80:81] neg_lo:[0,0,1] neg_hi:[0,0,1]
	v_fmamk_f32 v80, v92, 0x3e38aa3b, v191
	v_cvt_pk_bf16_f32 v69, v74, v75
	ds_read2_b64 v[72:75], v193 offset0:136 offset1:138
	v_fmamk_f32 v81, v93, 0x3e38aa3b, v191
	v_exp_f32_e32 v80, v80
	v_exp_f32_e32 v81, v81
	v_exp_f32_e32 v77, v77
	v_cvt_pk_bf16_f32 v67, v70, v71
	v_fmamk_f32 v78, v78, 0x3e38aa3b, v190
	v_pk_mul_f32 v[80:81], v[166:167], v[80:81]
	s_waitcnt lgkmcnt(0)
	v_mfma_f32_32x32x16_bf16 v[48:63], v[72:75], v[64:67], v[48:63]
	ds_read2_b64 v[72:75], v193 offset0:140 offset1:142
	v_fma_f32 v76, v164, v76, -v80
	v_fma_f32 v77, v165, v77, -v81
	v_fmamk_f32 v80, v94, 0x3e38aa3b, v191
	v_fmac_f32_e32 v191, 0x3e38aa3b, v95
	v_exp_f32_e32 v80, v80
	v_fmac_f32_e32 v190, 0x3e38aa3b, v79
	v_exp_f32_e32 v81, v191
	v_exp_f32_e32 v78, v78
	v_exp_f32_e32 v79, v190
	v_cvt_pk_bf16_f32 v70, v76, v77
	v_pk_mul_f32 v[80:81], v[166:167], v[80:81]
	s_nop 0
	v_pk_fma_f32 v[78:79], v[164:165], v[78:79], v[80:81] neg_lo:[0,0,1] neg_hi:[0,0,1]
	s_nop 0
	v_cvt_pk_bf16_f32 v71, v78, v79
	s_waitcnt lgkmcnt(0)
	s_nop 0
	v_mfma_f32_32x32x16_bf16 v[48:63], v[72:75], v[68:71], v[48:63]
	ds_read2_b64 v[72:75], v196 offset0:136 offset1:138
	ds_read2_b64 v[76:79], v196 offset0:140 offset1:142
	s_waitcnt lgkmcnt(1)
	v_mfma_f32_32x32x16_bf16 v[32:47], v[72:75], v[64:67], v[32:47]
	ds_read2_b64 v[72:75], v195 offset0:8 offset1:10
	s_waitcnt lgkmcnt(0)
	v_mfma_f32_32x32x16_bf16 v[16:31], v[72:75], v[64:67], v[16:31]
	ds_read2_b64 v[72:75], v195 offset0:12 offset1:14
	s_waitcnt lgkmcnt(0)
	v_mfma_f32_32x32x16_bf16 v[16:31], v[72:75], v[68:71], v[16:31]
	ds_read2_b64 v[72:75], v194 offset0:72 offset1:74
	s_waitcnt lgkmcnt(0)
; DI float bf2f(bfr v) { return __uint_as_float(((unsigned)v) << 16); }
; DI float siluf_(float x) { return x / (1.f + __expf(-x)); }
; DI void attn_unit(const Params& p, int l, int unit, unsigned char* smem) {
;     ...
;   float ss = 0.f;
; #pragma unroll
;   for (int dvb = 0; dvb < 4; ++dvb)
; #pragma unroll
;     for (int r = 0; r < 16; ++r) ss += oacc[dvb][r] * oacc[dvb][r];
;   ss += __shfl_xor(ss, 32);
;   const float rs = rsqrtf(ss * (1.f / 128.f) + EPS) * (1.f - lam_init);
;   bfr* YS = (bfr*)(WS_ + O_YS);
; #pragma unroll
;   for (int dvb = 0; dvb < 4; ++dvb)
; #pragma unroll
;     for (int g = 0; g < 4; ++g) {
;       const int dv = 32 * dvb + 8 * g + 4 * h;
;       const s16x4 z4 = *(const s16x4*)(P + rowq * PLD + C_DAZ + hd * 128 + dv);
;       const f32x4 gn = *(const f32x4*)(p.da_norm + l * 128 + dv);
;       float y[4];
;       for (int q = 0; q < 4; ++q) y[q] = oacc[dvb][4 * g + q] * rs * gn[q] * siluf_(bf2f((bfr)z4[q]));
	v_mfma_f32_32x32x16_bf16 v[0:15], v[72:75], v[64:67], v[0:15]
	v_mul_f32_e32 v74, v49, v49
	v_fmac_f32_e32 v74, v48, v48
	v_fmac_f32_e32 v74, v50, v50
	v_fmac_f32_e32 v74, v51, v51
	v_fmac_f32_e32 v74, v52, v52
	v_fmac_f32_e32 v74, v53, v53
	v_fmac_f32_e32 v74, v54, v54
	v_fmac_f32_e32 v74, v55, v55
	v_mfma_f32_32x32x16_bf16 v[32:47], v[76:79], v[68:71], v[32:47]
	v_fmac_f32_e32 v74, v56, v56
	v_fmac_f32_e32 v74, v57, v57
	v_fmac_f32_e32 v74, v58, v58
	v_fmac_f32_e32 v74, v59, v59
	v_fmac_f32_e32 v74, v60, v60
	v_fmac_f32_e32 v74, v61, v61
	v_fmac_f32_e32 v74, v62, v62
	v_fmac_f32_e32 v74, v63, v63
	s_nop 3
	v_fmac_f32_e32 v74, v32, v32
	v_fmac_f32_e32 v74, v33, v33
	v_fmac_f32_e32 v74, v34, v34
	v_fmac_f32_e32 v74, v35, v35
	v_fmac_f32_e32 v74, v36, v36
	v_fmac_f32_e32 v74, v37, v37
	v_fmac_f32_e32 v74, v38, v38
	v_fmac_f32_e32 v74, v39, v39
	v_fmac_f32_e32 v74, v40, v40
	v_fmac_f32_e32 v74, v41, v41
	v_fmac_f32_e32 v74, v42, v42
	v_fmac_f32_e32 v74, v43, v43
	v_fmac_f32_e32 v74, v44, v44
	v_fmac_f32_e32 v74, v45, v45
	v_fmac_f32_e32 v74, v46, v46
	ds_read2_b64 v[64:67], v194 offset0:76 offset1:78
	v_fmac_f32_e32 v74, v47, v47
	v_fmac_f32_e32 v74, v16, v16
	v_fmac_f32_e32 v74, v17, v17
	v_fmac_f32_e32 v74, v18, v18
	v_fmac_f32_e32 v74, v19, v19
	v_fmac_f32_e32 v74, v20, v20
	v_fmac_f32_e32 v74, v21, v21
	v_fmac_f32_e32 v74, v22, v22
	v_fmac_f32_e32 v74, v23, v23
	s_waitcnt lgkmcnt(0)
	v_mfma_f32_32x32x16_bf16 v[0:15], v[64:67], v[68:71], v[0:15]
	v_fmac_f32_e32 v74, v24, v24
	v_fmac_f32_e32 v74, v25, v25
	v_fmac_f32_e32 v74, v26, v26
	v_fmac_f32_e32 v74, v27, v27
	v_fmac_f32_e32 v74, v28, v28
	v_fmac_f32_e32 v74, v29, v29
	v_fmac_f32_e32 v74, v30, v30
	v_fmac_f32_e32 v74, v31, v31
	s_nop 3
	v_fmac_f32_e32 v74, v0, v0
	v_fmac_f32_e32 v74, v1, v1
	v_fmac_f32_e32 v74, v2, v2
	v_fmac_f32_e32 v74, v3, v3
	v_fmac_f32_e32 v74, v4, v4
	v_fmac_f32_e32 v74, v5, v5
	v_pk_mul_f32 v[72:73], v[6:7], v[6:7]
	v_pk_mul_f32 v[70:71], v[8:9], v[8:9]
	v_add_f32_e32 v72, v72, v74
	v_add_f32_e32 v72, v73, v72
	v_add_f32_e32 v70, v70, v72
	v_pk_mul_f32 v[68:69], v[10:11], v[10:11]
	v_add_f32_e32 v70, v71, v70
	v_add_f32_e32 v68, v68, v70
	v_pk_mul_f32 v[66:67], v[12:13], v[12:13]
	v_add_f32_e32 v68, v69, v68
	v_add_f32_e32 v66, v66, v68
	v_pk_mul_f32 v[64:65], v[14:15], v[14:15]
	v_add_f32_e32 v66, v67, v66
	v_add_f32_e32 v64, v64, v66
	v_add_f32_e32 v64, v65, v64
	ds_bpermute_b32 v65, v189, v64
	v_lshlrev_b64 v[68:69], 12, v[160:161]
	v_lshl_add_u64 v[66:67], v[162:163], 0, s[44:45]
	v_lshl_add_u64 v[68:69], s[10:11], 0, v[68:69]
	v_lshl_add_u64 v[72:73], v[68:69], 0, s[44:45]
	s_waitcnt lgkmcnt(0)
	v_add_f32_e32 v64, v64, v65
	v_fmamk_f32 v64, v64, 0x3c000000, v217
	v_cmp_gt_f32_e32 vcc, s37, v64
	v_mul_f32_e32 v65, 0x4b800000, v64
	v_lshl_add_u64 v[68:69], v[66:67], 0, v[208:209]
	v_cndmask_b32_e32 v64, v64, v65, vcc
	v_rsq_f32_e32 v64, v64
	s_mov_b64 s[10:11], 0x3c00
	v_lshl_add_u64 v[66:67], v[68:69], 0, s[10:11]
	s_movk_i32 s10, 0x3000
	v_mul_f32_e32 v65, 0x45800000, v64
	v_cndmask_b32_e32 v64, v64, v65, vcc
	v_add_co_u32_e32 v68, vcc, s10, v68
	v_lshlrev_b32_e32 v65, 2, v188
	s_nop 0
	v_addc_co_u32_e32 v69, vcc, 0, v69, vcc
	global_load_dwordx2 v[96:97], v[68:69], off offset:3072
	global_load_dwordx4 v[136:139], v65, s[18:19]
	global_load_dwordx2 v[98:99], v[66:67], off offset:16
	global_load_dwordx4 v[140:143], v65, s[18:19] offset:32
	global_load_dwordx2 v[100:101], v[66:67], off offset:32
	global_load_dwordx4 v[144:147], v65, s[18:19] offset:64
	global_load_dwordx2 v[102:103], v[66:67], off offset:48
	global_load_dwordx4 v[148:151], v65, s[18:19] offset:96
	global_load_dwordx2 v[104:105], v[66:67], off offset:64
	global_load_dwordx4 v[152:155], v65, s[18:19] offset:128
	global_load_dwordx2 v[106:107], v[66:67], off offset:80
	global_load_dwordx4 v[156:159], v65, s[18:19] offset:160
	global_load_dwordx2 v[108:109], v[66:67], off offset:96
	global_load_dwordx4 v[160:163], v65, s[18:19] offset:192
	global_load_dwordx2 v[110:111], v[66:67], off offset:112
	global_load_dwordx4 v[164:167], v65, s[18:19] offset:224
	global_load_dwordx2 v[112:113], v[66:67], off offset:128
	global_load_dwordx4 v[168:171], v65, s[18:19] offset:256
	global_load_dwordx2 v[114:115], v[66:67], off offset:144
	global_load_dwordx4 v[172:175], v65, s[18:19] offset:288
	global_load_dwordx2 v[82:83], v[66:67], off offset:160
	global_load_dwordx4 v[176:179], v65, s[18:19] offset:320
	global_load_dwordx2 v[84:85], v[66:67], off offset:176
	global_load_dwordx4 v[180:183], v65, s[18:19] offset:352
	global_load_dwordx2 v[86:87], v[66:67], off offset:192
	global_load_dwordx4 v[184:187], v65, s[18:19] offset:384
	global_load_dwordx2 v[88:89], v[66:67], off offset:208
	global_load_dwordx4 v[188:191], v65, s[18:19] offset:416
	global_load_dwordx2 v[90:91], v[66:67], off offset:224
	global_load_dwordx4 v[192:195], v65, s[18:19] offset:448
	global_load_dwordx2 v[92:93], v[66:67], off offset:240
	global_load_dwordx4 v[196:199], v65, s[18:19] offset:480
	s_waitcnt vmcnt(0)
; DI float bf2f(bfr v) { return __uint_as_float(((unsigned)v) << 16); }
; DI unsigned pk2(float a, float b) { f2_t v = {a, b}; bf2_t r = __builtin_convertvector(v, bf2_t); return __builtin_bit_cast(unsigned, r); }
; DI float siluf_(float x) { return x / (1.f + __expf(-x)); }
; DI void attn_unit(const Params& p, int l, int unit, unsigned char* smem) {
;     ...
; #pragma unroll
;   for (int dvb = 0; dvb < 4; ++dvb)
; #pragma unroll
;     for (int g = 0; g < 4; ++g) {
;       const int dv = 32 * dvb + 8 * g + 4 * h;
;       const s16x4 z4 = *(const s16x4*)(P + rowq * PLD + C_DAZ + hd * 128 + dv);
;       const f32x4 gn = *(const f32x4*)(p.da_norm + l * 128 + dv);
;       float y[4];
;       for (int q = 0; q < 4; ++q) y[q] = oacc[dvb][4 * g + q] * rs * gn[q] * siluf_(bf2f((bfr)z4[q]));
;       u32x2 w; w[0] = pk2(y[0], y[1]); w[1] = pk2(y[2], y[3]);
;       *(u32x2*)(YS + rowq * DM + 1536 + hd * 128 + dv) = w;
	v_mov_b32_e32 v74, v96
	v_mov_b32_e32 v75, v97
	v_mul_f32_e32 v64, v244, v64
	v_mov_b32_e32 v68, v136
	v_mov_b32_e32 v69, v137
	v_mov_b32_e32 v70, v138
	v_mov_b32_e32 v71, v139
	v_pk_mul_f32 v[48:49], v[48:49], v[64:65] op_sel_hi:[1,0]
	v_pk_mul_f32 v[50:51], v[50:51], v[64:65] op_sel_hi:[1,0]
	v_pk_mul_f32 v[52:53], v[52:53], v[64:65] op_sel_hi:[1,0]
	v_pk_mul_f32 v[54:55], v[54:55], v[64:65] op_sel_hi:[1,0]
	v_pk_mul_f32 v[56:57], v[56:57], v[64:65] op_sel_hi:[1,0]
	v_pk_mul_f32 v[32:33], v[32:33], v[64:65] op_sel_hi:[1,0]
	v_pk_mul_f32 v[34:35], v[34:35], v[64:65] op_sel_hi:[1,0]
	v_pk_mul_f32 v[36:37], v[36:37], v[64:65] op_sel_hi:[1,0]
	v_pk_mul_f32 v[38:39], v[38:39], v[64:65] op_sel_hi:[1,0]
	v_pk_mul_f32 v[40:41], v[40:41], v[64:65] op_sel_hi:[1,0]
	v_pk_mul_f32 v[16:17], v[16:17], v[64:65] op_sel_hi:[1,0]
	v_pk_mul_f32 v[18:19], v[18:19], v[64:65] op_sel_hi:[1,0]
	v_pk_mul_f32 v[20:21], v[20:21], v[64:65] op_sel_hi:[1,0]
	v_pk_mul_f32 v[22:23], v[22:23], v[64:65] op_sel_hi:[1,0]
	v_pk_mul_f32 v[24:25], v[24:25], v[64:65] op_sel_hi:[1,0]
	v_pk_mul_f32 v[0:1], v[0:1], v[64:65] op_sel_hi:[1,0]
	v_pk_mul_f32 v[2:3], v[2:3], v[64:65] op_sel_hi:[1,0]
	v_pk_mul_f32 v[4:5], v[4:5], v[64:65] op_sel_hi:[1,0]
	v_pk_mul_f32 v[6:7], v[6:7], v[64:65] op_sel_hi:[1,0]
	v_pk_mul_f32 v[8:9], v[8:9], v[64:65] op_sel_hi:[1,0]
	s_waitcnt lgkmcnt(0)
	v_and_b32_e32 v78, 0xffff0000, v74
	v_lshlrev_b32_e32 v74, 16, v74
	v_mul_f32_e32 v76, 0xbfb8aa3b, v74
	v_pk_mul_f32 v[48:49], v[68:69], v[48:49]
	v_mul_f32_e32 v68, 0xbfb8aa3b, v78
	v_exp_f32_e32 v76, v76
	v_exp_f32_e32 v77, v68
	v_pk_mul_f32 v[50:51], v[70:71], v[50:51]
	v_pk_add_f32 v[68:69], v[76:77], 1.0 op_sel_hi:[1,0]
	s_nop 0
	v_div_scale_f32 v76, s[10:11], v69, v69, v78
	v_rcp_f32_e32 v77, v76
	s_nop 0
	v_fma_f32 v79, -v76, v77, 1.0
	v_fmac_f32_e32 v77, v79, v77
	v_div_scale_f32 v79, vcc, v78, v69, v78
	v_mul_f32_e32 v80, v79, v77
	v_fma_f32 v81, -v76, v80, v79
	v_fmac_f32_e32 v80, v81, v77
	v_fma_f32 v76, -v76, v80, v79
	v_div_fmas_f32 v76, v76, v77, v80
	v_div_fixup_f32 v69, v76, v69, v78
	v_div_scale_f32 v76, s[10:11], v68, v68, v74
	v_rcp_f32_e32 v77, v76
	s_nop 0
	v_fma_f32 v78, -v76, v77, 1.0
	v_fmac_f32_e32 v77, v78, v77
	v_div_scale_f32 v78, vcc, v74, v68, v74
	v_mul_f32_e32 v79, v78, v77
	v_fma_f32 v80, -v76, v79, v78
	v_fmac_f32_e32 v79, v80, v77
	v_fma_f32 v76, -v76, v79, v78
	v_div_fmas_f32 v76, v76, v77, v79
	v_div_fixup_f32 v68, v76, v68, v74
	v_and_b32_e32 v74, 0xffff0000, v75
	v_lshlrev_b32_e32 v75, 16, v75
	v_pk_mul_f32 v[48:49], v[68:69], v[48:49]
	v_mul_f32_e32 v68, 0xbfb8aa3b, v75
	v_mul_f32_e32 v69, 0xbfb8aa3b, v74
	v_exp_f32_e32 v68, v68
	v_exp_f32_e32 v69, v69
	s_nop 0
	v_pk_add_f32 v[68:69], v[68:69], 1.0 op_sel_hi:[1,0]
	s_nop 0
	v_div_scale_f32 v70, s[10:11], v69, v69, v74
	v_rcp_f32_e32 v71, v70
	s_nop 0
	v_fma_f32 v76, -v70, v71, 1.0
	v_fmac_f32_e32 v71, v76, v71
	v_div_scale_f32 v76, vcc, v74, v69, v74
	v_mul_f32_e32 v77, v76, v71
	v_fma_f32 v78, -v70, v77, v76
	v_fmac_f32_e32 v77, v78, v71
	v_fma_f32 v70, -v70, v77, v76
	v_div_fmas_f32 v70, v70, v71, v77
	v_div_fixup_f32 v69, v70, v69, v74
	v_div_scale_f32 v70, s[10:11], v68, v68, v75
	v_rcp_f32_e32 v71, v70
	s_mov_b64 s[10:11], 0x33110c00
	v_fma_f32 v74, -v70, v71, 1.0
	v_fmac_f32_e32 v71, v74, v71
	v_div_scale_f32 v74, vcc, v75, v68, v75
	v_mul_f32_e32 v76, v74, v71
	v_fma_f32 v77, -v70, v76, v74
	v_fmac_f32_e32 v76, v77, v71
	v_fma_f32 v70, -v70, v76, v74
	v_div_fmas_f32 v70, v70, v71, v76
	v_div_fixup_f32 v68, v70, v68, v75
	v_pk_mul_f32 v[50:51], v[68:69], v[50:51]
	v_cvt_pk_bf16_f32 v68, v48, v49
	v_cvt_pk_bf16_f32 v69, v50, v51
	v_lshl_add_u64 v[50:51], v[72:73], 0, v[208:209]
	v_lshl_add_u64 v[48:49], v[50:51], 0, s[10:11]
	s_mov_b32 s10, 0x33110000
	v_add_co_u32_e32 v50, vcc, s10, v50
	s_nop 1
	v_addc_co_u32_e32 v51, vcc, 0, v51, vcc
	global_store_dwordx2 v[50:51], v[68:69], off offset:3072
	v_mov_b32_e32 v50, v98
	v_mov_b32_e32 v51, v99
	s_nop 0
	v_mov_b32_e32 v68, v140
	v_mov_b32_e32 v69, v141
	v_mov_b32_e32 v70, v142
	v_mov_b32_e32 v71, v143
	s_waitcnt lgkmcnt(0)
	v_and_b32_e32 v74, 0xffff0000, v50
	v_lshlrev_b32_e32 v50, 16, v50
	v_mul_f32_e32 v72, 0xbfb8aa3b, v50
	v_pk_mul_f32 v[52:53], v[68:69], v[52:53]
	v_mul_f32_e32 v68, 0xbfb8aa3b, v74
	v_exp_f32_e32 v72, v72
	v_exp_f32_e32 v73, v68
	v_pk_mul_f32 v[54:55], v[70:71], v[54:55]
	v_pk_add_f32 v[68:69], v[72:73], 1.0 op_sel_hi:[1,0]
	s_nop 0
	v_div_scale_f32 v72, s[10:11], v69, v69, v74
	v_rcp_f32_e32 v73, v72
	s_nop 0
	v_fma_f32 v75, -v72, v73, 1.0
	v_fmac_f32_e32 v73, v75, v73
	v_div_scale_f32 v75, vcc, v74, v69, v74
	v_mul_f32_e32 v76, v75, v73
	v_fma_f32 v77, -v72, v76, v75
	v_fmac_f32_e32 v76, v77, v73
	v_fma_f32 v72, -v72, v76, v75
	v_div_fmas_f32 v72, v72, v73, v76
	v_div_fixup_f32 v69, v72, v69, v74
	v_div_scale_f32 v72, s[10:11], v68, v68, v50
	v_rcp_f32_e32 v73, v72
	s_nop 0
	v_fma_f32 v74, -v72, v73, 1.0
	v_fmac_f32_e32 v73, v74, v73
	v_div_scale_f32 v74, vcc, v50, v68, v50
	v_mul_f32_e32 v75, v74, v73
	v_fma_f32 v76, -v72, v75, v74
	v_fmac_f32_e32 v75, v76, v73
	v_fma_f32 v72, -v72, v75, v74
	v_div_fmas_f32 v72, v72, v73, v75
	v_div_fixup_f32 v68, v72, v68, v50
	v_pk_mul_f32 v[52:53], v[68:69], v[52:53]
	v_and_b32_e32 v68, 0xffff0000, v51
	v_lshlrev_b32_e32 v69, 16, v51
	v_mul_f32_e32 v50, 0xbfb8aa3b, v69
	v_mul_f32_e32 v51, 0xbfb8aa3b, v68
	v_exp_f32_e32 v50, v50
	v_exp_f32_e32 v51, v51
	v_cvt_pk_bf16_f32 v52, v52, v53
	v_pk_add_f32 v[50:51], v[50:51], 1.0 op_sel_hi:[1,0]
	s_nop 0
	v_div_scale_f32 v70, s[10:11], v51, v51, v68
	v_rcp_f32_e32 v71, v70
	s_nop 0
	v_fma_f32 v72, -v70, v71, 1.0
	v_fmac_f32_e32 v71, v72, v71
	v_div_scale_f32 v72, vcc, v68, v51, v68
	v_mul_f32_e32 v73, v72, v71
	v_fma_f32 v74, -v70, v73, v72
	v_fmac_f32_e32 v73, v74, v71
	v_fma_f32 v70, -v70, v73, v72
	v_div_fmas_f32 v70, v70, v71, v73
	v_div_fixup_f32 v51, v70, v51, v68
	v_div_scale_f32 v68, s[10:11], v50, v50, v69
	v_rcp_f32_e32 v70, v68
	s_nop 0
	v_fma_f32 v71, -v68, v70, 1.0
	v_fmac_f32_e32 v70, v71, v70
	v_div_scale_f32 v71, vcc, v69, v50, v69
	v_mul_f32_e32 v72, v71, v70
	v_fma_f32 v73, -v68, v72, v71
	v_fmac_f32_e32 v72, v73, v70
	v_fma_f32 v68, -v68, v72, v71
	v_div_fmas_f32 v68, v68, v70, v72
	v_div_fixup_f32 v50, v68, v50, v69
	v_pk_mul_f32 v[50:51], v[50:51], v[54:55]
	s_nop 0
	v_cvt_pk_bf16_f32 v53, v50, v51
	global_store_dwordx2 v[48:49], v[52:53], off offset:16
	v_mov_b32_e32 v54, v100
	v_mov_b32_e32 v55, v101
	s_nop 0
	v_mov_b32_e32 v50, v144
	v_mov_b32_e32 v51, v145
	v_mov_b32_e32 v52, v146
	v_mov_b32_e32 v53, v147
	s_waitcnt lgkmcnt(0)
; DI float bf2f(bfr v) { return __uint_as_float(((unsigned)v) << 16); }
; DI unsigned pk2(float a, float b) { f2_t v = {a, b}; bf2_t r = __builtin_convertvector(v, bf2_t); return __builtin_bit_cast(unsigned, r); }
; DI float siluf_(float x) { return x / (1.f + __expf(-x)); }
; DI void attn_unit(const Params& p, int l, int unit, unsigned char* smem) {
;     ...
; #pragma unroll
;   for (int dvb = 0; dvb < 4; ++dvb)
; #pragma unroll
;     for (int g = 0; g < 4; ++g) {
;       const int dv = 32 * dvb + 8 * g + 4 * h;
;       const s16x4 z4 = *(const s16x4*)(P + rowq * PLD + C_DAZ + hd * 128 + dv);
;       const f32x4 gn = *(const f32x4*)(p.da_norm + l * 128 + dv);
;       float y[4];
;       for (int q = 0; q < 4; ++q) y[q] = oacc[dvb][4 * g + q] * rs * gn[q] * siluf_(bf2f((bfr)z4[q]));
;       u32x2 w; w[0] = pk2(y[0], y[1]); w[1] = pk2(y[2], y[3]);
;       *(u32x2*)(YS + rowq * DM + 1536 + hd * 128 + dv) = w;
	v_and_b32_e32 v70, 0xffff0000, v54
	v_lshlrev_b32_e32 v54, 16, v54
	v_mul_f32_e32 v68, 0xbfb8aa3b, v54
	v_pk_mul_f32 v[50:51], v[50:51], v[56:57]
	v_mul_f32_e32 v56, 0xbfb8aa3b, v70
	v_exp_f32_e32 v68, v68
	v_exp_f32_e32 v69, v56
	s_nop 0
	v_pk_add_f32 v[56:57], v[68:69], 1.0 op_sel_hi:[1,0]
	s_nop 0
	v_div_scale_f32 v68, s[10:11], v57, v57, v70
	v_rcp_f32_e32 v69, v68
	s_nop 0
	v_fma_f32 v71, -v68, v69, 1.0
	v_fmac_f32_e32 v69, v71, v69
	v_div_scale_f32 v71, vcc, v70, v57, v70
	v_mul_f32_e32 v72, v71, v69
	v_fma_f32 v73, -v68, v72, v71
	v_fmac_f32_e32 v72, v73, v69
	v_fma_f32 v68, -v68, v72, v71
	v_div_fmas_f32 v68, v68, v69, v72
	v_div_fixup_f32 v57, v68, v57, v70
	v_div_scale_f32 v68, s[10:11], v56, v56, v54
	v_rcp_f32_e32 v69, v68
	s_nop 0
	v_fma_f32 v70, -v68, v69, 1.0
	v_fmac_f32_e32 v69, v70, v69
	v_div_scale_f32 v70, vcc, v54, v56, v54
	v_mul_f32_e32 v71, v70, v69
	v_fma_f32 v72, -v68, v71, v70
	v_fmac_f32_e32 v71, v72, v69
	v_fma_f32 v68, -v68, v71, v70
	v_div_fmas_f32 v68, v68, v69, v71
	v_div_fixup_f32 v56, v68, v56, v54
	v_and_b32_e32 v68, 0xffff0000, v55
	v_lshlrev_b32_e32 v69, 16, v55
	v_mul_f32_e32 v54, 0xbfb8aa3b, v69
	v_mul_f32_e32 v55, 0xbfb8aa3b, v68
	v_exp_f32_e32 v54, v54
	v_exp_f32_e32 v55, v55
	v_pk_mul_f32 v[50:51], v[56:57], v[50:51]
	v_pk_mul_f32 v[56:57], v[58:59], v[64:65] op_sel_hi:[1,0]
	v_cvt_pk_bf16_f32 v50, v50, v51
	v_pk_add_f32 v[54:55], v[54:55], 1.0 op_sel_hi:[1,0]
	v_pk_mul_f32 v[52:53], v[52:53], v[56:57]
	v_div_scale_f32 v56, s[10:11], v55, v55, v68
	v_rcp_f32_e32 v57, v56
	s_nop 0
	v_fma_f32 v58, -v56, v57, 1.0
	v_fmac_f32_e32 v57, v58, v57
	v_div_scale_f32 v58, vcc, v68, v55, v68
	v_mul_f32_e32 v59, v58, v57
	v_fma_f32 v70, -v56, v59, v58
	v_fmac_f32_e32 v59, v70, v57
	v_fma_f32 v56, -v56, v59, v58
	v_div_fmas_f32 v56, v56, v57, v59
	v_div_fixup_f32 v55, v56, v55, v68
	v_div_scale_f32 v56, s[10:11], v54, v54, v69
	v_rcp_f32_e32 v57, v56
	s_nop 0
	v_fma_f32 v58, -v56, v57, 1.0
	v_fmac_f32_e32 v57, v58, v57
	v_div_scale_f32 v58, vcc, v69, v54, v69
	v_mul_f32_e32 v59, v58, v57
	v_fma_f32 v68, -v56, v59, v58
	v_fmac_f32_e32 v59, v68, v57
	v_fma_f32 v56, -v56, v59, v58
	v_div_fmas_f32 v56, v56, v57, v59
	v_div_fixup_f32 v54, v56, v54, v69
	v_pk_mul_f32 v[52:53], v[54:55], v[52:53]
	v_pk_mul_f32 v[58:59], v[60:61], v[64:65] op_sel_hi:[1,0]
	v_cvt_pk_bf16_f32 v51, v52, v53
	global_store_dwordx2 v[48:49], v[50:51], off offset:32
	v_mov_b32_e32 v54, v102
	v_mov_b32_e32 v55, v103
	s_nop 0
	v_mov_b32_e32 v50, v148
	v_mov_b32_e32 v51, v149
	v_mov_b32_e32 v52, v150
	v_mov_b32_e32 v53, v151
	s_waitcnt lgkmcnt(0)
	v_and_b32_e32 v68, 0xffff0000, v54
	v_lshlrev_b32_e32 v54, 16, v54
	v_mul_f32_e32 v56, 0xbfb8aa3b, v54
	v_mul_f32_e32 v57, 0xbfb8aa3b, v68
	v_exp_f32_e32 v56, v56
	v_exp_f32_e32 v57, v57
	v_pk_mul_f32 v[50:51], v[50:51], v[58:59]
	v_pk_add_f32 v[56:57], v[56:57], 1.0 op_sel_hi:[1,0]
	s_nop 0
	v_div_scale_f32 v58, s[10:11], v57, v57, v68
	v_rcp_f32_e32 v59, v58
	s_nop 0
	v_fma_f32 v60, -v58, v59, 1.0
	v_fmac_f32_e32 v59, v60, v59
	v_div_scale_f32 v60, vcc, v68, v57, v68
	v_mul_f32_e32 v61, v60, v59
	v_fma_f32 v69, -v58, v61, v60
	v_fmac_f32_e32 v61, v69, v59
	v_fma_f32 v58, -v58, v61, v60
	v_div_fmas_f32 v58, v58, v59, v61
	v_div_fixup_f32 v57, v58, v57, v68
	v_div_scale_f32 v58, s[10:11], v56, v56, v54
	v_rcp_f32_e32 v59, v58
	s_nop 0
	v_fma_f32 v60, -v58, v59, 1.0
	v_fmac_f32_e32 v59, v60, v59
	v_div_scale_f32 v60, vcc, v54, v56, v54
	v_mul_f32_e32 v61, v60, v59
	v_fma_f32 v68, -v58, v61, v60
	v_fmac_f32_e32 v61, v68, v59
	v_fma_f32 v58, -v58, v61, v60
	v_div_fmas_f32 v58, v58, v59, v61
	v_div_fixup_f32 v56, v58, v56, v54
	v_and_b32_e32 v58, 0xffff0000, v55
	v_lshlrev_b32_e32 v59, 16, v55
	v_mul_f32_e32 v54, 0xbfb8aa3b, v59
	v_mul_f32_e32 v55, 0xbfb8aa3b, v58
	v_exp_f32_e32 v54, v54
	v_exp_f32_e32 v55, v55
	v_pk_mul_f32 v[50:51], v[56:57], v[50:51]
	v_pk_mul_f32 v[56:57], v[62:63], v[64:65] op_sel_hi:[1,0]
	v_cvt_pk_bf16_f32 v50, v50, v51
	v_pk_add_f32 v[54:55], v[54:55], 1.0 op_sel_hi:[1,0]
	v_pk_mul_f32 v[52:53], v[52:53], v[56:57]
	v_div_scale_f32 v56, s[10:11], v55, v55, v58
	v_rcp_f32_e32 v57, v56
	s_nop 0
	v_fma_f32 v60, -v56, v57, 1.0
	v_fmac_f32_e32 v57, v60, v57
	v_div_scale_f32 v60, vcc, v58, v55, v58
	v_mul_f32_e32 v61, v60, v57
	v_fma_f32 v62, -v56, v61, v60
	v_fmac_f32_e32 v61, v62, v57
	v_fma_f32 v56, -v56, v61, v60
	v_div_fmas_f32 v56, v56, v57, v61
	v_div_fixup_f32 v55, v56, v55, v58
	v_div_scale_f32 v56, s[10:11], v54, v54, v59
	v_rcp_f32_e32 v57, v56
	s_nop 0
	v_fma_f32 v58, -v56, v57, 1.0
	v_fmac_f32_e32 v57, v58, v57
	v_div_scale_f32 v58, vcc, v59, v54, v59
	v_mul_f32_e32 v60, v58, v57
	v_fma_f32 v61, -v56, v60, v58
	v_fmac_f32_e32 v60, v61, v57
	v_fma_f32 v56, -v56, v60, v58
	v_div_fmas_f32 v56, v56, v57, v60
	v_div_fixup_f32 v54, v56, v54, v59
	v_pk_mul_f32 v[52:53], v[54:55], v[52:53]
	s_nop 0
	v_cvt_pk_bf16_f32 v51, v52, v53
	global_store_dwordx2 v[48:49], v[50:51], off offset:48
	v_mov_b32_e32 v54, v104
	v_mov_b32_e32 v55, v105
	s_nop 0
	v_mov_b32_e32 v50, v152
	v_mov_b32_e32 v51, v153
	v_mov_b32_e32 v52, v154
	v_mov_b32_e32 v53, v155
	s_waitcnt lgkmcnt(0)
; DI float bf2f(bfr v) { return __uint_as_float(((unsigned)v) << 16); }
; DI unsigned pk2(float a, float b) { f2_t v = {a, b}; bf2_t r = __builtin_convertvector(v, bf2_t); return __builtin_bit_cast(unsigned, r); }
; DI float siluf_(float x) { return x / (1.f + __expf(-x)); }
; DI void attn_unit(const Params& p, int l, int unit, unsigned char* smem) {
;     ...
; #pragma unroll
;   for (int dvb = 0; dvb < 4; ++dvb)
; #pragma unroll
;     for (int g = 0; g < 4; ++g) {
;       const int dv = 32 * dvb + 8 * g + 4 * h;
;       const s16x4 z4 = *(const s16x4*)(P + rowq * PLD + C_DAZ + hd * 128 + dv);
;       const f32x4 gn = *(const f32x4*)(p.da_norm + l * 128 + dv);
;       float y[4];
;       for (int q = 0; q < 4; ++q) y[q] = oacc[dvb][4 * g + q] * rs * gn[q] * siluf_(bf2f((bfr)z4[q]));
;       u32x2 w; w[0] = pk2(y[0], y[1]); w[1] = pk2(y[2], y[3]);
;       *(u32x2*)(YS + rowq * DM + 1536 + hd * 128 + dv) = w;
	v_and_b32_e32 v58, 0xffff0000, v54
	v_lshlrev_b32_e32 v54, 16, v54
	v_mul_f32_e32 v56, 0xbfb8aa3b, v54
	v_pk_mul_f32 v[32:33], v[50:51], v[32:33]
	v_mul_f32_e32 v50, 0xbfb8aa3b, v58
	v_exp_f32_e32 v56, v56
	v_exp_f32_e32 v57, v50
	v_pk_mul_f32 v[34:35], v[52:53], v[34:35]
	v_pk_add_f32 v[50:51], v[56:57], 1.0 op_sel_hi:[1,0]
	s_nop 0
	v_div_scale_f32 v56, s[10:11], v51, v51, v58
	v_rcp_f32_e32 v57, v56
	s_nop 0
	v_fma_f32 v59, -v56, v57, 1.0
	v_fmac_f32_e32 v57, v59, v57
	v_div_scale_f32 v59, vcc, v58, v51, v58
	v_mul_f32_e32 v60, v59, v57
	v_fma_f32 v61, -v56, v60, v59
	v_fmac_f32_e32 v60, v61, v57
	v_fma_f32 v56, -v56, v60, v59
	v_div_fmas_f32 v56, v56, v57, v60
	v_div_fixup_f32 v51, v56, v51, v58
	v_div_scale_f32 v56, s[10:11], v50, v50, v54
	v_rcp_f32_e32 v57, v56
	s_nop 0
	v_fma_f32 v58, -v56, v57, 1.0
	v_fmac_f32_e32 v57, v58, v57
	v_div_scale_f32 v58, vcc, v54, v50, v54
	v_mul_f32_e32 v59, v58, v57
	v_fma_f32 v60, -v56, v59, v58
	v_fmac_f32_e32 v59, v60, v57
	v_fma_f32 v56, -v56, v59, v58
	v_div_fmas_f32 v56, v56, v57, v59
	v_div_fixup_f32 v50, v56, v50, v54
	v_and_b32_e32 v54, 0xffff0000, v55
	v_lshlrev_b32_e32 v55, 16, v55
	v_pk_mul_f32 v[32:33], v[50:51], v[32:33]
	v_mul_f32_e32 v50, 0xbfb8aa3b, v55
	v_mul_f32_e32 v51, 0xbfb8aa3b, v54
	v_exp_f32_e32 v50, v50
	v_exp_f32_e32 v51, v51
	v_cvt_pk_bf16_f32 v32, v32, v33
	v_pk_add_f32 v[50:51], v[50:51], 1.0 op_sel_hi:[1,0]
	s_nop 0
	v_div_scale_f32 v52, s[10:11], v51, v51, v54
	v_rcp_f32_e32 v53, v52
	s_nop 0
	v_fma_f32 v56, -v52, v53, 1.0
	v_fmac_f32_e32 v53, v56, v53
	v_div_scale_f32 v56, vcc, v54, v51, v54
	v_mul_f32_e32 v57, v56, v53
	v_fma_f32 v58, -v52, v57, v56
	v_fmac_f32_e32 v57, v58, v53
	v_fma_f32 v52, -v52, v57, v56
	v_div_fmas_f32 v52, v52, v53, v57
	v_div_fixup_f32 v51, v52, v51, v54
	v_div_scale_f32 v52, s[10:11], v50, v50, v55
	v_rcp_f32_e32 v53, v52
	s_nop 0
	v_fma_f32 v54, -v52, v53, 1.0
	v_fmac_f32_e32 v53, v54, v53
	v_div_scale_f32 v54, vcc, v55, v50, v55
	v_mul_f32_e32 v56, v54, v53
	v_fma_f32 v57, -v52, v56, v54
	v_fmac_f32_e32 v56, v57, v53
	v_fma_f32 v52, -v52, v56, v54
	v_div_fmas_f32 v52, v52, v53, v56
	v_div_fixup_f32 v50, v52, v50, v55
	v_pk_mul_f32 v[34:35], v[50:51], v[34:35]
	s_nop 0
	v_cvt_pk_bf16_f32 v33, v34, v35
	global_store_dwordx2 v[48:49], v[32:33], off offset:64
	v_mov_b32_e32 v50, v106
	v_mov_b32_e32 v51, v107
	s_nop 0
	v_mov_b32_e32 v32, v156
	v_mov_b32_e32 v33, v157
	v_mov_b32_e32 v34, v158
	v_mov_b32_e32 v35, v159
	s_waitcnt lgkmcnt(0)
	v_and_b32_e32 v54, 0xffff0000, v50
	v_lshlrev_b32_e32 v50, 16, v50
	v_mul_f32_e32 v52, 0xbfb8aa3b, v50
	v_pk_mul_f32 v[32:33], v[32:33], v[36:37]
	v_mul_f32_e32 v36, 0xbfb8aa3b, v54
	v_exp_f32_e32 v52, v52
	v_exp_f32_e32 v53, v36
	v_pk_mul_f32 v[34:35], v[34:35], v[38:39]
	v_pk_add_f32 v[36:37], v[52:53], 1.0 op_sel_hi:[1,0]
	s_nop 0
	v_div_scale_f32 v52, s[10:11], v37, v37, v54
	v_rcp_f32_e32 v53, v52
	s_nop 0
	v_fma_f32 v55, -v52, v53, 1.0
	v_fmac_f32_e32 v53, v55, v53
	v_div_scale_f32 v55, vcc, v54, v37, v54
	v_mul_f32_e32 v56, v55, v53
	v_fma_f32 v57, -v52, v56, v55
	v_fmac_f32_e32 v56, v57, v53
	v_fma_f32 v52, -v52, v56, v55
	v_div_fmas_f32 v52, v52, v53, v56
	v_div_fixup_f32 v37, v52, v37, v54
	v_div_scale_f32 v52, s[10:11], v36, v36, v50
	v_rcp_f32_e32 v53, v52
	s_nop 0
	v_fma_f32 v54, -v52, v53, 1.0
	v_fmac_f32_e32 v53, v54, v53
	v_div_scale_f32 v54, vcc, v50, v36, v50
	v_mul_f32_e32 v55, v54, v53
	v_fma_f32 v56, -v52, v55, v54
	v_fmac_f32_e32 v55, v56, v53
	v_fma_f32 v52, -v52, v55, v54
	v_div_fmas_f32 v52, v52, v53, v55
	v_div_fixup_f32 v36, v52, v36, v50
	v_and_b32_e32 v50, 0xffff0000, v51
	v_lshlrev_b32_e32 v51, 16, v51
	v_pk_mul_f32 v[32:33], v[36:37], v[32:33]
	v_mul_f32_e32 v36, 0xbfb8aa3b, v51
	v_mul_f32_e32 v37, 0xbfb8aa3b, v50
	v_exp_f32_e32 v36, v36
	v_exp_f32_e32 v37, v37
	v_cvt_pk_bf16_f32 v32, v32, v33
	v_pk_add_f32 v[36:37], v[36:37], 1.0 op_sel_hi:[1,0]
	s_nop 0
	v_div_scale_f32 v38, s[10:11], v37, v37, v50
	v_rcp_f32_e32 v39, v38
	s_nop 0
	v_fma_f32 v52, -v38, v39, 1.0
	v_fmac_f32_e32 v39, v52, v39
	v_div_scale_f32 v52, vcc, v50, v37, v50
	v_mul_f32_e32 v53, v52, v39
	v_fma_f32 v54, -v38, v53, v52
	v_fmac_f32_e32 v53, v54, v39
	v_fma_f32 v38, -v38, v53, v52
	v_div_fmas_f32 v38, v38, v39, v53
	v_div_fixup_f32 v37, v38, v37, v50
	v_div_scale_f32 v38, s[10:11], v36, v36, v51
	v_rcp_f32_e32 v39, v38
	s_nop 0
	v_fma_f32 v50, -v38, v39, 1.0
	v_fmac_f32_e32 v39, v50, v39
	v_div_scale_f32 v50, vcc, v51, v36, v51
	v_mul_f32_e32 v52, v50, v39
	v_fma_f32 v53, -v38, v52, v50
	v_fmac_f32_e32 v52, v53, v39
	v_fma_f32 v38, -v38, v52, v50
	v_div_fmas_f32 v38, v38, v39, v52
	v_div_fixup_f32 v36, v38, v36, v51
	v_pk_mul_f32 v[34:35], v[36:37], v[34:35]
	s_nop 0
	v_cvt_pk_bf16_f32 v33, v34, v35
	global_store_dwordx2 v[48:49], v[32:33], off offset:80
	v_mov_b32_e32 v36, v108
	v_mov_b32_e32 v37, v109
	s_nop 0
	v_mov_b32_e32 v32, v160
	v_mov_b32_e32 v33, v161
	v_mov_b32_e32 v34, v162
	v_mov_b32_e32 v35, v163
	s_waitcnt lgkmcnt(0)
; DI float bf2f(bfr v) { return __uint_as_float(((unsigned)v) << 16); }
; DI unsigned pk2(float a, float b) { f2_t v = {a, b}; bf2_t r = __builtin_convertvector(v, bf2_t); return __builtin_bit_cast(unsigned, r); }
; DI float siluf_(float x) { return x / (1.f + __expf(-x)); }
; DI void attn_unit(const Params& p, int l, int unit, unsigned char* smem) {
;     ...
; #pragma unroll
;   for (int dvb = 0; dvb < 4; ++dvb)
; #pragma unroll
;     for (int g = 0; g < 4; ++g) {
;       const int dv = 32 * dvb + 8 * g + 4 * h;
;       const s16x4 z4 = *(const s16x4*)(P + rowq * PLD + C_DAZ + hd * 128 + dv);
;       const f32x4 gn = *(const f32x4*)(p.da_norm + l * 128 + dv);
;       float y[4];
;       for (int q = 0; q < 4; ++q) y[q] = oacc[dvb][4 * g + q] * rs * gn[q] * siluf_(bf2f((bfr)z4[q]));
;       u32x2 w; w[0] = pk2(y[0], y[1]); w[1] = pk2(y[2], y[3]);
;       *(u32x2*)(YS + rowq * DM + 1536 + hd * 128 + dv) = w;
	v_and_b32_e32 v50, 0xffff0000, v36
	v_lshlrev_b32_e32 v36, 16, v36
	v_mul_f32_e32 v38, 0xbfb8aa3b, v36
	v_mul_f32_e32 v39, 0xbfb8aa3b, v50
	v_exp_f32_e32 v38, v38
	v_exp_f32_e32 v39, v39
	v_pk_mul_f32 v[32:33], v[32:33], v[40:41]
	v_pk_add_f32 v[38:39], v[38:39], 1.0 op_sel_hi:[1,0]
	s_nop 0
	v_div_scale_f32 v40, s[10:11], v39, v39, v50
	v_rcp_f32_e32 v41, v40
	s_nop 0
	v_fma_f32 v51, -v40, v41, 1.0
	v_fmac_f32_e32 v41, v51, v41
	v_div_scale_f32 v51, vcc, v50, v39, v50
	v_mul_f32_e32 v52, v51, v41
	v_fma_f32 v53, -v40, v52, v51
	v_fmac_f32_e32 v52, v53, v41
	v_fma_f32 v40, -v40, v52, v51
	v_div_fmas_f32 v40, v40, v41, v52
	v_div_fixup_f32 v39, v40, v39, v50
	v_div_scale_f32 v40, s[10:11], v38, v38, v36
	v_rcp_f32_e32 v41, v40
	s_nop 0
	v_fma_f32 v50, -v40, v41, 1.0
	v_fmac_f32_e32 v41, v50, v41
	v_div_scale_f32 v50, vcc, v36, v38, v36
	v_mul_f32_e32 v51, v50, v41
	v_fma_f32 v52, -v40, v51, v50
	v_fmac_f32_e32 v51, v52, v41
	v_fma_f32 v40, -v40, v51, v50
	v_div_fmas_f32 v40, v40, v41, v51
	v_div_fixup_f32 v38, v40, v38, v36
	v_and_b32_e32 v40, 0xffff0000, v37
	v_lshlrev_b32_e32 v41, 16, v37
	v_mul_f32_e32 v36, 0xbfb8aa3b, v41
	v_mul_f32_e32 v37, 0xbfb8aa3b, v40
	v_exp_f32_e32 v36, v36
	v_exp_f32_e32 v37, v37
	v_pk_mul_f32 v[32:33], v[38:39], v[32:33]
	v_pk_mul_f32 v[38:39], v[42:43], v[64:65] op_sel_hi:[1,0]
	v_cvt_pk_bf16_f32 v32, v32, v33
	v_pk_add_f32 v[36:37], v[36:37], 1.0 op_sel_hi:[1,0]
	v_pk_mul_f32 v[34:35], v[34:35], v[38:39]
	v_div_scale_f32 v38, s[10:11], v37, v37, v40
	v_rcp_f32_e32 v39, v38
	s_nop 0
	v_fma_f32 v42, -v38, v39, 1.0
	v_fmac_f32_e32 v39, v42, v39
	v_div_scale_f32 v42, vcc, v40, v37, v40
	v_mul_f32_e32 v43, v42, v39
	v_fma_f32 v50, -v38, v43, v42
	v_fmac_f32_e32 v43, v50, v39
	v_fma_f32 v38, -v38, v43, v42
	v_div_fmas_f32 v38, v38, v39, v43
	v_div_fixup_f32 v37, v38, v37, v40
	v_div_scale_f32 v38, s[10:11], v36, v36, v41
	v_rcp_f32_e32 v39, v38
	s_nop 0
	v_fma_f32 v40, -v38, v39, 1.0
	v_fmac_f32_e32 v39, v40, v39
	v_div_scale_f32 v40, vcc, v41, v36, v41
	v_mul_f32_e32 v42, v40, v39
	v_fma_f32 v43, -v38, v42, v40
	v_fmac_f32_e32 v42, v43, v39
	v_fma_f32 v38, -v38, v42, v40
	v_div_fmas_f32 v38, v38, v39, v42
	v_div_fixup_f32 v36, v38, v36, v41
	v_pk_mul_f32 v[34:35], v[36:37], v[34:35]
	v_pk_mul_f32 v[40:41], v[44:45], v[64:65] op_sel_hi:[1,0]
	v_cvt_pk_bf16_f32 v33, v34, v35
	global_store_dwordx2 v[48:49], v[32:33], off offset:96
	v_mov_b32_e32 v36, v110
	v_mov_b32_e32 v37, v111
	s_nop 0
	v_mov_b32_e32 v32, v164
	v_mov_b32_e32 v33, v165
	v_mov_b32_e32 v34, v166
	v_mov_b32_e32 v35, v167
	s_waitcnt lgkmcnt(0)
	v_and_b32_e32 v42, 0xffff0000, v36
	v_lshlrev_b32_e32 v36, 16, v36
	v_mul_f32_e32 v38, 0xbfb8aa3b, v36
	v_mul_f32_e32 v39, 0xbfb8aa3b, v42
	v_exp_f32_e32 v38, v38
	v_exp_f32_e32 v39, v39
	v_pk_mul_f32 v[32:33], v[32:33], v[40:41]
	v_pk_add_f32 v[38:39], v[38:39], 1.0 op_sel_hi:[1,0]
	s_nop 0
	v_div_scale_f32 v40, s[10:11], v39, v39, v42
	v_rcp_f32_e32 v41, v40
	s_nop 0
	v_fma_f32 v43, -v40, v41, 1.0
	v_fmac_f32_e32 v41, v43, v41
	v_div_scale_f32 v43, vcc, v42, v39, v42
	v_mul_f32_e32 v44, v43, v41
	v_fma_f32 v45, -v40, v44, v43
	v_fmac_f32_e32 v44, v45, v41
	v_fma_f32 v40, -v40, v44, v43
	v_div_fmas_f32 v40, v40, v41, v44
	v_div_fixup_f32 v39, v40, v39, v42
	v_div_scale_f32 v40, s[10:11], v38, v38, v36
	v_rcp_f32_e32 v41, v40
	s_nop 0
	v_fma_f32 v42, -v40, v41, 1.0
	v_fmac_f32_e32 v41, v42, v41
	v_div_scale_f32 v42, vcc, v36, v38, v36
	v_mul_f32_e32 v43, v42, v41
	v_fma_f32 v44, -v40, v43, v42
	v_fmac_f32_e32 v43, v44, v41
	v_fma_f32 v40, -v40, v43, v42
	v_div_fmas_f32 v40, v40, v41, v43
	v_div_fixup_f32 v38, v40, v38, v36
	v_and_b32_e32 v40, 0xffff0000, v37
	v_lshlrev_b32_e32 v41, 16, v37
	v_mul_f32_e32 v36, 0xbfb8aa3b, v41
	v_mul_f32_e32 v37, 0xbfb8aa3b, v40
	v_exp_f32_e32 v36, v36
	v_exp_f32_e32 v37, v37
	v_pk_mul_f32 v[32:33], v[38:39], v[32:33]
	v_pk_mul_f32 v[38:39], v[46:47], v[64:65] op_sel_hi:[1,0]
	v_cvt_pk_bf16_f32 v32, v32, v33
	v_pk_add_f32 v[36:37], v[36:37], 1.0 op_sel_hi:[1,0]
	v_pk_mul_f32 v[34:35], v[34:35], v[38:39]
	v_div_scale_f32 v38, s[10:11], v37, v37, v40
	v_rcp_f32_e32 v39, v38
	s_nop 0
	v_fma_f32 v42, -v38, v39, 1.0
	v_fmac_f32_e32 v39, v42, v39
	v_div_scale_f32 v42, vcc, v40, v37, v40
	v_mul_f32_e32 v43, v42, v39
	v_fma_f32 v44, -v38, v43, v42
	v_fmac_f32_e32 v43, v44, v39
	v_fma_f32 v38, -v38, v43, v42
	v_div_fmas_f32 v38, v38, v39, v43
	v_div_fixup_f32 v37, v38, v37, v40
	v_div_scale_f32 v38, s[10:11], v36, v36, v41
	v_rcp_f32_e32 v39, v38
	s_nop 0
	v_fma_f32 v40, -v38, v39, 1.0
	v_fmac_f32_e32 v39, v40, v39
	v_div_scale_f32 v40, vcc, v41, v36, v41
	v_mul_f32_e32 v42, v40, v39
	v_fma_f32 v43, -v38, v42, v40
	v_fmac_f32_e32 v42, v43, v39
	v_fma_f32 v38, -v38, v42, v40
	v_div_fmas_f32 v38, v38, v39, v42
	v_div_fixup_f32 v36, v38, v36, v41
	v_pk_mul_f32 v[34:35], v[36:37], v[34:35]
	s_nop 0
	v_cvt_pk_bf16_f32 v33, v34, v35
	global_store_dwordx2 v[48:49], v[32:33], off offset:112
	v_mov_b32_e32 v36, v112
	v_mov_b32_e32 v37, v113
	s_nop 0
	v_mov_b32_e32 v32, v168
	v_mov_b32_e32 v33, v169
	v_mov_b32_e32 v34, v170
	v_mov_b32_e32 v35, v171
	s_waitcnt lgkmcnt(0)
; DI float bf2f(bfr v) { return __uint_as_float(((unsigned)v) << 16); }
; DI unsigned pk2(float a, float b) { f2_t v = {a, b}; bf2_t r = __builtin_convertvector(v, bf2_t); return __builtin_bit_cast(unsigned, r); }
; DI float siluf_(float x) { return x / (1.f + __expf(-x)); }
; DI void attn_unit(const Params& p, int l, int unit, unsigned char* smem) {
;     ...
; #pragma unroll
;   for (int dvb = 0; dvb < 4; ++dvb)
; #pragma unroll
;     for (int g = 0; g < 4; ++g) {
;       const int dv = 32 * dvb + 8 * g + 4 * h;
;       const s16x4 z4 = *(const s16x4*)(P + rowq * PLD + C_DAZ + hd * 128 + dv);
;       const f32x4 gn = *(const f32x4*)(p.da_norm + l * 128 + dv);
;       float y[4];
;       for (int q = 0; q < 4; ++q) y[q] = oacc[dvb][4 * g + q] * rs * gn[q] * siluf_(bf2f((bfr)z4[q]));
;       u32x2 w; w[0] = pk2(y[0], y[1]); w[1] = pk2(y[2], y[3]);
;       *(u32x2*)(YS + rowq * DM + 1536 + hd * 128 + dv) = w;
	v_and_b32_e32 v40, 0xffff0000, v36
	v_lshlrev_b32_e32 v36, 16, v36
	v_mul_f32_e32 v38, 0xbfb8aa3b, v36
	v_pk_mul_f32 v[16:17], v[32:33], v[16:17]
	v_mul_f32_e32 v32, 0xbfb8aa3b, v40
	v_exp_f32_e32 v38, v38
	v_exp_f32_e32 v39, v32
	v_pk_mul_f32 v[18:19], v[34:35], v[18:19]
	v_pk_add_f32 v[32:33], v[38:39], 1.0 op_sel_hi:[1,0]
	s_nop 0
	v_div_scale_f32 v38, s[10:11], v33, v33, v40
	v_rcp_f32_e32 v39, v38
	s_nop 0
	v_fma_f32 v41, -v38, v39, 1.0
	v_fmac_f32_e32 v39, v41, v39
	v_div_scale_f32 v41, vcc, v40, v33, v40
	v_mul_f32_e32 v42, v41, v39
	v_fma_f32 v43, -v38, v42, v41
	v_fmac_f32_e32 v42, v43, v39
	v_fma_f32 v38, -v38, v42, v41
	v_div_fmas_f32 v38, v38, v39, v42
	v_div_fixup_f32 v33, v38, v33, v40
	v_div_scale_f32 v38, s[10:11], v32, v32, v36
	v_rcp_f32_e32 v39, v38
	s_nop 0
	v_fma_f32 v40, -v38, v39, 1.0
	v_fmac_f32_e32 v39, v40, v39
	v_div_scale_f32 v40, vcc, v36, v32, v36
	v_mul_f32_e32 v41, v40, v39
	v_fma_f32 v42, -v38, v41, v40
	v_fmac_f32_e32 v41, v42, v39
	v_fma_f32 v38, -v38, v41, v40
	v_div_fmas_f32 v38, v38, v39, v41
	v_div_fixup_f32 v32, v38, v32, v36
	v_and_b32_e32 v36, 0xffff0000, v37
	v_lshlrev_b32_e32 v37, 16, v37
	v_pk_mul_f32 v[16:17], v[32:33], v[16:17]
	v_mul_f32_e32 v32, 0xbfb8aa3b, v37
	v_mul_f32_e32 v33, 0xbfb8aa3b, v36
	v_exp_f32_e32 v32, v32
	v_exp_f32_e32 v33, v33
	v_cvt_pk_bf16_f32 v16, v16, v17
	v_pk_add_f32 v[32:33], v[32:33], 1.0 op_sel_hi:[1,0]
	s_nop 0
	v_div_scale_f32 v34, s[10:11], v33, v33, v36
	v_rcp_f32_e32 v35, v34
	s_nop 0
	v_fma_f32 v38, -v34, v35, 1.0
	v_fmac_f32_e32 v35, v38, v35
	v_div_scale_f32 v38, vcc, v36, v33, v36
	v_mul_f32_e32 v39, v38, v35
	v_fma_f32 v40, -v34, v39, v38
	v_fmac_f32_e32 v39, v40, v35
	v_fma_f32 v34, -v34, v39, v38
	v_div_fmas_f32 v34, v34, v35, v39
	v_div_fixup_f32 v33, v34, v33, v36
	v_div_scale_f32 v34, s[10:11], v32, v32, v37
	v_rcp_f32_e32 v35, v34
	s_nop 0
	v_fma_f32 v36, -v34, v35, 1.0
	v_fmac_f32_e32 v35, v36, v35
	v_div_scale_f32 v36, vcc, v37, v32, v37
	v_mul_f32_e32 v38, v36, v35
	v_fma_f32 v39, -v34, v38, v36
	v_fmac_f32_e32 v38, v39, v35
	v_fma_f32 v34, -v34, v38, v36
	v_div_fmas_f32 v34, v34, v35, v38
	v_div_fixup_f32 v32, v34, v32, v37
	v_pk_mul_f32 v[18:19], v[32:33], v[18:19]
	s_nop 0
	v_cvt_pk_bf16_f32 v17, v18, v19
	global_store_dwordx2 v[48:49], v[16:17], off offset:128
	v_mov_b32_e32 v32, v114
	v_mov_b32_e32 v33, v115
	s_nop 0
	v_mov_b32_e32 v16, v172
	v_mov_b32_e32 v17, v173
	v_mov_b32_e32 v18, v174
	v_mov_b32_e32 v19, v175
	s_waitcnt lgkmcnt(0)
	v_and_b32_e32 v36, 0xffff0000, v32
	v_lshlrev_b32_e32 v32, 16, v32
	v_mul_f32_e32 v34, 0xbfb8aa3b, v32
	v_pk_mul_f32 v[16:17], v[16:17], v[20:21]
	v_mul_f32_e32 v20, 0xbfb8aa3b, v36
	v_exp_f32_e32 v34, v34
	v_exp_f32_e32 v35, v20
	v_pk_mul_f32 v[18:19], v[18:19], v[22:23]
	v_pk_add_f32 v[20:21], v[34:35], 1.0 op_sel_hi:[1,0]
	s_nop 0
	v_div_scale_f32 v34, s[10:11], v21, v21, v36
	v_rcp_f32_e32 v35, v34
	s_nop 0
	v_fma_f32 v37, -v34, v35, 1.0
	v_fmac_f32_e32 v35, v37, v35
	v_div_scale_f32 v37, vcc, v36, v21, v36
	v_mul_f32_e32 v38, v37, v35
	v_fma_f32 v39, -v34, v38, v37
	v_fmac_f32_e32 v38, v39, v35
	v_fma_f32 v34, -v34, v38, v37
	v_div_fmas_f32 v34, v34, v35, v38
	v_div_fixup_f32 v21, v34, v21, v36
	v_div_scale_f32 v34, s[10:11], v20, v20, v32
	v_rcp_f32_e32 v35, v34
	s_nop 0
	v_fma_f32 v36, -v34, v35, 1.0
	v_fmac_f32_e32 v35, v36, v35
	v_div_scale_f32 v36, vcc, v32, v20, v32
	v_mul_f32_e32 v37, v36, v35
	v_fma_f32 v38, -v34, v37, v36
	v_fmac_f32_e32 v37, v38, v35
	v_fma_f32 v34, -v34, v37, v36
	v_div_fmas_f32 v34, v34, v35, v37
	v_div_fixup_f32 v20, v34, v20, v32
	v_and_b32_e32 v32, 0xffff0000, v33
	v_lshlrev_b32_e32 v33, 16, v33
	v_pk_mul_f32 v[16:17], v[20:21], v[16:17]
	v_mul_f32_e32 v20, 0xbfb8aa3b, v33
	v_mul_f32_e32 v21, 0xbfb8aa3b, v32
	v_exp_f32_e32 v20, v20
	v_exp_f32_e32 v21, v21
	v_cvt_pk_bf16_f32 v16, v16, v17
	v_pk_add_f32 v[20:21], v[20:21], 1.0 op_sel_hi:[1,0]
	s_nop 0
	v_div_scale_f32 v22, s[10:11], v21, v21, v32
	v_rcp_f32_e32 v23, v22
	s_nop 0
	v_fma_f32 v34, -v22, v23, 1.0
	v_fmac_f32_e32 v23, v34, v23
	v_div_scale_f32 v34, vcc, v32, v21, v32
	v_mul_f32_e32 v35, v34, v23
	v_fma_f32 v36, -v22, v35, v34
	v_fmac_f32_e32 v35, v36, v23
	v_fma_f32 v22, -v22, v35, v34
	v_div_fmas_f32 v22, v22, v23, v35
	v_div_fixup_f32 v21, v22, v21, v32
	v_div_scale_f32 v22, s[10:11], v20, v20, v33
	v_rcp_f32_e32 v23, v22
	s_nop 0
	v_fma_f32 v32, -v22, v23, 1.0
	v_fmac_f32_e32 v23, v32, v23
	v_div_scale_f32 v32, vcc, v33, v20, v33
	v_mul_f32_e32 v34, v32, v23
	v_fma_f32 v35, -v22, v34, v32
	v_fmac_f32_e32 v34, v35, v23
	v_fma_f32 v22, -v22, v34, v32
	v_div_fmas_f32 v22, v22, v23, v34
	v_div_fixup_f32 v20, v22, v20, v33
	v_pk_mul_f32 v[18:19], v[20:21], v[18:19]
	s_nop 0
	v_cvt_pk_bf16_f32 v17, v18, v19
	global_store_dwordx2 v[48:49], v[16:17], off offset:144
	v_mov_b32_e32 v20, v82
	v_mov_b32_e32 v21, v83
	s_nop 0
	v_mov_b32_e32 v16, v176
	v_mov_b32_e32 v17, v177
	v_mov_b32_e32 v18, v178
	v_mov_b32_e32 v19, v179
	s_waitcnt lgkmcnt(0)
; DI float bf2f(bfr v) { return __uint_as_float(((unsigned)v) << 16); }
; DI unsigned pk2(float a, float b) { f2_t v = {a, b}; bf2_t r = __builtin_convertvector(v, bf2_t); return __builtin_bit_cast(unsigned, r); }
; DI float siluf_(float x) { return x / (1.f + __expf(-x)); }
; DI void attn_unit(const Params& p, int l, int unit, unsigned char* smem) {
;     ...
; #pragma unroll
;   for (int dvb = 0; dvb < 4; ++dvb)
; #pragma unroll
;     for (int g = 0; g < 4; ++g) {
;       const int dv = 32 * dvb + 8 * g + 4 * h;
;       const s16x4 z4 = *(const s16x4*)(P + rowq * PLD + C_DAZ + hd * 128 + dv);
;       const f32x4 gn = *(const f32x4*)(p.da_norm + l * 128 + dv);
;       float y[4];
;       for (int q = 0; q < 4; ++q) y[q] = oacc[dvb][4 * g + q] * rs * gn[q] * siluf_(bf2f((bfr)z4[q]));
;       u32x2 w; w[0] = pk2(y[0], y[1]); w[1] = pk2(y[2], y[3]);
;       *(u32x2*)(YS + rowq * DM + 1536 + hd * 128 + dv) = w;
	v_and_b32_e32 v32, 0xffff0000, v20
	v_lshlrev_b32_e32 v20, 16, v20
	v_mul_f32_e32 v22, 0xbfb8aa3b, v20
	v_mul_f32_e32 v23, 0xbfb8aa3b, v32
	v_exp_f32_e32 v22, v22
	v_exp_f32_e32 v23, v23
	v_pk_mul_f32 v[16:17], v[16:17], v[24:25]
	v_pk_add_f32 v[22:23], v[22:23], 1.0 op_sel_hi:[1,0]
	s_nop 0
	v_div_scale_f32 v24, s[10:11], v23, v23, v32
	v_rcp_f32_e32 v25, v24
	s_nop 0
	v_fma_f32 v33, -v24, v25, 1.0
	v_fmac_f32_e32 v25, v33, v25
	v_div_scale_f32 v33, vcc, v32, v23, v32
	v_mul_f32_e32 v34, v33, v25
	v_fma_f32 v35, -v24, v34, v33
	v_fmac_f32_e32 v34, v35, v25
	v_fma_f32 v24, -v24, v34, v33
	v_div_fmas_f32 v24, v24, v25, v34
	v_div_fixup_f32 v23, v24, v23, v32
	v_div_scale_f32 v24, s[10:11], v22, v22, v20
	v_rcp_f32_e32 v25, v24
	s_nop 0
	v_fma_f32 v32, -v24, v25, 1.0
	v_fmac_f32_e32 v25, v32, v25
	v_div_scale_f32 v32, vcc, v20, v22, v20
	v_mul_f32_e32 v33, v32, v25
	v_fma_f32 v34, -v24, v33, v32
	v_fmac_f32_e32 v33, v34, v25
	v_fma_f32 v24, -v24, v33, v32
	v_div_fmas_f32 v24, v24, v25, v33
	v_div_fixup_f32 v22, v24, v22, v20
	v_and_b32_e32 v24, 0xffff0000, v21
	v_lshlrev_b32_e32 v25, 16, v21
	v_mul_f32_e32 v20, 0xbfb8aa3b, v25
	v_mul_f32_e32 v21, 0xbfb8aa3b, v24
	v_exp_f32_e32 v20, v20
	v_exp_f32_e32 v21, v21
	v_pk_mul_f32 v[16:17], v[22:23], v[16:17]
	v_pk_mul_f32 v[22:23], v[26:27], v[64:65] op_sel_hi:[1,0]
	v_cvt_pk_bf16_f32 v16, v16, v17
	v_pk_add_f32 v[20:21], v[20:21], 1.0 op_sel_hi:[1,0]
	v_pk_mul_f32 v[18:19], v[18:19], v[22:23]
	v_div_scale_f32 v22, s[10:11], v21, v21, v24
	v_rcp_f32_e32 v23, v22
	s_nop 0
	v_fma_f32 v26, -v22, v23, 1.0
	v_fmac_f32_e32 v23, v26, v23
	v_div_scale_f32 v26, vcc, v24, v21, v24
	v_mul_f32_e32 v27, v26, v23
	v_fma_f32 v32, -v22, v27, v26
	v_fmac_f32_e32 v27, v32, v23
	v_fma_f32 v22, -v22, v27, v26
	v_div_fmas_f32 v22, v22, v23, v27
	v_div_fixup_f32 v21, v22, v21, v24
	v_div_scale_f32 v22, s[10:11], v20, v20, v25
	v_rcp_f32_e32 v23, v22
	s_nop 0
	v_fma_f32 v24, -v22, v23, 1.0
	v_fmac_f32_e32 v23, v24, v23
	v_div_scale_f32 v24, vcc, v25, v20, v25
	v_mul_f32_e32 v26, v24, v23
	v_fma_f32 v27, -v22, v26, v24
	v_fmac_f32_e32 v26, v27, v23
	v_fma_f32 v22, -v22, v26, v24
	v_div_fmas_f32 v22, v22, v23, v26
	v_div_fixup_f32 v20, v22, v20, v25
	v_pk_mul_f32 v[18:19], v[20:21], v[18:19]
	v_pk_mul_f32 v[24:25], v[28:29], v[64:65] op_sel_hi:[1,0]
	v_cvt_pk_bf16_f32 v17, v18, v19
	global_store_dwordx2 v[48:49], v[16:17], off offset:160
	v_mov_b32_e32 v20, v84
	v_mov_b32_e32 v21, v85
	s_nop 0
	v_mov_b32_e32 v16, v180
	v_mov_b32_e32 v17, v181
	v_mov_b32_e32 v18, v182
	v_mov_b32_e32 v19, v183
	s_waitcnt lgkmcnt(0)
	v_and_b32_e32 v26, 0xffff0000, v20
	v_lshlrev_b32_e32 v20, 16, v20
	v_mul_f32_e32 v22, 0xbfb8aa3b, v20
	v_mul_f32_e32 v23, 0xbfb8aa3b, v26
	v_exp_f32_e32 v22, v22
	v_exp_f32_e32 v23, v23
	v_pk_mul_f32 v[16:17], v[16:17], v[24:25]
	v_pk_add_f32 v[22:23], v[22:23], 1.0 op_sel_hi:[1,0]
	s_nop 0
	v_div_scale_f32 v24, s[10:11], v23, v23, v26
	v_rcp_f32_e32 v25, v24
	s_nop 0
	v_fma_f32 v27, -v24, v25, 1.0
	v_fmac_f32_e32 v25, v27, v25
	v_div_scale_f32 v27, vcc, v26, v23, v26
	v_mul_f32_e32 v28, v27, v25
	v_fma_f32 v29, -v24, v28, v27
	v_fmac_f32_e32 v28, v29, v25
	v_fma_f32 v24, -v24, v28, v27
	v_div_fmas_f32 v24, v24, v25, v28
	v_div_fixup_f32 v23, v24, v23, v26
	v_div_scale_f32 v24, s[10:11], v22, v22, v20
	v_rcp_f32_e32 v25, v24
	s_nop 0
	v_fma_f32 v26, -v24, v25, 1.0
	v_fmac_f32_e32 v25, v26, v25
	v_div_scale_f32 v26, vcc, v20, v22, v20
	v_mul_f32_e32 v27, v26, v25
	v_fma_f32 v28, -v24, v27, v26
	v_fmac_f32_e32 v27, v28, v25
	v_fma_f32 v24, -v24, v27, v26
	v_div_fmas_f32 v24, v24, v25, v27
	v_div_fixup_f32 v22, v24, v22, v20
	v_and_b32_e32 v24, 0xffff0000, v21
	v_lshlrev_b32_e32 v25, 16, v21
	v_mul_f32_e32 v20, 0xbfb8aa3b, v25
	v_mul_f32_e32 v21, 0xbfb8aa3b, v24
	v_exp_f32_e32 v20, v20
	v_exp_f32_e32 v21, v21
	v_pk_mul_f32 v[16:17], v[22:23], v[16:17]
	v_pk_mul_f32 v[22:23], v[30:31], v[64:65] op_sel_hi:[1,0]
	v_cvt_pk_bf16_f32 v16, v16, v17
	v_pk_add_f32 v[20:21], v[20:21], 1.0 op_sel_hi:[1,0]
	v_pk_mul_f32 v[18:19], v[18:19], v[22:23]
	v_div_scale_f32 v22, s[10:11], v21, v21, v24
	v_rcp_f32_e32 v23, v22
	s_nop 0
	v_fma_f32 v26, -v22, v23, 1.0
	v_fmac_f32_e32 v23, v26, v23
	v_div_scale_f32 v26, vcc, v24, v21, v24
	v_mul_f32_e32 v27, v26, v23
	v_fma_f32 v28, -v22, v27, v26
	v_fmac_f32_e32 v27, v28, v23
	v_fma_f32 v22, -v22, v27, v26
	v_div_fmas_f32 v22, v22, v23, v27
	v_div_fixup_f32 v21, v22, v21, v24
	v_div_scale_f32 v22, s[10:11], v20, v20, v25
	v_rcp_f32_e32 v23, v22
	s_nop 0
	v_fma_f32 v24, -v22, v23, 1.0
	v_fmac_f32_e32 v23, v24, v23
	v_div_scale_f32 v24, vcc, v25, v20, v25
	v_mul_f32_e32 v26, v24, v23
	v_fma_f32 v27, -v22, v26, v24
	v_fmac_f32_e32 v26, v27, v23
	v_fma_f32 v22, -v22, v26, v24
	v_div_fmas_f32 v22, v22, v23, v26
	v_div_fixup_f32 v20, v22, v20, v25
	v_pk_mul_f32 v[18:19], v[20:21], v[18:19]
	s_nop 0
	v_cvt_pk_bf16_f32 v17, v18, v19
	global_store_dwordx2 v[48:49], v[16:17], off offset:176
	v_mov_b32_e32 v20, v86
	v_mov_b32_e32 v21, v87
	s_nop 0
	v_mov_b32_e32 v16, v184
	v_mov_b32_e32 v17, v185
	v_mov_b32_e32 v18, v186
	v_mov_b32_e32 v19, v187
	s_waitcnt lgkmcnt(0)
; DI float bf2f(bfr v) { return __uint_as_float(((unsigned)v) << 16); }
; DI unsigned pk2(float a, float b) { f2_t v = {a, b}; bf2_t r = __builtin_convertvector(v, bf2_t); return __builtin_bit_cast(unsigned, r); }
; DI float siluf_(float x) { return x / (1.f + __expf(-x)); }
; DI void attn_unit(const Params& p, int l, int unit, unsigned char* smem) {
;     ...
; #pragma unroll
;   for (int dvb = 0; dvb < 4; ++dvb)
; #pragma unroll
;     for (int g = 0; g < 4; ++g) {
;       const int dv = 32 * dvb + 8 * g + 4 * h;
;       const s16x4 z4 = *(const s16x4*)(P + rowq * PLD + C_DAZ + hd * 128 + dv);
;       const f32x4 gn = *(const f32x4*)(p.da_norm + l * 128 + dv);
;       float y[4];
;       for (int q = 0; q < 4; ++q) y[q] = oacc[dvb][4 * g + q] * rs * gn[q] * siluf_(bf2f((bfr)z4[q]));
;       u32x2 w; w[0] = pk2(y[0], y[1]); w[1] = pk2(y[2], y[3]);
;       *(u32x2*)(YS + rowq * DM + 1536 + hd * 128 + dv) = w;
	v_and_b32_e32 v24, 0xffff0000, v20
	v_lshlrev_b32_e32 v20, 16, v20
	v_mul_f32_e32 v22, 0xbfb8aa3b, v20
	v_pk_mul_f32 v[0:1], v[16:17], v[0:1]
	v_mul_f32_e32 v16, 0xbfb8aa3b, v24
	v_exp_f32_e32 v22, v22
	v_exp_f32_e32 v23, v16
	v_pk_mul_f32 v[2:3], v[18:19], v[2:3]
	v_pk_add_f32 v[16:17], v[22:23], 1.0 op_sel_hi:[1,0]
	s_nop 0
	v_div_scale_f32 v22, s[10:11], v17, v17, v24
	v_rcp_f32_e32 v23, v22
	s_nop 0
	v_fma_f32 v25, -v22, v23, 1.0
	v_fmac_f32_e32 v23, v25, v23
	v_div_scale_f32 v25, vcc, v24, v17, v24
	v_mul_f32_e32 v26, v25, v23
	v_fma_f32 v27, -v22, v26, v25
	v_fmac_f32_e32 v26, v27, v23
	v_fma_f32 v22, -v22, v26, v25
	v_div_fmas_f32 v22, v22, v23, v26
	v_div_fixup_f32 v17, v22, v17, v24
	v_div_scale_f32 v22, s[10:11], v16, v16, v20
	v_rcp_f32_e32 v23, v22
	s_nop 0
	v_fma_f32 v24, -v22, v23, 1.0
	v_fmac_f32_e32 v23, v24, v23
	v_div_scale_f32 v24, vcc, v20, v16, v20
	v_mul_f32_e32 v25, v24, v23
	v_fma_f32 v26, -v22, v25, v24
	v_fmac_f32_e32 v25, v26, v23
	v_fma_f32 v22, -v22, v25, v24
	v_div_fmas_f32 v22, v22, v23, v25
	v_div_fixup_f32 v16, v22, v16, v20
	v_and_b32_e32 v20, 0xffff0000, v21
	v_lshlrev_b32_e32 v21, 16, v21
	v_pk_mul_f32 v[0:1], v[16:17], v[0:1]
	v_mul_f32_e32 v16, 0xbfb8aa3b, v21
	v_mul_f32_e32 v17, 0xbfb8aa3b, v20
	v_exp_f32_e32 v16, v16
	v_exp_f32_e32 v17, v17
	v_cvt_pk_bf16_f32 v0, v0, v1
	v_pk_add_f32 v[16:17], v[16:17], 1.0 op_sel_hi:[1,0]
	s_nop 0
	v_div_scale_f32 v18, s[10:11], v17, v17, v20
	v_rcp_f32_e32 v19, v18
	s_nop 0
	v_fma_f32 v22, -v18, v19, 1.0
	v_fmac_f32_e32 v19, v22, v19
	v_div_scale_f32 v22, vcc, v20, v17, v20
	v_mul_f32_e32 v23, v22, v19
	v_fma_f32 v24, -v18, v23, v22
	v_fmac_f32_e32 v23, v24, v19
	v_fma_f32 v18, -v18, v23, v22
	v_div_fmas_f32 v18, v18, v19, v23
	v_div_fixup_f32 v17, v18, v17, v20
	v_div_scale_f32 v18, s[10:11], v16, v16, v21
	v_rcp_f32_e32 v19, v18
	s_nop 0
	v_fma_f32 v20, -v18, v19, 1.0
	v_fmac_f32_e32 v19, v20, v19
	v_div_scale_f32 v20, vcc, v21, v16, v21
	v_mul_f32_e32 v22, v20, v19
	v_fma_f32 v23, -v18, v22, v20
	v_fmac_f32_e32 v22, v23, v19
	v_fma_f32 v18, -v18, v22, v20
	v_div_fmas_f32 v18, v18, v19, v22
	v_div_fixup_f32 v16, v18, v16, v21
	v_pk_mul_f32 v[2:3], v[16:17], v[2:3]
	s_nop 0
	v_cvt_pk_bf16_f32 v1, v2, v3
	global_store_dwordx2 v[48:49], v[0:1], off offset:192
	v_mov_b32_e32 v16, v88
	v_mov_b32_e32 v17, v89
	s_nop 0
	v_mov_b32_e32 v0, v188
	v_mov_b32_e32 v1, v189
	v_mov_b32_e32 v2, v190
	v_mov_b32_e32 v3, v191
	s_waitcnt lgkmcnt(0)
	v_and_b32_e32 v20, 0xffff0000, v16
	v_lshlrev_b32_e32 v16, 16, v16
	v_mul_f32_e32 v18, 0xbfb8aa3b, v16
	v_pk_mul_f32 v[0:1], v[0:1], v[4:5]
	v_mul_f32_e32 v4, 0xbfb8aa3b, v20
	v_exp_f32_e32 v18, v18
	v_exp_f32_e32 v19, v4
	v_pk_mul_f32 v[2:3], v[2:3], v[6:7]
	v_pk_add_f32 v[4:5], v[18:19], 1.0 op_sel_hi:[1,0]
	s_nop 0
	v_div_scale_f32 v18, s[10:11], v5, v5, v20
	v_rcp_f32_e32 v19, v18
	s_nop 0
	v_fma_f32 v21, -v18, v19, 1.0
	v_fmac_f32_e32 v19, v21, v19
	v_div_scale_f32 v21, vcc, v20, v5, v20
	v_mul_f32_e32 v22, v21, v19
	v_fma_f32 v23, -v18, v22, v21
	v_fmac_f32_e32 v22, v23, v19
	v_fma_f32 v18, -v18, v22, v21
	v_div_fmas_f32 v18, v18, v19, v22
	v_div_fixup_f32 v5, v18, v5, v20
	v_div_scale_f32 v18, s[10:11], v4, v4, v16
	v_rcp_f32_e32 v19, v18
	s_nop 0
	v_fma_f32 v20, -v18, v19, 1.0
	v_fmac_f32_e32 v19, v20, v19
	v_div_scale_f32 v20, vcc, v16, v4, v16
	v_mul_f32_e32 v21, v20, v19
	v_fma_f32 v22, -v18, v21, v20
	v_fmac_f32_e32 v21, v22, v19
	v_fma_f32 v18, -v18, v21, v20
	v_div_fmas_f32 v18, v18, v19, v21
	v_div_fixup_f32 v4, v18, v4, v16
	v_and_b32_e32 v16, 0xffff0000, v17
	v_lshlrev_b32_e32 v17, 16, v17
	v_pk_mul_f32 v[0:1], v[4:5], v[0:1]
	v_mul_f32_e32 v4, 0xbfb8aa3b, v17
	v_mul_f32_e32 v5, 0xbfb8aa3b, v16
	v_exp_f32_e32 v4, v4
	v_exp_f32_e32 v5, v5
	v_cvt_pk_bf16_f32 v0, v0, v1
	v_pk_add_f32 v[4:5], v[4:5], 1.0 op_sel_hi:[1,0]
	s_nop 0
	v_div_scale_f32 v6, s[10:11], v5, v5, v16
	v_rcp_f32_e32 v7, v6
	s_nop 0
	v_fma_f32 v18, -v6, v7, 1.0
	v_fmac_f32_e32 v7, v18, v7
	v_div_scale_f32 v18, vcc, v16, v5, v16
	v_mul_f32_e32 v19, v18, v7
	v_fma_f32 v20, -v6, v19, v18
	v_fmac_f32_e32 v19, v20, v7
	v_fma_f32 v6, -v6, v19, v18
	v_div_fmas_f32 v6, v6, v7, v19
	v_div_fixup_f32 v5, v6, v5, v16
	v_div_scale_f32 v6, s[10:11], v4, v4, v17
	v_rcp_f32_e32 v7, v6
	s_nop 0
	v_fma_f32 v16, -v6, v7, 1.0
	v_fmac_f32_e32 v7, v16, v7
	v_div_scale_f32 v16, vcc, v17, v4, v17
	v_mul_f32_e32 v18, v16, v7
	v_fma_f32 v19, -v6, v18, v16
	v_fmac_f32_e32 v18, v19, v7
	v_fma_f32 v6, -v6, v18, v16
	v_div_fmas_f32 v6, v6, v7, v18
	v_div_fixup_f32 v4, v6, v4, v17
	v_pk_mul_f32 v[2:3], v[4:5], v[2:3]
	s_nop 0
	v_cvt_pk_bf16_f32 v1, v2, v3
	global_store_dwordx2 v[48:49], v[0:1], off offset:208
	v_mov_b32_e32 v4, v90
	v_mov_b32_e32 v5, v91
	s_nop 0
	v_mov_b32_e32 v0, v192
	v_mov_b32_e32 v1, v193
	v_mov_b32_e32 v2, v194
	v_mov_b32_e32 v3, v195
	s_waitcnt lgkmcnt(0)
; DI float bf2f(bfr v) { return __uint_as_float(((unsigned)v) << 16); }
; DI unsigned pk2(float a, float b) { f2_t v = {a, b}; bf2_t r = __builtin_convertvector(v, bf2_t); return __builtin_bit_cast(unsigned, r); }
; DI float siluf_(float x) { return x / (1.f + __expf(-x)); }
; DI void attn_unit(const Params& p, int l, int unit, unsigned char* smem) {
;     ...
; #pragma unroll
;   for (int dvb = 0; dvb < 4; ++dvb)
; #pragma unroll
;     for (int g = 0; g < 4; ++g) {
;       const int dv = 32 * dvb + 8 * g + 4 * h;
;       const s16x4 z4 = *(const s16x4*)(P + rowq * PLD + C_DAZ + hd * 128 + dv);
;       const f32x4 gn = *(const f32x4*)(p.da_norm + l * 128 + dv);
;       float y[4];
;       for (int q = 0; q < 4; ++q) y[q] = oacc[dvb][4 * g + q] * rs * gn[q] * siluf_(bf2f((bfr)z4[q]));
;       u32x2 w; w[0] = pk2(y[0], y[1]); w[1] = pk2(y[2], y[3]);
;       *(u32x2*)(YS + rowq * DM + 1536 + hd * 128 + dv) = w;
;     }
	v_and_b32_e32 v16, 0xffff0000, v4
	v_lshlrev_b32_e32 v4, 16, v4
	v_mul_f32_e32 v6, 0xbfb8aa3b, v4
	v_mul_f32_e32 v7, 0xbfb8aa3b, v16
	v_exp_f32_e32 v6, v6
	v_exp_f32_e32 v7, v7
	v_pk_mul_f32 v[0:1], v[0:1], v[8:9]
	v_pk_add_f32 v[6:7], v[6:7], 1.0 op_sel_hi:[1,0]
	s_nop 0
	v_div_scale_f32 v8, s[10:11], v7, v7, v16
	v_rcp_f32_e32 v9, v8
	s_nop 0
	v_fma_f32 v17, -v8, v9, 1.0
	v_fmac_f32_e32 v9, v17, v9
	v_div_scale_f32 v17, vcc, v16, v7, v16
	v_mul_f32_e32 v18, v17, v9
	v_fma_f32 v19, -v8, v18, v17
	v_fmac_f32_e32 v18, v19, v9
	v_fma_f32 v8, -v8, v18, v17
	v_div_fmas_f32 v8, v8, v9, v18
	v_div_fixup_f32 v7, v8, v7, v16
	v_div_scale_f32 v8, s[10:11], v6, v6, v4
	v_rcp_f32_e32 v9, v8
	s_nop 0
	v_fma_f32 v16, -v8, v9, 1.0
	v_fmac_f32_e32 v9, v16, v9
	v_div_scale_f32 v16, vcc, v4, v6, v4
	v_mul_f32_e32 v17, v16, v9
	v_fma_f32 v18, -v8, v17, v16
	v_fmac_f32_e32 v17, v18, v9
	v_fma_f32 v8, -v8, v17, v16
	v_div_fmas_f32 v8, v8, v9, v17
	v_div_fixup_f32 v6, v8, v6, v4
	v_and_b32_e32 v8, 0xffff0000, v5
	v_lshlrev_b32_e32 v9, 16, v5
	v_mul_f32_e32 v4, 0xbfb8aa3b, v9
	v_mul_f32_e32 v5, 0xbfb8aa3b, v8
	v_exp_f32_e32 v4, v4
	v_exp_f32_e32 v5, v5
	v_pk_mul_f32 v[0:1], v[6:7], v[0:1]
	v_pk_mul_f32 v[6:7], v[10:11], v[64:65] op_sel_hi:[1,0]
	v_cvt_pk_bf16_f32 v0, v0, v1
	v_pk_add_f32 v[4:5], v[4:5], 1.0 op_sel_hi:[1,0]
	v_pk_mul_f32 v[2:3], v[2:3], v[6:7]
	v_div_scale_f32 v6, s[10:11], v5, v5, v8
	v_rcp_f32_e32 v7, v6
	s_nop 0
	v_fma_f32 v10, -v6, v7, 1.0
	v_fmac_f32_e32 v7, v10, v7
	v_div_scale_f32 v10, vcc, v8, v5, v8
	v_mul_f32_e32 v11, v10, v7
	v_fma_f32 v16, -v6, v11, v10
	v_fmac_f32_e32 v11, v16, v7
	v_fma_f32 v6, -v6, v11, v10
	v_div_fmas_f32 v6, v6, v7, v11
	v_div_fixup_f32 v5, v6, v5, v8
	v_div_scale_f32 v6, s[10:11], v4, v4, v9
	v_rcp_f32_e32 v7, v6
	s_nop 0
	v_fma_f32 v8, -v6, v7, 1.0
	v_fmac_f32_e32 v7, v8, v7
	v_div_scale_f32 v8, vcc, v9, v4, v9
	v_mul_f32_e32 v10, v8, v7
	v_fma_f32 v11, -v6, v10, v8
	v_fmac_f32_e32 v10, v11, v7
	v_fma_f32 v6, -v6, v10, v8
	v_div_fmas_f32 v6, v6, v7, v10
	v_div_fixup_f32 v4, v6, v4, v9
	v_pk_mul_f32 v[2:3], v[4:5], v[2:3]
	v_pk_mul_f32 v[8:9], v[12:13], v[64:65] op_sel_hi:[1,0]
	v_cvt_pk_bf16_f32 v1, v2, v3
	global_store_dwordx2 v[48:49], v[0:1], off offset:224
	v_mov_b32_e32 v0, v92
	v_mov_b32_e32 v1, v93
	s_nop 0
	v_mov_b32_e32 v2, v196
	v_mov_b32_e32 v3, v197
	v_mov_b32_e32 v4, v198
	v_mov_b32_e32 v5, v199
	s_waitcnt lgkmcnt(0)
	v_and_b32_e32 v10, 0xffff0000, v0
	v_lshlrev_b32_e32 v0, 16, v0
	v_mul_f32_e32 v6, 0xbfb8aa3b, v0
	v_mul_f32_e32 v7, 0xbfb8aa3b, v10
	v_exp_f32_e32 v6, v6
	v_exp_f32_e32 v7, v7
	v_pk_mul_f32 v[2:3], v[2:3], v[8:9]
	v_pk_add_f32 v[6:7], v[6:7], 1.0 op_sel_hi:[1,0]
	s_nop 0
	v_div_scale_f32 v8, s[10:11], v7, v7, v10
	v_rcp_f32_e32 v9, v8
	s_nop 0
	v_fma_f32 v11, -v8, v9, 1.0
	v_fmac_f32_e32 v9, v11, v9
	v_div_scale_f32 v11, vcc, v10, v7, v10
	v_mul_f32_e32 v12, v11, v9
	v_fma_f32 v13, -v8, v12, v11
	v_fmac_f32_e32 v12, v13, v9
	v_fma_f32 v8, -v8, v12, v11
	v_div_fmas_f32 v8, v8, v9, v12
	v_div_fixup_f32 v7, v8, v7, v10
	v_div_scale_f32 v8, s[10:11], v6, v6, v0
	v_rcp_f32_e32 v9, v8
	s_nop 0
	v_fma_f32 v10, -v8, v9, 1.0
	v_fmac_f32_e32 v9, v10, v9
	v_div_scale_f32 v10, vcc, v0, v6, v0
	v_mul_f32_e32 v11, v10, v9
	v_fma_f32 v12, -v8, v11, v10
	v_fmac_f32_e32 v11, v12, v9
	v_fma_f32 v8, -v8, v11, v10
	v_div_fmas_f32 v8, v8, v9, v11
	v_div_fixup_f32 v6, v8, v6, v0
	v_and_b32_e32 v8, 0xffff0000, v1
	v_lshlrev_b32_e32 v9, 16, v1
	v_mul_f32_e32 v0, 0xbfb8aa3b, v9
	v_mul_f32_e32 v1, 0xbfb8aa3b, v8
	v_exp_f32_e32 v0, v0
	v_exp_f32_e32 v1, v1
	v_pk_mul_f32 v[2:3], v[6:7], v[2:3]
	v_pk_mul_f32 v[6:7], v[14:15], v[64:65] op_sel_hi:[1,0]
	v_cvt_pk_bf16_f32 v2, v2, v3
	v_pk_add_f32 v[0:1], v[0:1], 1.0 op_sel_hi:[1,0]
	v_pk_mul_f32 v[4:5], v[4:5], v[6:7]
	v_div_scale_f32 v6, s[10:11], v1, v1, v8
	v_rcp_f32_e32 v7, v6
	s_nop 0
	v_fma_f32 v10, -v6, v7, 1.0
	v_fmac_f32_e32 v7, v10, v7
	v_div_scale_f32 v10, vcc, v8, v1, v8
	v_mul_f32_e32 v11, v10, v7
	v_fma_f32 v12, -v6, v11, v10
	v_fmac_f32_e32 v11, v12, v7
	v_fma_f32 v6, -v6, v11, v10
	v_div_fmas_f32 v6, v6, v7, v11
	v_div_fixup_f32 v1, v6, v1, v8
	v_div_scale_f32 v6, s[10:11], v0, v0, v9
	v_rcp_f32_e32 v7, v6
	s_nop 0
	v_fma_f32 v8, -v6, v7, 1.0
	v_fmac_f32_e32 v7, v8, v7
	v_div_scale_f32 v8, vcc, v9, v0, v9
	v_mul_f32_e32 v10, v8, v7
	v_fma_f32 v11, -v6, v10, v8
	v_fmac_f32_e32 v10, v11, v7
	v_fma_f32 v6, -v6, v10, v8
	v_div_fmas_f32 v6, v6, v7, v10
	v_div_fixup_f32 v0, v6, v0, v9
	v_pk_mul_f32 v[0:1], v[0:1], v[4:5]
	s_nop 0
	v_cvt_pk_bf16_f32 v3, v0, v1
	global_store_dwordx2 v[48:49], v[2:3], off offset:240
	s_branch .LBB0_511
